# p4/p6 GEMM epilogues: all gate/M/macc loads of an iteration issued up front (one wait instead of 16 exposed round trips)
# speedup vs baseline: 1.1150x; 1.0321x over previous
; DEVI float sigmoidf_(float x) { return 1.f / (1.f + __expf(-x)); }
; template <int BR, int IN, int OUT>
; DEVI void p6_branch(const Params& P, int pm, int pn, float* macc, char* smem, int tid) {
;     ...
; #pragma unroll 8
;   for (int q = 0; q < 16; ++q) {
;     const int id = tid + 256 * q, row = id >> 5, c4 = id & 31;
;     const long grow = (long)pm * 128 + row;
;     const int gcol = pn * 128 + c4 * 4;
;     float4 a = *reinterpret_cast<const float4*>(T + row * 128 + c4 * 4);
;     float g[4];
;     load4bf(Z + grow * NCOL + (9 + BR) * 1024 + gcol, g);
;     float v[4] = {sigmoidf_(g[0]) * a.x, sigmoidf_(g[1]) * a.y, sigmoidf_(g[2]) * a.z, sigmoidf_(g[3]) * a.w};
;     if (IN == 1) {
;       float mo[4]; load4bf(M + grow * 1024 + gcol, mo);
;       v[0] += mo[0]; v[1] += mo[1]; v[2] += mo[2]; v[3] += mo[3];
;     }
;     if (IN == 2) {
;       float4 mo = *reinterpret_cast<const float4*>(macc + grow * 1024 + gcol);
;       v[0] += mo.x; v[1] += mo.y; v[2] += mo.z; v[3] += mo.w;
;     }
;     if (OUT == 1) *reinterpret_cast<float4*>(macc + grow * 1024 + gcol) = make_float4(v[0], v[1], v[2], v[3]);
;     else store4bf(M + grow * 1024 + gcol, v);
;   }
.LBB0_513:
	v_add_u32_e32 v238, s24, v91
	v_ashrrev_i32_e32 v236, 5, v238
	v_ashrrev_i32_e32 v237, 31, v236
	v_lshl_add_u64 v[240:241], s[74:75], 0, v[236:237]
	v_mov_b64_e32 v[236:237], s[26:27]
	v_mad_u64_u32 v[242:243], s[50:51], v240, s22, v[236:237]
	v_mad_i32_i24 v243, v241, s22, v243
	v_lshl_add_u64 v[242:243], v[242:243], 0, v[2:3]
	v_add_co_u32_e32 v242, vcc, 0x4000, v242
	s_nop 1
	v_addc_co_u32_e32 v243, vcc, 0, v243, vcc
	global_load_dwordx2 v[220:221], v[242:243], off offset:2048
	v_add_u32_e32 v238, s24, v91
	v_mov_b64_e32 v[236:237], s[26:27]
	v_add_u32_e32 v239, 0x100, v238
	v_ashrrev_i32_e32 v240, 5, v239
	v_ashrrev_i32_e32 v241, 31, v240
	v_lshl_add_u64 v[242:243], s[74:75], 0, v[240:241]
	v_mad_u64_u32 v[240:241], s[50:51], v242, s22, v[236:237]
	v_mad_i32_i24 v241, v243, s22, v241
	v_lshl_add_u64 v[240:241], v[240:241], 0, v[2:3]
	v_add_co_u32_e32 v240, vcc, s36, v240
	s_nop 1
	v_addc_co_u32_e32 v241, vcc, 0, v241, vcc
	global_load_dwordx2 v[222:223], v[240:241], off offset:2048
	v_add_u32_e32 v238, s24, v91
	v_mov_b64_e32 v[236:237], s[26:27]
	v_add_u32_e32 v239, 0x200, v238
	v_ashrrev_i32_e32 v240, 5, v239
	v_ashrrev_i32_e32 v241, 31, v240
	v_lshl_add_u64 v[242:243], s[74:75], 0, v[240:241]
	v_mad_u64_u32 v[240:241], s[50:51], v242, s22, v[236:237]
	v_mad_i32_i24 v241, v243, s22, v241
	v_lshl_add_u64 v[240:241], v[240:241], 0, v[2:3]
	v_add_co_u32_e32 v240, vcc, s36, v240
	s_nop 1
	v_addc_co_u32_e32 v241, vcc, 0, v241, vcc
	global_load_dwordx2 v[224:225], v[240:241], off offset:2048
	v_add_u32_e32 v238, s24, v91
	v_mov_b64_e32 v[236:237], s[26:27]
	v_add_u32_e32 v239, 0x300, v238
	v_ashrrev_i32_e32 v240, 5, v239
	v_ashrrev_i32_e32 v241, 31, v240
	v_lshl_add_u64 v[242:243], s[74:75], 0, v[240:241]
	v_mad_u64_u32 v[240:241], s[50:51], v242, s22, v[236:237]
	v_mad_i32_i24 v241, v243, s22, v241
	v_lshl_add_u64 v[240:241], v[240:241], 0, v[2:3]
	v_add_co_u32_e32 v240, vcc, s36, v240
	s_nop 1
	v_addc_co_u32_e32 v241, vcc, 0, v241, vcc
	global_load_dwordx2 v[226:227], v[240:241], off offset:2048
	v_add_u32_e32 v238, s24, v91
	v_mov_b64_e32 v[236:237], s[26:27]
	v_add_u32_e32 v239, 0x400, v238
	v_ashrrev_i32_e32 v240, 5, v239
	v_ashrrev_i32_e32 v241, 31, v240
	v_lshl_add_u64 v[242:243], s[74:75], 0, v[240:241]
	v_mad_u64_u32 v[240:241], s[50:51], v242, s22, v[236:237]
	v_mad_i32_i24 v241, v243, s22, v241
	v_lshl_add_u64 v[240:241], v[240:241], 0, v[2:3]
	v_add_co_u32_e32 v240, vcc, s36, v240
	s_nop 1
	v_addc_co_u32_e32 v241, vcc, 0, v241, vcc
	global_load_dwordx2 v[228:229], v[240:241], off offset:2048
	v_add_u32_e32 v238, s24, v91
	v_mov_b64_e32 v[236:237], s[26:27]
	v_add_u32_e32 v239, 0x500, v238
	v_ashrrev_i32_e32 v240, 5, v239
	v_ashrrev_i32_e32 v241, 31, v240
	v_lshl_add_u64 v[242:243], s[74:75], 0, v[240:241]
	v_mad_u64_u32 v[240:241], s[50:51], v242, s22, v[236:237]
	v_mad_i32_i24 v241, v243, s22, v241
	v_lshl_add_u64 v[240:241], v[240:241], 0, v[2:3]
	v_add_co_u32_e32 v240, vcc, s36, v240
	s_nop 1
	v_addc_co_u32_e32 v241, vcc, 0, v241, vcc
	global_load_dwordx2 v[230:231], v[240:241], off offset:2048
	v_add_u32_e32 v238, s24, v91
	v_mov_b64_e32 v[236:237], s[26:27]
	v_add_u32_e32 v239, 0x600, v238
	v_ashrrev_i32_e32 v240, 5, v239
	v_ashrrev_i32_e32 v241, 31, v240
	v_lshl_add_u64 v[242:243], s[74:75], 0, v[240:241]
	v_mad_u64_u32 v[240:241], s[50:51], v242, s22, v[236:237]
	v_mad_i32_i24 v241, v243, s22, v241
	v_lshl_add_u64 v[240:241], v[240:241], 0, v[2:3]
	v_add_co_u32_e32 v240, vcc, s36, v240
	s_nop 1
	v_addc_co_u32_e32 v241, vcc, 0, v241, vcc
	global_load_dwordx2 v[232:233], v[240:241], off offset:2048
	v_add_u32_e32 v238, s24, v91
	v_mov_b64_e32 v[236:237], s[26:27]
	v_add_u32_e32 v238, 0x700, v238
	v_ashrrev_i32_e32 v240, 5, v238
	v_ashrrev_i32_e32 v241, 31, v240
	v_lshl_add_u64 v[238:239], s[74:75], 0, v[240:241]
	v_mad_u64_u32 v[236:237], s[50:51], v238, s22, v[236:237]
	v_mad_i32_i24 v237, v239, s22, v237
	v_lshl_add_u64 v[236:237], v[236:237], 0, v[2:3]
	v_add_co_u32_e32 v236, vcc, s36, v236
	s_nop 1
	v_addc_co_u32_e32 v237, vcc, 0, v237, vcc
	global_load_dwordx2 v[234:235], v[236:237], off offset:2048
	s_waitcnt vmcnt(0)
	v_add_u32_e32 v6, s24, v91
	v_ashrrev_i32_e32 v4, 5, v6
	v_ashrrev_i32_e32 v5, 31, v4
	v_lshl_add_u64 v[8:9], s[74:75], 0, v[4:5]
	v_lshl_or_b32 v7, v4, 9, v169
	v_mov_b64_e32 v[4:5], s[26:27]
	v_mad_u64_u32 v[10:11], s[50:51], v8, s22, v[4:5]
	v_mad_i32_i24 v11, v9, s22, v11
	v_lshl_add_u64 v[10:11], v[10:11], 0, v[2:3]
	v_add_co_u32_e32 v10, vcc, 0x4000, v10
	v_lshlrev_b64 v[8:9], 11, v[8:9]
	s_nop 0
	v_addc_co_u32_e32 v11, vcc, 0, v11, vcc
	v_mov_b32_e32 v10, v220
	v_mov_b32_e32 v11, v221
	v_lshl_add_u64 v[16:17], v[0:1], 0, v[8:9]
	s_addk_i32 s24, 0x800
	s_cmpk_lg_i32 s24, 0x1000
	v_lshlrev_b32_e32 v12, 16, v10
	v_and_b32_e32 v10, 0xffff0000, v10
	v_lshlrev_b32_e32 v13, 16, v11
	v_mul_f32_e32 v10, 0xbfb8aa3b, v10
	v_mul_f32_e32 v12, 0xbfb8aa3b, v12
	v_exp_f32_e32 v14, v10
	v_mul_f32_e32 v10, 0xbfb8aa3b, v13
	v_exp_f32_e32 v12, v12
	v_exp_f32_e32 v13, v10
	v_and_b32_e32 v11, 0xffff0000, v11
	v_mul_f32_e32 v10, 0xbfb8aa3b, v11
	v_exp_f32_e32 v15, v10
	v_pk_add_f32 v[12:13], v[12:13], 1.0 op_sel_hi:[1,0]
	ds_read_b128 v[8:11], v7
	v_div_scale_f32 v7, s[50:51], v13, v13, 1.0
	v_rcp_f32_e32 v18, v7
	v_pk_add_f32 v[14:15], v[14:15], 1.0 op_sel_hi:[1,0]
	v_fma_f32 v19, -v7, v18, 1.0
	v_fmac_f32_e32 v18, v19, v18
	v_div_scale_f32 v19, vcc, 1.0, v13, 1.0
	v_mul_f32_e32 v20, v19, v18
	v_fma_f32 v21, -v7, v20, v19
	v_fmac_f32_e32 v20, v21, v18
	v_fma_f32 v7, -v7, v20, v19
	v_div_fmas_f32 v7, v7, v18, v20
	v_div_fixup_f32 v13, v7, v13, 1.0
	v_div_scale_f32 v7, s[50:51], v12, v12, 1.0
	v_rcp_f32_e32 v18, v7
	s_nop 0
	v_fma_f32 v19, -v7, v18, 1.0
	v_fmac_f32_e32 v18, v19, v18
	v_div_scale_f32 v19, vcc, 1.0, v12, 1.0
	v_mul_f32_e32 v20, v19, v18
	v_fma_f32 v21, -v7, v20, v19
	v_fmac_f32_e32 v20, v21, v18
	v_fma_f32 v7, -v7, v20, v19
	v_div_fmas_f32 v7, v7, v18, v20
	v_div_fixup_f32 v12, v7, v12, 1.0
	v_div_scale_f32 v7, s[50:51], v15, v15, 1.0
	s_waitcnt lgkmcnt(0)
; DEVI float sigmoidf_(float x) { return 1.f / (1.f + __expf(-x)); }
; template <int BR, int IN, int OUT>
; DEVI void p6_branch(const Params& P, int pm, int pn, float* macc, char* smem, int tid) {
;     ...
; #pragma unroll 8
;   for (int q = 0; q < 16; ++q) {
;     const int id = tid + 256 * q, row = id >> 5, c4 = id & 31;
;     const long grow = (long)pm * 128 + row;
;     const int gcol = pn * 128 + c4 * 4;
;     float4 a = *reinterpret_cast<const float4*>(T + row * 128 + c4 * 4);
;     float g[4];
;     load4bf(Z + grow * NCOL + (9 + BR) * 1024 + gcol, g);
;     float v[4] = {sigmoidf_(g[0]) * a.x, sigmoidf_(g[1]) * a.y, sigmoidf_(g[2]) * a.z, sigmoidf_(g[3]) * a.w};
;     if (IN == 1) {
;       float mo[4]; load4bf(M + grow * 1024 + gcol, mo);
;       v[0] += mo[0]; v[1] += mo[1]; v[2] += mo[2]; v[3] += mo[3];
;     }
;     if (IN == 2) {
;       float4 mo = *reinterpret_cast<const float4*>(macc + grow * 1024 + gcol);
;       v[0] += mo.x; v[1] += mo.y; v[2] += mo.z; v[3] += mo.w;
;     }
;     if (OUT == 1) *reinterpret_cast<float4*>(macc + grow * 1024 + gcol) = make_float4(v[0], v[1], v[2], v[3]);
;     else store4bf(M + grow * 1024 + gcol, v);
;   }
	v_mov_b32_e32 v18, v8
	v_rcp_f32_e32 v8, v7
	v_mov_b32_e32 v19, v10
	v_pk_mul_f32 v[12:13], v[18:19], v[12:13]
	v_fma_f32 v10, -v7, v8, 1.0
	v_fmac_f32_e32 v8, v10, v8
	v_div_scale_f32 v10, vcc, 1.0, v15, 1.0
	v_mul_f32_e32 v18, v10, v8
	v_fma_f32 v19, -v7, v18, v10
	v_fmac_f32_e32 v18, v19, v8
	v_fma_f32 v7, -v7, v18, v10
	v_div_fmas_f32 v7, v7, v8, v18
	v_div_fixup_f32 v15, v7, v15, 1.0
	v_div_scale_f32 v7, s[50:51], v14, v14, 1.0
	v_rcp_f32_e32 v8, v7
	s_nop 0
	v_fma_f32 v10, -v7, v8, 1.0
	v_fmac_f32_e32 v8, v10, v8
	v_div_scale_f32 v10, vcc, 1.0, v14, 1.0
	v_mul_f32_e32 v18, v10, v8
	v_fma_f32 v19, -v7, v18, v10
	v_fmac_f32_e32 v18, v19, v8
	v_fma_f32 v7, -v7, v18, v10
	v_div_fmas_f32 v7, v7, v8, v18
	v_div_fixup_f32 v14, v7, v14, 1.0
	v_mov_b32_e32 v10, v9
	v_pk_mul_f32 v[8:9], v[10:11], v[14:15]
	v_and_b32_sdwa v10, v12, v95 dst_sel:DWORD dst_unused:UNUSED_PAD src0_sel:WORD_1 src1_sel:DWORD
	v_add3_u32 v10, v12, v10, s39
	v_and_b32_sdwa v11, v9, v95 dst_sel:DWORD dst_unused:UNUSED_PAD src0_sel:WORD_1 src1_sel:DWORD
	v_and_b32_sdwa v12, v8, v95 dst_sel:DWORD dst_unused:UNUSED_PAD src0_sel:WORD_1 src1_sel:DWORD
	v_and_b32_sdwa v7, v13, v95 dst_sel:DWORD dst_unused:UNUSED_PAD src0_sel:WORD_1 src1_sel:DWORD
	v_add3_u32 v9, v9, v11, s39
	v_add3_u32 v8, v8, v12, s39
	v_add3_u32 v7, v13, v7, s39
	v_and_b32_e32 v9, 0xffff0000, v9
	v_and_b32_e32 v8, 0xffff0000, v8
	v_or_b32_sdwa v9, v9, v7 dst_sel:DWORD dst_unused:UNUSED_PAD src0_sel:DWORD src1_sel:WORD_1
	v_or_b32_sdwa v8, v8, v10 dst_sel:DWORD dst_unused:UNUSED_PAD src0_sel:DWORD src1_sel:WORD_1
	v_add_u32_e32 v7, 0x100, v6
	global_store_dwordx2 v[16:17], v[8:9], off
	v_ashrrev_i32_e32 v8, 5, v7
	v_ashrrev_i32_e32 v9, 31, v8
	v_lshl_add_u64 v[10:11], s[74:75], 0, v[8:9]
	v_lshl_or_b32 v7, v8, 9, v169
	v_mad_u64_u32 v[8:9], s[50:51], v10, s22, v[4:5]
	v_mad_i32_i24 v9, v11, s22, v9
	v_lshl_add_u64 v[8:9], v[8:9], 0, v[2:3]
	v_add_co_u32_e32 v8, vcc, s36, v8
	s_nop 1
	v_addc_co_u32_e32 v9, vcc, 0, v9, vcc
	v_mov_b32_e32 v8, v222
	v_mov_b32_e32 v9, v223
	v_lshlrev_b32_e32 v12, 16, v8
	v_and_b32_e32 v8, 0xffff0000, v8
	v_lshlrev_b32_e32 v13, 16, v9
	v_mul_f32_e32 v8, 0xbfb8aa3b, v8
	v_mul_f32_e32 v12, 0xbfb8aa3b, v12
	v_exp_f32_e32 v14, v8
	v_mul_f32_e32 v8, 0xbfb8aa3b, v13
	v_exp_f32_e32 v12, v12
	v_exp_f32_e32 v13, v8
	v_and_b32_e32 v9, 0xffff0000, v9
	v_mul_f32_e32 v8, 0xbfb8aa3b, v9
	v_exp_f32_e32 v15, v8
	v_lshlrev_b64 v[8:9], 11, v[10:11]
	v_pk_add_f32 v[12:13], v[12:13], 1.0 op_sel_hi:[1,0]
	v_lshl_add_u64 v[16:17], v[0:1], 0, v[8:9]
	ds_read_b128 v[8:11], v7
	v_div_scale_f32 v7, s[50:51], v13, v13, 1.0
	v_rcp_f32_e32 v18, v7
	v_pk_add_f32 v[14:15], v[14:15], 1.0 op_sel_hi:[1,0]
	v_fma_f32 v19, -v7, v18, 1.0
	v_fmac_f32_e32 v18, v19, v18
	v_div_scale_f32 v19, vcc, 1.0, v13, 1.0
	v_mul_f32_e32 v20, v19, v18
	v_fma_f32 v21, -v7, v20, v19
	v_fmac_f32_e32 v20, v21, v18
	v_fma_f32 v7, -v7, v20, v19
	v_div_fmas_f32 v7, v7, v18, v20
	v_div_fixup_f32 v13, v7, v13, 1.0
	v_div_scale_f32 v7, s[50:51], v12, v12, 1.0
	v_rcp_f32_e32 v18, v7
	s_nop 0
	v_fma_f32 v19, -v7, v18, 1.0
	v_fmac_f32_e32 v18, v19, v18
	v_div_scale_f32 v19, vcc, 1.0, v12, 1.0
	v_mul_f32_e32 v20, v19, v18
	v_fma_f32 v21, -v7, v20, v19
	v_fmac_f32_e32 v20, v21, v18
	v_fma_f32 v7, -v7, v20, v19
	v_div_fmas_f32 v7, v7, v18, v20
	v_div_fixup_f32 v12, v7, v12, 1.0
	v_div_scale_f32 v7, s[50:51], v15, v15, 1.0
	s_waitcnt lgkmcnt(0)
	v_mov_b32_e32 v18, v8
	v_rcp_f32_e32 v8, v7
	v_mov_b32_e32 v19, v10
	v_pk_mul_f32 v[12:13], v[18:19], v[12:13]
	v_fma_f32 v10, -v7, v8, 1.0
	v_fmac_f32_e32 v8, v10, v8
	v_div_scale_f32 v10, vcc, 1.0, v15, 1.0
	v_mul_f32_e32 v18, v10, v8
	v_fma_f32 v19, -v7, v18, v10
	v_fmac_f32_e32 v18, v19, v8
	v_fma_f32 v7, -v7, v18, v10
	v_div_fmas_f32 v7, v7, v8, v18
	v_div_fixup_f32 v15, v7, v15, 1.0
	v_div_scale_f32 v7, s[50:51], v14, v14, 1.0
	v_rcp_f32_e32 v8, v7
	s_nop 0
	v_fma_f32 v10, -v7, v8, 1.0
	v_fmac_f32_e32 v8, v10, v8
	v_div_scale_f32 v10, vcc, 1.0, v14, 1.0
	v_mul_f32_e32 v18, v10, v8
	v_fma_f32 v19, -v7, v18, v10
	v_fmac_f32_e32 v18, v19, v8
	v_fma_f32 v7, -v7, v18, v10
	v_div_fmas_f32 v7, v7, v8, v18
	v_div_fixup_f32 v14, v7, v14, 1.0
	v_mov_b32_e32 v10, v9
	v_pk_mul_f32 v[8:9], v[10:11], v[14:15]
	v_and_b32_sdwa v10, v12, v95 dst_sel:DWORD dst_unused:UNUSED_PAD src0_sel:WORD_1 src1_sel:DWORD
	v_add3_u32 v10, v12, v10, s39
	v_and_b32_sdwa v11, v9, v95 dst_sel:DWORD dst_unused:UNUSED_PAD src0_sel:WORD_1 src1_sel:DWORD
	v_and_b32_sdwa v12, v8, v95 dst_sel:DWORD dst_unused:UNUSED_PAD src0_sel:WORD_1 src1_sel:DWORD
	v_and_b32_sdwa v7, v13, v95 dst_sel:DWORD dst_unused:UNUSED_PAD src0_sel:WORD_1 src1_sel:DWORD
	v_add3_u32 v9, v9, v11, s39
	v_add3_u32 v8, v8, v12, s39
	v_add3_u32 v7, v13, v7, s39
	v_and_b32_e32 v9, 0xffff0000, v9
	v_and_b32_e32 v8, 0xffff0000, v8
	v_or_b32_sdwa v9, v9, v7 dst_sel:DWORD dst_unused:UNUSED_PAD src0_sel:DWORD src1_sel:WORD_1
	v_or_b32_sdwa v8, v8, v10 dst_sel:DWORD dst_unused:UNUSED_PAD src0_sel:DWORD src1_sel:WORD_1
	v_add_u32_e32 v7, 0x200, v6
	global_store_dwordx2 v[16:17], v[8:9], off
	v_ashrrev_i32_e32 v8, 5, v7
	v_ashrrev_i32_e32 v9, 31, v8
	v_lshl_add_u64 v[10:11], s[74:75], 0, v[8:9]
	v_lshl_or_b32 v7, v8, 9, v169
	v_mad_u64_u32 v[8:9], s[50:51], v10, s22, v[4:5]
	v_mad_i32_i24 v9, v11, s22, v9
	v_lshl_add_u64 v[8:9], v[8:9], 0, v[2:3]
	v_add_co_u32_e32 v8, vcc, s36, v8
	s_nop 1
	v_addc_co_u32_e32 v9, vcc, 0, v9, vcc
	v_mov_b32_e32 v8, v224
	v_mov_b32_e32 v9, v225
	v_lshlrev_b32_e32 v12, 16, v8
	v_and_b32_e32 v8, 0xffff0000, v8
	v_lshlrev_b32_e32 v13, 16, v9
	v_mul_f32_e32 v8, 0xbfb8aa3b, v8
	v_mul_f32_e32 v12, 0xbfb8aa3b, v12
	v_exp_f32_e32 v14, v8
	v_mul_f32_e32 v8, 0xbfb8aa3b, v13
	v_exp_f32_e32 v12, v12
	v_exp_f32_e32 v13, v8
	v_and_b32_e32 v9, 0xffff0000, v9
	v_mul_f32_e32 v8, 0xbfb8aa3b, v9
	v_exp_f32_e32 v15, v8
	v_lshlrev_b64 v[8:9], 11, v[10:11]
	v_pk_add_f32 v[12:13], v[12:13], 1.0 op_sel_hi:[1,0]
	v_lshl_add_u64 v[16:17], v[0:1], 0, v[8:9]
	ds_read_b128 v[8:11], v7
	v_div_scale_f32 v7, s[50:51], v13, v13, 1.0
	v_rcp_f32_e32 v18, v7
	v_pk_add_f32 v[14:15], v[14:15], 1.0 op_sel_hi:[1,0]
	v_fma_f32 v19, -v7, v18, 1.0
	v_fmac_f32_e32 v18, v19, v18
	v_div_scale_f32 v19, vcc, 1.0, v13, 1.0
	v_mul_f32_e32 v20, v19, v18
	v_fma_f32 v21, -v7, v20, v19
	v_fmac_f32_e32 v20, v21, v18
	v_fma_f32 v7, -v7, v20, v19
	v_div_fmas_f32 v7, v7, v18, v20
	v_div_fixup_f32 v13, v7, v13, 1.0
	v_div_scale_f32 v7, s[50:51], v12, v12, 1.0
	v_rcp_f32_e32 v18, v7
	s_nop 0
	v_fma_f32 v19, -v7, v18, 1.0
	v_fmac_f32_e32 v18, v19, v18
	v_div_scale_f32 v19, vcc, 1.0, v12, 1.0
	v_mul_f32_e32 v20, v19, v18
	v_fma_f32 v21, -v7, v20, v19
	v_fmac_f32_e32 v20, v21, v18
	v_fma_f32 v7, -v7, v20, v19
	v_div_fmas_f32 v7, v7, v18, v20
	v_div_fixup_f32 v12, v7, v12, 1.0
	v_div_scale_f32 v7, s[50:51], v15, v15, 1.0
	s_waitcnt lgkmcnt(0)
; DEVI float sigmoidf_(float x) { return 1.f / (1.f + __expf(-x)); }
; template <int BR, int IN, int OUT>
; DEVI void p6_branch(const Params& P, int pm, int pn, float* macc, char* smem, int tid) {
;     ...
; #pragma unroll 8
;   for (int q = 0; q < 16; ++q) {
;     const int id = tid + 256 * q, row = id >> 5, c4 = id & 31;
;     const long grow = (long)pm * 128 + row;
;     const int gcol = pn * 128 + c4 * 4;
;     float4 a = *reinterpret_cast<const float4*>(T + row * 128 + c4 * 4);
;     float g[4];
;     load4bf(Z + grow * NCOL + (9 + BR) * 1024 + gcol, g);
;     float v[4] = {sigmoidf_(g[0]) * a.x, sigmoidf_(g[1]) * a.y, sigmoidf_(g[2]) * a.z, sigmoidf_(g[3]) * a.w};
;     if (IN == 1) {
;       float mo[4]; load4bf(M + grow * 1024 + gcol, mo);
;       v[0] += mo[0]; v[1] += mo[1]; v[2] += mo[2]; v[3] += mo[3];
;     }
;     if (IN == 2) {
;       float4 mo = *reinterpret_cast<const float4*>(macc + grow * 1024 + gcol);
;       v[0] += mo.x; v[1] += mo.y; v[2] += mo.z; v[3] += mo.w;
;     }
;     if (OUT == 1) *reinterpret_cast<float4*>(macc + grow * 1024 + gcol) = make_float4(v[0], v[1], v[2], v[3]);
;     else store4bf(M + grow * 1024 + gcol, v);
;   }
	v_mov_b32_e32 v18, v8
	v_rcp_f32_e32 v8, v7
	v_mov_b32_e32 v19, v10
	v_pk_mul_f32 v[12:13], v[18:19], v[12:13]
	v_fma_f32 v10, -v7, v8, 1.0
	v_fmac_f32_e32 v8, v10, v8
	v_div_scale_f32 v10, vcc, 1.0, v15, 1.0
	v_mul_f32_e32 v18, v10, v8
	v_fma_f32 v19, -v7, v18, v10
	v_fmac_f32_e32 v18, v19, v8
	v_fma_f32 v7, -v7, v18, v10
	v_div_fmas_f32 v7, v7, v8, v18
	v_div_fixup_f32 v15, v7, v15, 1.0
	v_div_scale_f32 v7, s[50:51], v14, v14, 1.0
	v_rcp_f32_e32 v8, v7
	s_nop 0
	v_fma_f32 v10, -v7, v8, 1.0
	v_fmac_f32_e32 v8, v10, v8
	v_div_scale_f32 v10, vcc, 1.0, v14, 1.0
	v_mul_f32_e32 v18, v10, v8
	v_fma_f32 v19, -v7, v18, v10
	v_fmac_f32_e32 v18, v19, v8
	v_fma_f32 v7, -v7, v18, v10
	v_div_fmas_f32 v7, v7, v8, v18
	v_div_fixup_f32 v14, v7, v14, 1.0
	v_mov_b32_e32 v10, v9
	v_pk_mul_f32 v[8:9], v[10:11], v[14:15]
	v_and_b32_sdwa v10, v12, v95 dst_sel:DWORD dst_unused:UNUSED_PAD src0_sel:WORD_1 src1_sel:DWORD
	v_add3_u32 v10, v12, v10, s39
	v_and_b32_sdwa v11, v9, v95 dst_sel:DWORD dst_unused:UNUSED_PAD src0_sel:WORD_1 src1_sel:DWORD
	v_and_b32_sdwa v12, v8, v95 dst_sel:DWORD dst_unused:UNUSED_PAD src0_sel:WORD_1 src1_sel:DWORD
	v_and_b32_sdwa v7, v13, v95 dst_sel:DWORD dst_unused:UNUSED_PAD src0_sel:WORD_1 src1_sel:DWORD
	v_add3_u32 v9, v9, v11, s39
	v_add3_u32 v8, v8, v12, s39
	v_add3_u32 v7, v13, v7, s39
	v_and_b32_e32 v9, 0xffff0000, v9
	v_and_b32_e32 v8, 0xffff0000, v8
	v_or_b32_sdwa v9, v9, v7 dst_sel:DWORD dst_unused:UNUSED_PAD src0_sel:DWORD src1_sel:WORD_1
	v_or_b32_sdwa v8, v8, v10 dst_sel:DWORD dst_unused:UNUSED_PAD src0_sel:DWORD src1_sel:WORD_1
	v_add_u32_e32 v7, 0x300, v6
	global_store_dwordx2 v[16:17], v[8:9], off
	v_ashrrev_i32_e32 v8, 5, v7
	v_ashrrev_i32_e32 v9, 31, v8
	v_lshl_add_u64 v[10:11], s[74:75], 0, v[8:9]
	v_lshl_or_b32 v7, v8, 9, v169
	v_mad_u64_u32 v[8:9], s[50:51], v10, s22, v[4:5]
	v_mad_i32_i24 v9, v11, s22, v9
	v_lshl_add_u64 v[8:9], v[8:9], 0, v[2:3]
	v_add_co_u32_e32 v8, vcc, s36, v8
	s_nop 1
	v_addc_co_u32_e32 v9, vcc, 0, v9, vcc
	v_mov_b32_e32 v8, v226
	v_mov_b32_e32 v9, v227
	v_lshlrev_b32_e32 v12, 16, v8
	v_and_b32_e32 v8, 0xffff0000, v8
	v_lshlrev_b32_e32 v13, 16, v9
	v_mul_f32_e32 v8, 0xbfb8aa3b, v8
	v_mul_f32_e32 v12, 0xbfb8aa3b, v12
	v_exp_f32_e32 v14, v8
	v_mul_f32_e32 v8, 0xbfb8aa3b, v13
	v_exp_f32_e32 v12, v12
	v_exp_f32_e32 v13, v8
	v_and_b32_e32 v9, 0xffff0000, v9
	v_mul_f32_e32 v8, 0xbfb8aa3b, v9
	v_exp_f32_e32 v15, v8
	v_lshlrev_b64 v[8:9], 11, v[10:11]
	v_pk_add_f32 v[12:13], v[12:13], 1.0 op_sel_hi:[1,0]
	v_lshl_add_u64 v[16:17], v[0:1], 0, v[8:9]
	ds_read_b128 v[8:11], v7
	v_div_scale_f32 v7, s[50:51], v13, v13, 1.0
	v_rcp_f32_e32 v18, v7
	v_pk_add_f32 v[14:15], v[14:15], 1.0 op_sel_hi:[1,0]
	v_fma_f32 v19, -v7, v18, 1.0
	v_fmac_f32_e32 v18, v19, v18
	v_div_scale_f32 v19, vcc, 1.0, v13, 1.0
	v_mul_f32_e32 v20, v19, v18
	v_fma_f32 v21, -v7, v20, v19
	v_fmac_f32_e32 v20, v21, v18
	v_fma_f32 v7, -v7, v20, v19
	v_div_fmas_f32 v7, v7, v18, v20
	v_div_fixup_f32 v13, v7, v13, 1.0
	v_div_scale_f32 v7, s[50:51], v12, v12, 1.0
	v_rcp_f32_e32 v18, v7
	s_nop 0
	v_fma_f32 v19, -v7, v18, 1.0
	v_fmac_f32_e32 v18, v19, v18
	v_div_scale_f32 v19, vcc, 1.0, v12, 1.0
	v_mul_f32_e32 v20, v19, v18
	v_fma_f32 v21, -v7, v20, v19
	v_fmac_f32_e32 v20, v21, v18
	v_fma_f32 v7, -v7, v20, v19
	v_div_fmas_f32 v7, v7, v18, v20
	v_div_fixup_f32 v12, v7, v12, 1.0
	v_div_scale_f32 v7, s[50:51], v15, v15, 1.0
	s_waitcnt lgkmcnt(0)
	v_mov_b32_e32 v18, v8
	v_rcp_f32_e32 v8, v7
	v_mov_b32_e32 v19, v10
	v_pk_mul_f32 v[12:13], v[18:19], v[12:13]
	v_fma_f32 v10, -v7, v8, 1.0
	v_fmac_f32_e32 v8, v10, v8
	v_div_scale_f32 v10, vcc, 1.0, v15, 1.0
	v_mul_f32_e32 v18, v10, v8
	v_fma_f32 v19, -v7, v18, v10
	v_fmac_f32_e32 v18, v19, v8
	v_fma_f32 v7, -v7, v18, v10
	v_div_fmas_f32 v7, v7, v8, v18
	v_div_fixup_f32 v15, v7, v15, 1.0
	v_div_scale_f32 v7, s[50:51], v14, v14, 1.0
	v_rcp_f32_e32 v8, v7
	s_nop 0
	v_fma_f32 v10, -v7, v8, 1.0
	v_fmac_f32_e32 v8, v10, v8
	v_div_scale_f32 v10, vcc, 1.0, v14, 1.0
	v_mul_f32_e32 v18, v10, v8
	v_fma_f32 v19, -v7, v18, v10
	v_fmac_f32_e32 v18, v19, v8
	v_fma_f32 v7, -v7, v18, v10
	v_div_fmas_f32 v7, v7, v8, v18
	v_div_fixup_f32 v14, v7, v14, 1.0
	v_mov_b32_e32 v10, v9
	v_pk_mul_f32 v[8:9], v[10:11], v[14:15]
	v_and_b32_sdwa v10, v12, v95 dst_sel:DWORD dst_unused:UNUSED_PAD src0_sel:WORD_1 src1_sel:DWORD
	v_add3_u32 v10, v12, v10, s39
	v_and_b32_sdwa v11, v9, v95 dst_sel:DWORD dst_unused:UNUSED_PAD src0_sel:WORD_1 src1_sel:DWORD
	v_and_b32_sdwa v12, v8, v95 dst_sel:DWORD dst_unused:UNUSED_PAD src0_sel:WORD_1 src1_sel:DWORD
	v_and_b32_sdwa v7, v13, v95 dst_sel:DWORD dst_unused:UNUSED_PAD src0_sel:WORD_1 src1_sel:DWORD
	v_add3_u32 v9, v9, v11, s39
	v_add3_u32 v8, v8, v12, s39
	v_add3_u32 v7, v13, v7, s39
	v_and_b32_e32 v9, 0xffff0000, v9
	v_and_b32_e32 v8, 0xffff0000, v8
	v_or_b32_sdwa v9, v9, v7 dst_sel:DWORD dst_unused:UNUSED_PAD src0_sel:DWORD src1_sel:WORD_1
	v_or_b32_sdwa v8, v8, v10 dst_sel:DWORD dst_unused:UNUSED_PAD src0_sel:DWORD src1_sel:WORD_1
	v_add_u32_e32 v7, 0x400, v6
	global_store_dwordx2 v[16:17], v[8:9], off
	v_ashrrev_i32_e32 v8, 5, v7
	v_ashrrev_i32_e32 v9, 31, v8
	v_lshl_add_u64 v[10:11], s[74:75], 0, v[8:9]
	v_lshl_or_b32 v7, v8, 9, v169
	v_mad_u64_u32 v[8:9], s[50:51], v10, s22, v[4:5]
	v_mad_i32_i24 v9, v11, s22, v9
	v_lshl_add_u64 v[8:9], v[8:9], 0, v[2:3]
	v_add_co_u32_e32 v8, vcc, s36, v8
	s_nop 1
	v_addc_co_u32_e32 v9, vcc, 0, v9, vcc
	v_mov_b32_e32 v8, v228
	v_mov_b32_e32 v9, v229
	v_lshlrev_b32_e32 v12, 16, v8
	v_and_b32_e32 v8, 0xffff0000, v8
	v_lshlrev_b32_e32 v13, 16, v9
	v_mul_f32_e32 v8, 0xbfb8aa3b, v8
	v_mul_f32_e32 v12, 0xbfb8aa3b, v12
	v_exp_f32_e32 v14, v8
	v_mul_f32_e32 v8, 0xbfb8aa3b, v13
	v_exp_f32_e32 v12, v12
	v_exp_f32_e32 v13, v8
	v_and_b32_e32 v9, 0xffff0000, v9
	v_mul_f32_e32 v8, 0xbfb8aa3b, v9
	v_exp_f32_e32 v15, v8
	v_lshlrev_b64 v[8:9], 11, v[10:11]
	v_pk_add_f32 v[12:13], v[12:13], 1.0 op_sel_hi:[1,0]
	v_lshl_add_u64 v[16:17], v[0:1], 0, v[8:9]
	ds_read_b128 v[8:11], v7
	v_div_scale_f32 v7, s[50:51], v13, v13, 1.0
	v_rcp_f32_e32 v18, v7
	v_pk_add_f32 v[14:15], v[14:15], 1.0 op_sel_hi:[1,0]
	v_fma_f32 v19, -v7, v18, 1.0
	v_fmac_f32_e32 v18, v19, v18
	v_div_scale_f32 v19, vcc, 1.0, v13, 1.0
	v_mul_f32_e32 v20, v19, v18
	v_fma_f32 v21, -v7, v20, v19
	v_fmac_f32_e32 v20, v21, v18
	v_fma_f32 v7, -v7, v20, v19
	v_div_fmas_f32 v7, v7, v18, v20
	v_div_fixup_f32 v13, v7, v13, 1.0
	v_div_scale_f32 v7, s[50:51], v12, v12, 1.0
	v_rcp_f32_e32 v18, v7
	s_nop 0
	v_fma_f32 v19, -v7, v18, 1.0
	v_fmac_f32_e32 v18, v19, v18
	v_div_scale_f32 v19, vcc, 1.0, v12, 1.0
	v_mul_f32_e32 v20, v19, v18
	v_fma_f32 v21, -v7, v20, v19
	v_fmac_f32_e32 v20, v21, v18
	v_fma_f32 v7, -v7, v20, v19
	v_div_fmas_f32 v7, v7, v18, v20
	v_div_fixup_f32 v12, v7, v12, 1.0
	v_div_scale_f32 v7, s[50:51], v15, v15, 1.0
	s_waitcnt lgkmcnt(0)
; DEVI float sigmoidf_(float x) { return 1.f / (1.f + __expf(-x)); }
; template <int BR, int IN, int OUT>
; DEVI void p6_branch(const Params& P, int pm, int pn, float* macc, char* smem, int tid) {
;     ...
; #pragma unroll 8
;   for (int q = 0; q < 16; ++q) {
;     const int id = tid + 256 * q, row = id >> 5, c4 = id & 31;
;     const long grow = (long)pm * 128 + row;
;     const int gcol = pn * 128 + c4 * 4;
;     float4 a = *reinterpret_cast<const float4*>(T + row * 128 + c4 * 4);
;     float g[4];
;     load4bf(Z + grow * NCOL + (9 + BR) * 1024 + gcol, g);
;     float v[4] = {sigmoidf_(g[0]) * a.x, sigmoidf_(g[1]) * a.y, sigmoidf_(g[2]) * a.z, sigmoidf_(g[3]) * a.w};
;     if (IN == 1) {
;       float mo[4]; load4bf(M + grow * 1024 + gcol, mo);
;       v[0] += mo[0]; v[1] += mo[1]; v[2] += mo[2]; v[3] += mo[3];
;     }
;     if (IN == 2) {
;       float4 mo = *reinterpret_cast<const float4*>(macc + grow * 1024 + gcol);
;       v[0] += mo.x; v[1] += mo.y; v[2] += mo.z; v[3] += mo.w;
;     }
;     if (OUT == 1) *reinterpret_cast<float4*>(macc + grow * 1024 + gcol) = make_float4(v[0], v[1], v[2], v[3]);
;     else store4bf(M + grow * 1024 + gcol, v);
;   }
	v_mov_b32_e32 v18, v8
	v_rcp_f32_e32 v8, v7
	v_mov_b32_e32 v19, v10
	v_pk_mul_f32 v[12:13], v[18:19], v[12:13]
	v_fma_f32 v10, -v7, v8, 1.0
	v_fmac_f32_e32 v8, v10, v8
	v_div_scale_f32 v10, vcc, 1.0, v15, 1.0
	v_mul_f32_e32 v18, v10, v8
	v_fma_f32 v19, -v7, v18, v10
	v_fmac_f32_e32 v18, v19, v8
	v_fma_f32 v7, -v7, v18, v10
	v_div_fmas_f32 v7, v7, v8, v18
	v_div_fixup_f32 v15, v7, v15, 1.0
	v_div_scale_f32 v7, s[50:51], v14, v14, 1.0
	v_rcp_f32_e32 v8, v7
	s_nop 0
	v_fma_f32 v10, -v7, v8, 1.0
	v_fmac_f32_e32 v8, v10, v8
	v_div_scale_f32 v10, vcc, 1.0, v14, 1.0
	v_mul_f32_e32 v18, v10, v8
	v_fma_f32 v19, -v7, v18, v10
	v_fmac_f32_e32 v18, v19, v8
	v_fma_f32 v7, -v7, v18, v10
	v_div_fmas_f32 v7, v7, v8, v18
	v_div_fixup_f32 v14, v7, v14, 1.0
	v_mov_b32_e32 v10, v9
	v_pk_mul_f32 v[8:9], v[10:11], v[14:15]
	v_and_b32_sdwa v10, v12, v95 dst_sel:DWORD dst_unused:UNUSED_PAD src0_sel:WORD_1 src1_sel:DWORD
	v_add3_u32 v10, v12, v10, s39
	v_and_b32_sdwa v11, v9, v95 dst_sel:DWORD dst_unused:UNUSED_PAD src0_sel:WORD_1 src1_sel:DWORD
	v_and_b32_sdwa v12, v8, v95 dst_sel:DWORD dst_unused:UNUSED_PAD src0_sel:WORD_1 src1_sel:DWORD
	v_and_b32_sdwa v7, v13, v95 dst_sel:DWORD dst_unused:UNUSED_PAD src0_sel:WORD_1 src1_sel:DWORD
	v_add3_u32 v9, v9, v11, s39
	v_add3_u32 v8, v8, v12, s39
	v_add3_u32 v7, v13, v7, s39
	v_and_b32_e32 v9, 0xffff0000, v9
	v_and_b32_e32 v8, 0xffff0000, v8
	v_or_b32_sdwa v9, v9, v7 dst_sel:DWORD dst_unused:UNUSED_PAD src0_sel:DWORD src1_sel:WORD_1
	v_or_b32_sdwa v8, v8, v10 dst_sel:DWORD dst_unused:UNUSED_PAD src0_sel:DWORD src1_sel:WORD_1
	v_add_u32_e32 v7, 0x500, v6
	global_store_dwordx2 v[16:17], v[8:9], off
	v_ashrrev_i32_e32 v8, 5, v7
	v_ashrrev_i32_e32 v9, 31, v8
	v_lshl_add_u64 v[10:11], s[74:75], 0, v[8:9]
	v_lshl_or_b32 v7, v8, 9, v169
	v_mad_u64_u32 v[8:9], s[50:51], v10, s22, v[4:5]
	v_mad_i32_i24 v9, v11, s22, v9
	v_lshl_add_u64 v[8:9], v[8:9], 0, v[2:3]
	v_add_co_u32_e32 v8, vcc, s36, v8
	s_nop 1
	v_addc_co_u32_e32 v9, vcc, 0, v9, vcc
	v_mov_b32_e32 v8, v230
	v_mov_b32_e32 v9, v231
	v_lshlrev_b32_e32 v12, 16, v8
	v_and_b32_e32 v8, 0xffff0000, v8
	v_lshlrev_b32_e32 v13, 16, v9
	v_mul_f32_e32 v8, 0xbfb8aa3b, v8
	v_mul_f32_e32 v12, 0xbfb8aa3b, v12
	v_exp_f32_e32 v14, v8
	v_mul_f32_e32 v8, 0xbfb8aa3b, v13
	v_exp_f32_e32 v12, v12
	v_exp_f32_e32 v13, v8
	v_and_b32_e32 v9, 0xffff0000, v9
	v_mul_f32_e32 v8, 0xbfb8aa3b, v9
	v_exp_f32_e32 v15, v8
	v_lshlrev_b64 v[8:9], 11, v[10:11]
	v_pk_add_f32 v[12:13], v[12:13], 1.0 op_sel_hi:[1,0]
	v_lshl_add_u64 v[16:17], v[0:1], 0, v[8:9]
	ds_read_b128 v[8:11], v7
	v_div_scale_f32 v7, s[50:51], v13, v13, 1.0
	v_rcp_f32_e32 v18, v7
	v_pk_add_f32 v[14:15], v[14:15], 1.0 op_sel_hi:[1,0]
	v_fma_f32 v19, -v7, v18, 1.0
	v_fmac_f32_e32 v18, v19, v18
	v_div_scale_f32 v19, vcc, 1.0, v13, 1.0
	v_mul_f32_e32 v20, v19, v18
	v_fma_f32 v21, -v7, v20, v19
	v_fmac_f32_e32 v20, v21, v18
	v_fma_f32 v7, -v7, v20, v19
	v_div_fmas_f32 v7, v7, v18, v20
	v_div_fixup_f32 v13, v7, v13, 1.0
	v_div_scale_f32 v7, s[50:51], v12, v12, 1.0
	v_rcp_f32_e32 v18, v7
	s_nop 0
	v_fma_f32 v19, -v7, v18, 1.0
	v_fmac_f32_e32 v18, v19, v18
	v_div_scale_f32 v19, vcc, 1.0, v12, 1.0
	v_mul_f32_e32 v20, v19, v18
	v_fma_f32 v21, -v7, v20, v19
	v_fmac_f32_e32 v20, v21, v18
	v_fma_f32 v7, -v7, v20, v19
	v_div_fmas_f32 v7, v7, v18, v20
	v_div_fixup_f32 v12, v7, v12, 1.0
	v_div_scale_f32 v7, s[50:51], v15, v15, 1.0
	s_waitcnt lgkmcnt(0)
	v_mov_b32_e32 v18, v8
	v_rcp_f32_e32 v8, v7
	v_mov_b32_e32 v19, v10
	v_pk_mul_f32 v[12:13], v[18:19], v[12:13]
	v_fma_f32 v10, -v7, v8, 1.0
	v_fmac_f32_e32 v8, v10, v8
	v_div_scale_f32 v10, vcc, 1.0, v15, 1.0
	v_mul_f32_e32 v18, v10, v8
	v_fma_f32 v19, -v7, v18, v10
	v_fmac_f32_e32 v18, v19, v8
	v_fma_f32 v7, -v7, v18, v10
	v_div_fmas_f32 v7, v7, v8, v18
	v_div_fixup_f32 v15, v7, v15, 1.0
	v_div_scale_f32 v7, s[50:51], v14, v14, 1.0
	v_rcp_f32_e32 v8, v7
	s_nop 0
	v_fma_f32 v10, -v7, v8, 1.0
	v_fmac_f32_e32 v8, v10, v8
	v_div_scale_f32 v10, vcc, 1.0, v14, 1.0
	v_mul_f32_e32 v18, v10, v8
	v_fma_f32 v19, -v7, v18, v10
	v_fmac_f32_e32 v18, v19, v8
	v_fma_f32 v7, -v7, v18, v10
	v_div_fmas_f32 v7, v7, v8, v18
	v_div_fixup_f32 v14, v7, v14, 1.0
	v_mov_b32_e32 v10, v9
	v_pk_mul_f32 v[8:9], v[10:11], v[14:15]
	v_and_b32_sdwa v10, v12, v95 dst_sel:DWORD dst_unused:UNUSED_PAD src0_sel:WORD_1 src1_sel:DWORD
	v_add3_u32 v10, v12, v10, s39
	v_and_b32_sdwa v11, v9, v95 dst_sel:DWORD dst_unused:UNUSED_PAD src0_sel:WORD_1 src1_sel:DWORD
	v_and_b32_sdwa v12, v8, v95 dst_sel:DWORD dst_unused:UNUSED_PAD src0_sel:WORD_1 src1_sel:DWORD
	v_and_b32_sdwa v7, v13, v95 dst_sel:DWORD dst_unused:UNUSED_PAD src0_sel:WORD_1 src1_sel:DWORD
	v_add3_u32 v9, v9, v11, s39
	v_add3_u32 v8, v8, v12, s39
	v_add3_u32 v7, v13, v7, s39
	v_and_b32_e32 v9, 0xffff0000, v9
	v_and_b32_e32 v8, 0xffff0000, v8
	v_or_b32_sdwa v9, v9, v7 dst_sel:DWORD dst_unused:UNUSED_PAD src0_sel:DWORD src1_sel:WORD_1
	v_or_b32_sdwa v8, v8, v10 dst_sel:DWORD dst_unused:UNUSED_PAD src0_sel:DWORD src1_sel:WORD_1
	v_add_u32_e32 v7, 0x600, v6
	global_store_dwordx2 v[16:17], v[8:9], off
	v_ashrrev_i32_e32 v8, 5, v7
	v_ashrrev_i32_e32 v9, 31, v8
	v_lshl_add_u64 v[10:11], s[74:75], 0, v[8:9]
	v_lshl_or_b32 v7, v8, 9, v169
	v_mad_u64_u32 v[8:9], s[50:51], v10, s22, v[4:5]
	v_mad_i32_i24 v9, v11, s22, v9
	v_lshl_add_u64 v[8:9], v[8:9], 0, v[2:3]
	v_add_co_u32_e32 v8, vcc, s36, v8
	v_add_u32_e32 v6, 0x700, v6
	s_nop 0
	v_addc_co_u32_e32 v9, vcc, 0, v9, vcc
	v_mov_b32_e32 v8, v232
	v_mov_b32_e32 v9, v233
	v_lshlrev_b32_e32 v12, 16, v8
	v_and_b32_e32 v8, 0xffff0000, v8
	v_lshlrev_b32_e32 v13, 16, v9
	v_mul_f32_e32 v8, 0xbfb8aa3b, v8
	v_mul_f32_e32 v12, 0xbfb8aa3b, v12
	v_exp_f32_e32 v14, v8
	v_mul_f32_e32 v8, 0xbfb8aa3b, v13
	v_exp_f32_e32 v12, v12
	v_exp_f32_e32 v13, v8
	v_and_b32_e32 v9, 0xffff0000, v9
	v_mul_f32_e32 v8, 0xbfb8aa3b, v9
	v_exp_f32_e32 v15, v8
	v_lshlrev_b64 v[8:9], 11, v[10:11]
	v_pk_add_f32 v[12:13], v[12:13], 1.0 op_sel_hi:[1,0]
	v_lshl_add_u64 v[16:17], v[0:1], 0, v[8:9]
	ds_read_b128 v[8:11], v7
	v_div_scale_f32 v7, s[50:51], v13, v13, 1.0
	v_rcp_f32_e32 v18, v7
	v_pk_add_f32 v[14:15], v[14:15], 1.0 op_sel_hi:[1,0]
	v_fma_f32 v19, -v7, v18, 1.0
	v_fmac_f32_e32 v18, v19, v18
	v_div_scale_f32 v19, vcc, 1.0, v13, 1.0
	v_mul_f32_e32 v20, v19, v18
	v_fma_f32 v21, -v7, v20, v19
	v_fmac_f32_e32 v20, v21, v18
	v_fma_f32 v7, -v7, v20, v19
	v_div_fmas_f32 v7, v7, v18, v20
	v_div_fixup_f32 v13, v7, v13, 1.0
	v_div_scale_f32 v7, s[50:51], v12, v12, 1.0
	v_rcp_f32_e32 v18, v7
	s_nop 0
	v_fma_f32 v19, -v7, v18, 1.0
	v_fmac_f32_e32 v18, v19, v18
	v_div_scale_f32 v19, vcc, 1.0, v12, 1.0
	v_mul_f32_e32 v20, v19, v18
	v_fma_f32 v21, -v7, v20, v19
	v_fmac_f32_e32 v20, v21, v18
	v_fma_f32 v7, -v7, v20, v19
	v_div_fmas_f32 v7, v7, v18, v20
	v_div_fixup_f32 v12, v7, v12, 1.0
	v_div_scale_f32 v7, s[50:51], v15, v15, 1.0
	s_waitcnt lgkmcnt(0)
; DEVI float sigmoidf_(float x) { return 1.f / (1.f + __expf(-x)); }
; template <int BR, int IN, int OUT>
; DEVI void p6_branch(const Params& P, int pm, int pn, float* macc, char* smem, int tid) {
;     ...
; #pragma unroll 8
;   for (int q = 0; q < 16; ++q) {
;     const int id = tid + 256 * q, row = id >> 5, c4 = id & 31;
;     const long grow = (long)pm * 128 + row;
;     const int gcol = pn * 128 + c4 * 4;
;     float4 a = *reinterpret_cast<const float4*>(T + row * 128 + c4 * 4);
;     float g[4];
;     load4bf(Z + grow * NCOL + (9 + BR) * 1024 + gcol, g);
;     float v[4] = {sigmoidf_(g[0]) * a.x, sigmoidf_(g[1]) * a.y, sigmoidf_(g[2]) * a.z, sigmoidf_(g[3]) * a.w};
;     if (IN == 1) {
;       float mo[4]; load4bf(M + grow * 1024 + gcol, mo);
;       v[0] += mo[0]; v[1] += mo[1]; v[2] += mo[2]; v[3] += mo[3];
;     }
;     if (IN == 2) {
;       float4 mo = *reinterpret_cast<const float4*>(macc + grow * 1024 + gcol);
;       v[0] += mo.x; v[1] += mo.y; v[2] += mo.z; v[3] += mo.w;
;     }
;     if (OUT == 1) *reinterpret_cast<float4*>(macc + grow * 1024 + gcol) = make_float4(v[0], v[1], v[2], v[3]);
;     else store4bf(M + grow * 1024 + gcol, v);
;   }
	v_mov_b32_e32 v18, v8
	v_rcp_f32_e32 v8, v7
	v_mov_b32_e32 v19, v10
	v_pk_mul_f32 v[12:13], v[18:19], v[12:13]
	v_fma_f32 v10, -v7, v8, 1.0
	v_fmac_f32_e32 v8, v10, v8
	v_div_scale_f32 v10, vcc, 1.0, v15, 1.0
	v_mul_f32_e32 v18, v10, v8
	v_fma_f32 v19, -v7, v18, v10
	v_fmac_f32_e32 v18, v19, v8
	v_fma_f32 v7, -v7, v18, v10
	v_div_fmas_f32 v7, v7, v8, v18
	v_div_fixup_f32 v15, v7, v15, 1.0
	v_div_scale_f32 v7, s[50:51], v14, v14, 1.0
	v_rcp_f32_e32 v8, v7
	s_nop 0
	v_fma_f32 v10, -v7, v8, 1.0
	v_fmac_f32_e32 v8, v10, v8
	v_div_scale_f32 v10, vcc, 1.0, v14, 1.0
	v_mul_f32_e32 v18, v10, v8
	v_fma_f32 v19, -v7, v18, v10
	v_fmac_f32_e32 v18, v19, v8
	v_fma_f32 v7, -v7, v18, v10
	v_div_fmas_f32 v7, v7, v8, v18
	v_div_fixup_f32 v14, v7, v14, 1.0
	v_mov_b32_e32 v10, v9
	v_pk_mul_f32 v[8:9], v[10:11], v[14:15]
	v_and_b32_sdwa v10, v12, v95 dst_sel:DWORD dst_unused:UNUSED_PAD src0_sel:WORD_1 src1_sel:DWORD
	v_add3_u32 v10, v12, v10, s39
	v_and_b32_sdwa v11, v9, v95 dst_sel:DWORD dst_unused:UNUSED_PAD src0_sel:WORD_1 src1_sel:DWORD
	v_and_b32_sdwa v12, v8, v95 dst_sel:DWORD dst_unused:UNUSED_PAD src0_sel:WORD_1 src1_sel:DWORD
	v_and_b32_sdwa v7, v13, v95 dst_sel:DWORD dst_unused:UNUSED_PAD src0_sel:WORD_1 src1_sel:DWORD
	v_add3_u32 v9, v9, v11, s39
	v_add3_u32 v8, v8, v12, s39
	v_add3_u32 v7, v13, v7, s39
	v_and_b32_e32 v9, 0xffff0000, v9
	v_and_b32_e32 v8, 0xffff0000, v8
	v_or_b32_sdwa v9, v9, v7 dst_sel:DWORD dst_unused:UNUSED_PAD src0_sel:DWORD src1_sel:WORD_1
	v_or_b32_sdwa v8, v8, v10 dst_sel:DWORD dst_unused:UNUSED_PAD src0_sel:DWORD src1_sel:WORD_1
	global_store_dwordx2 v[16:17], v[8:9], off
	v_ashrrev_i32_e32 v8, 5, v6
	v_ashrrev_i32_e32 v9, 31, v8
	v_lshl_add_u64 v[6:7], s[74:75], 0, v[8:9]
	v_mad_u64_u32 v[4:5], s[50:51], v6, s22, v[4:5]
	v_mad_i32_i24 v5, v7, s22, v5
	v_lshl_add_u64 v[4:5], v[4:5], 0, v[2:3]
	v_add_co_u32_e32 v4, vcc, s36, v4
	v_lshl_or_b32 v8, v8, 9, v169
	s_nop 0
	v_addc_co_u32_e32 v5, vcc, 0, v5, vcc
	v_mov_b32_e32 v4, v234
	v_mov_b32_e32 v5, v235
	v_lshlrev_b32_e32 v9, 16, v4
	v_and_b32_e32 v4, 0xffff0000, v4
	v_lshlrev_b32_e32 v11, 16, v5
	v_mul_f32_e32 v4, 0xbfb8aa3b, v4
	v_mul_f32_e32 v9, 0xbfb8aa3b, v9
	v_exp_f32_e32 v12, v4
	v_mul_f32_e32 v4, 0xbfb8aa3b, v11
	v_exp_f32_e32 v10, v9
	v_exp_f32_e32 v11, v4
	v_and_b32_e32 v5, 0xffff0000, v5
	v_mul_f32_e32 v4, 0xbfb8aa3b, v5
	v_exp_f32_e32 v13, v4
	v_lshlrev_b64 v[4:5], 11, v[6:7]
	v_lshl_add_u64 v[14:15], v[0:1], 0, v[4:5]
	ds_read_b128 v[4:7], v8
	v_pk_add_f32 v[8:9], v[10:11], 1.0 op_sel_hi:[1,0]
	s_nop 0
	v_div_scale_f32 v10, s[50:51], v9, v9, 1.0
	v_rcp_f32_e32 v11, v10
	s_nop 0
	v_fma_f32 v16, -v10, v11, 1.0
	v_fmac_f32_e32 v11, v16, v11
	v_div_scale_f32 v16, vcc, 1.0, v9, 1.0
	v_mul_f32_e32 v17, v16, v11
	v_fma_f32 v18, -v10, v17, v16
	v_fmac_f32_e32 v17, v18, v11
	v_fma_f32 v10, -v10, v17, v16
	v_div_fmas_f32 v10, v10, v11, v17
	v_div_fixup_f32 v9, v10, v9, 1.0
	v_div_scale_f32 v10, s[50:51], v8, v8, 1.0
	v_rcp_f32_e32 v11, v10
	s_nop 0
	v_fma_f32 v16, -v10, v11, 1.0
	v_fmac_f32_e32 v11, v16, v11
	v_div_scale_f32 v16, vcc, 1.0, v8, 1.0
	v_mul_f32_e32 v17, v16, v11
	v_fma_f32 v18, -v10, v17, v16
	v_fmac_f32_e32 v17, v18, v11
	v_fma_f32 v10, -v10, v17, v16
	v_div_fmas_f32 v10, v10, v11, v17
	v_div_fixup_f32 v8, v10, v8, 1.0
	s_waitcnt lgkmcnt(0)
	v_mov_b32_e32 v10, v4
	v_mov_b32_e32 v11, v6
	v_pk_mul_f32 v[8:9], v[10:11], v[8:9]
	v_pk_add_f32 v[10:11], v[12:13], 1.0 op_sel_hi:[1,0]
	s_nop 0
	v_div_scale_f32 v4, s[50:51], v11, v11, 1.0
	v_rcp_f32_e32 v6, v4
	s_nop 0
	v_fma_f32 v12, -v4, v6, 1.0
	v_fmac_f32_e32 v6, v12, v6
	v_div_scale_f32 v12, vcc, 1.0, v11, 1.0
	v_mul_f32_e32 v13, v12, v6
	v_fma_f32 v16, -v4, v13, v12
	v_fmac_f32_e32 v13, v16, v6
	v_fma_f32 v4, -v4, v13, v12
	v_div_fmas_f32 v4, v4, v6, v13
	v_div_fixup_f32 v11, v4, v11, 1.0
	v_div_scale_f32 v4, s[50:51], v10, v10, 1.0
	v_rcp_f32_e32 v6, v4
	s_nop 0
	v_fma_f32 v12, -v4, v6, 1.0
	v_fmac_f32_e32 v6, v12, v6
	v_div_scale_f32 v12, vcc, 1.0, v10, 1.0
	v_mul_f32_e32 v13, v12, v6
	v_fma_f32 v16, -v4, v13, v12
	v_fmac_f32_e32 v13, v16, v6
	v_fma_f32 v4, -v4, v13, v12
	v_div_fmas_f32 v4, v4, v6, v13
	v_div_fixup_f32 v10, v4, v10, 1.0
	v_mov_b32_e32 v6, v5
	v_pk_mul_f32 v[4:5], v[6:7], v[10:11]
	v_and_b32_sdwa v6, v9, v95 dst_sel:DWORD dst_unused:UNUSED_PAD src0_sel:WORD_1 src1_sel:DWORD
	v_and_b32_sdwa v7, v8, v95 dst_sel:DWORD dst_unused:UNUSED_PAD src0_sel:WORD_1 src1_sel:DWORD
	v_add3_u32 v7, v8, v7, s39
	v_add3_u32 v6, v9, v6, s39
	v_and_b32_sdwa v8, v5, v95 dst_sel:DWORD dst_unused:UNUSED_PAD src0_sel:WORD_1 src1_sel:DWORD
	v_and_b32_sdwa v9, v4, v95 dst_sel:DWORD dst_unused:UNUSED_PAD src0_sel:WORD_1 src1_sel:DWORD
	v_add3_u32 v5, v5, v8, s39
	v_add3_u32 v4, v4, v9, s39
	v_and_b32_e32 v5, 0xffff0000, v5
	v_and_b32_e32 v4, 0xffff0000, v4
	v_or_b32_sdwa v5, v5, v6 dst_sel:DWORD dst_unused:UNUSED_PAD src0_sel:DWORD src1_sel:WORD_1
	v_or_b32_sdwa v4, v4, v7 dst_sel:DWORD dst_unused:UNUSED_PAD src0_sel:DWORD src1_sel:WORD_1
	global_store_dwordx2 v[14:15], v[4:5], off
	s_cbranch_scc1 .LBB0_513
	s_mov_b64 s[26:27], 0

; DEVI float sigmoidf_(float x) { return 1.f / (1.f + __expf(-x)); }
; DEVI char* wsp(const Params& P, size_t off) { asm volatile("" : "+s"(off)); return P.ws + off; }
; #define ZERO_ACC(a) _Pragma("unroll") for (int m_ = 0; m_ < 4; ++m_) _Pragma("unroll") for (int n_ = 0; n_ < 4; ++n_) a[m_][n_] = f32x4{0.f, 0.f, 0.f, 0.f}
; template <int BR, int IN, int OUT>
; DEVI void p6_branch(const Params& P, int pm, int pn, float* macc, char* smem, int tid) {
;   asm volatile("" : "+s"(pm), "+s"(pn));
;   const bfu* Z = (const bfu*)wsp(P, O_Z);
;   bfu* M = (bfu*)wsp(P, O_CB);
;   const bfu* A = (const bfu*)wsp(P, BR == 0 ? O_UA : BR == 1 ? O_UB : O_UC) + (long)pm * 128 * 1024;
;   const bfu* B = (const bfu*)wsp(P, BR == 0 ? O_WOA : BR == 1 ? O_WOB : O_WOC) + (long)pn * 128 * 1024;
;   f32x4 acc[4][4]; ZERO_ACC(acc);
;   gemm_core(acc, A, 1024, B, 1024, 1024, smem, tid);
;   epi_stage_f32(acc, smem, tid);
;   const float* T = reinterpret_cast<const float*>(smem);
; #pragma unroll 8
;   for (int q = 0; q < 16; ++q) {
;     const int id = tid + 256 * q, row = id >> 5, c4 = id & 31;
;     const long grow = (long)pm * 128 + row;
;     const int gcol = pn * 128 + c4 * 4;
;     float4 a = *reinterpret_cast<const float4*>(T + row * 128 + c4 * 4);
;     float g[4];
;     load4bf(Z + grow * NCOL + (9 + BR) * 1024 + gcol, g);
;     float v[4] = {sigmoidf_(g[0]) * a.x, sigmoidf_(g[1]) * a.y, sigmoidf_(g[2]) * a.z, sigmoidf_(g[3]) * a.w};
;     if (IN == 1) {
;       float mo[4]; load4bf(M + grow * 1024 + gcol, mo);
;       v[0] += mo[0]; v[1] += mo[1]; v[2] += mo[2]; v[3] += mo[3];
;     }
;     if (IN == 2) {
;       float4 mo = *reinterpret_cast<const float4*>(macc + grow * 1024 + gcol);
;       v[0] += mo.x; v[1] += mo.y; v[2] += mo.z; v[3] += mo.w;
;     }
;     if (OUT == 1) *reinterpret_cast<float4*>(macc + grow * 1024 + gcol) = make_float4(v[0], v[1], v[2], v[3]);
;     else store4bf(M + grow * 1024 + gcol, v);
;   }
.LBB0_737:
	v_add_u32_e32 v242, s24, v91
	v_ashrrev_i32_e32 v240, 5, v242
	v_ashrrev_i32_e32 v241, 31, v240
	v_lshl_add_u64 v[244:245], s[46:47], 0, v[240:241]
	v_mov_b64_e32 v[240:241], s[44:45]
	v_mad_u64_u32 v[246:247], s[48:49], v244, s22, v[240:241]
	v_mad_i32_i24 v247, v245, s22, v247
	v_lshl_add_u64 v[246:247], v[246:247], 0, v[4:5]
	v_add_co_u32_e32 v246, vcc, 0x5000, v246
	s_nop 1
	v_addc_co_u32_e32 v247, vcc, 0, v247, vcc
	global_load_dwordx2 v[208:209], v[246:247], off offset:2048
	v_add_u32_e32 v242, s24, v91
	v_ashrrev_i32_e32 v240, 5, v242
	v_ashrrev_i32_e32 v241, 31, v240
	v_lshl_add_u64 v[244:245], s[46:47], 0, v[240:241]
	v_lshlrev_b64 v[246:247], 11, v[244:245]
	v_lshl_add_u64 v[246:247], v[0:1], 0, v[246:247]
	global_load_dwordx2 v[210:211], v[246:247], off
	v_add_u32_e32 v242, s24, v91
	v_mov_b64_e32 v[240:241], s[44:45]
	v_add_u32_e32 v243, 0x100, v242
	v_ashrrev_i32_e32 v244, 5, v243
	v_ashrrev_i32_e32 v245, 31, v244
	v_lshl_add_u64 v[246:247], s[46:47], 0, v[244:245]
	v_mad_u64_u32 v[244:245], s[48:49], v246, s22, v[240:241]
	v_mad_i32_i24 v245, v247, s22, v245
	v_lshl_add_u64 v[244:245], v[244:245], 0, v[4:5]
	v_add_co_u32_e32 v244, vcc, s21, v244
	s_nop 1
	v_addc_co_u32_e32 v245, vcc, 0, v245, vcc
	global_load_dwordx2 v[212:213], v[244:245], off offset:2048
	v_add_u32_e32 v240, s24, v91
	v_add_u32_e32 v241, 0x100, v240
	v_ashrrev_i32_e32 v242, 5, v241
	v_ashrrev_i32_e32 v243, 31, v242
	v_lshl_add_u64 v[244:245], s[46:47], 0, v[242:243]
	v_lshlrev_b64 v[242:243], 11, v[244:245]
	v_lshl_add_u64 v[242:243], v[0:1], 0, v[242:243]
	global_load_dwordx2 v[214:215], v[242:243], off
	v_add_u32_e32 v242, s24, v91
	v_mov_b64_e32 v[240:241], s[44:45]
	v_add_u32_e32 v243, 0x200, v242
	v_ashrrev_i32_e32 v244, 5, v243
	v_ashrrev_i32_e32 v245, 31, v244
	v_lshl_add_u64 v[246:247], s[46:47], 0, v[244:245]
	v_mad_u64_u32 v[244:245], s[48:49], v246, s22, v[240:241]
	v_mad_i32_i24 v245, v247, s22, v245
	v_lshl_add_u64 v[244:245], v[244:245], 0, v[4:5]
	v_add_co_u32_e32 v244, vcc, s21, v244
	s_nop 1
	v_addc_co_u32_e32 v245, vcc, 0, v245, vcc
	global_load_dwordx2 v[216:217], v[244:245], off offset:2048
	v_add_u32_e32 v240, s24, v91
	v_add_u32_e32 v241, 0x200, v240
	v_ashrrev_i32_e32 v242, 5, v241
	v_ashrrev_i32_e32 v243, 31, v242
	v_lshl_add_u64 v[244:245], s[46:47], 0, v[242:243]
	v_lshlrev_b64 v[242:243], 11, v[244:245]
	v_lshl_add_u64 v[242:243], v[0:1], 0, v[242:243]
	global_load_dwordx2 v[218:219], v[242:243], off
	v_add_u32_e32 v242, s24, v91
	v_mov_b64_e32 v[240:241], s[44:45]
	v_add_u32_e32 v243, 0x300, v242
	v_ashrrev_i32_e32 v244, 5, v243
	v_ashrrev_i32_e32 v245, 31, v244
	v_lshl_add_u64 v[246:247], s[46:47], 0, v[244:245]
	v_mad_u64_u32 v[244:245], s[48:49], v246, s22, v[240:241]
	v_mad_i32_i24 v245, v247, s22, v245
	v_lshl_add_u64 v[244:245], v[244:245], 0, v[4:5]
	v_add_co_u32_e32 v244, vcc, s21, v244
	s_nop 1
	v_addc_co_u32_e32 v245, vcc, 0, v245, vcc
	global_load_dwordx2 v[220:221], v[244:245], off offset:2048
	v_add_u32_e32 v240, s24, v91
	v_add_u32_e32 v241, 0x300, v240
	v_ashrrev_i32_e32 v242, 5, v241
	v_ashrrev_i32_e32 v243, 31, v242
	v_lshl_add_u64 v[244:245], s[46:47], 0, v[242:243]
	v_lshlrev_b64 v[242:243], 11, v[244:245]
	v_lshl_add_u64 v[242:243], v[0:1], 0, v[242:243]
	global_load_dwordx2 v[222:223], v[242:243], off
	v_add_u32_e32 v242, s24, v91
	v_mov_b64_e32 v[240:241], s[44:45]
	v_add_u32_e32 v243, 0x400, v242
	v_ashrrev_i32_e32 v244, 5, v243
	v_ashrrev_i32_e32 v245, 31, v244
	v_lshl_add_u64 v[246:247], s[46:47], 0, v[244:245]
	v_mad_u64_u32 v[244:245], s[48:49], v246, s22, v[240:241]
	v_mad_i32_i24 v245, v247, s22, v245
	v_lshl_add_u64 v[244:245], v[244:245], 0, v[4:5]
	v_add_co_u32_e32 v244, vcc, s21, v244
	s_nop 1
	v_addc_co_u32_e32 v245, vcc, 0, v245, vcc
	global_load_dwordx2 v[224:225], v[244:245], off offset:2048
	v_add_u32_e32 v240, s24, v91
	v_add_u32_e32 v241, 0x400, v240
	v_ashrrev_i32_e32 v242, 5, v241
	v_ashrrev_i32_e32 v243, 31, v242
	v_lshl_add_u64 v[244:245], s[46:47], 0, v[242:243]
	v_lshlrev_b64 v[242:243], 11, v[244:245]
	v_lshl_add_u64 v[242:243], v[0:1], 0, v[242:243]
	global_load_dwordx2 v[226:227], v[242:243], off
	v_add_u32_e32 v242, s24, v91
	v_mov_b64_e32 v[240:241], s[44:45]
	v_add_u32_e32 v243, 0x500, v242
	v_ashrrev_i32_e32 v244, 5, v243
	v_ashrrev_i32_e32 v245, 31, v244
	v_lshl_add_u64 v[246:247], s[46:47], 0, v[244:245]
	v_mad_u64_u32 v[244:245], s[48:49], v246, s22, v[240:241]
	v_mad_i32_i24 v245, v247, s22, v245
	v_lshl_add_u64 v[244:245], v[244:245], 0, v[4:5]
	v_add_co_u32_e32 v244, vcc, s21, v244
	s_nop 1
	v_addc_co_u32_e32 v245, vcc, 0, v245, vcc
	global_load_dwordx2 v[228:229], v[244:245], off offset:2048
	v_add_u32_e32 v240, s24, v91
	v_add_u32_e32 v241, 0x500, v240
	v_ashrrev_i32_e32 v242, 5, v241
	v_ashrrev_i32_e32 v243, 31, v242
	v_lshl_add_u64 v[244:245], s[46:47], 0, v[242:243]
	v_lshlrev_b64 v[242:243], 11, v[244:245]
	v_lshl_add_u64 v[242:243], v[0:1], 0, v[242:243]
	global_load_dwordx2 v[230:231], v[242:243], off
	v_add_u32_e32 v242, s24, v91
	v_mov_b64_e32 v[240:241], s[44:45]
	v_add_u32_e32 v243, 0x600, v242
	v_ashrrev_i32_e32 v244, 5, v243
	v_ashrrev_i32_e32 v245, 31, v244
	v_lshl_add_u64 v[246:247], s[46:47], 0, v[244:245]
	v_mad_u64_u32 v[244:245], s[48:49], v246, s22, v[240:241]
	v_mad_i32_i24 v245, v247, s22, v245
	v_lshl_add_u64 v[244:245], v[244:245], 0, v[4:5]
	v_add_co_u32_e32 v244, vcc, s21, v244
	s_nop 1
	v_addc_co_u32_e32 v245, vcc, 0, v245, vcc
	global_load_dwordx2 v[232:233], v[244:245], off offset:2048
	v_add_u32_e32 v240, s24, v91
	v_add_u32_e32 v241, 0x600, v240
	v_ashrrev_i32_e32 v242, 5, v241
	v_ashrrev_i32_e32 v243, 31, v242
	v_lshl_add_u64 v[244:245], s[46:47], 0, v[242:243]
	v_lshlrev_b64 v[242:243], 11, v[244:245]
	v_lshl_add_u64 v[242:243], v[0:1], 0, v[242:243]
	global_load_dwordx2 v[234:235], v[242:243], off
	v_add_u32_e32 v242, s24, v91
	v_mov_b64_e32 v[240:241], s[44:45]
	v_add_u32_e32 v242, 0x700, v242
	v_ashrrev_i32_e32 v242, 5, v242
	v_ashrrev_i32_e32 v243, 31, v242
	v_lshl_add_u64 v[244:245], s[46:47], 0, v[242:243]
	v_mad_u64_u32 v[240:241], s[48:49], v244, s22, v[240:241]
	v_mad_i32_i24 v241, v245, s22, v241
	v_lshl_add_u64 v[240:241], v[240:241], 0, v[4:5]
	v_add_co_u32_e32 v240, vcc, s21, v240
	s_nop 1
	v_addc_co_u32_e32 v241, vcc, 0, v241, vcc
	global_load_dwordx2 v[236:237], v[240:241], off offset:2048
	v_add_u32_e32 v242, s24, v91
	v_add_u32_e32 v242, 0x700, v242
	v_ashrrev_i32_e32 v242, 5, v242
	v_ashrrev_i32_e32 v243, 31, v242
	v_lshl_add_u64 v[244:245], s[46:47], 0, v[242:243]
	v_lshlrev_b64 v[240:241], 11, v[244:245]
	v_lshl_add_u64 v[240:241], v[0:1], 0, v[240:241]
	global_load_dwordx2 v[238:239], v[240:241], off
	s_waitcnt vmcnt(0)
; DEVI float sigmoidf_(float x) { return 1.f / (1.f + __expf(-x)); }
; DEVI char* wsp(const Params& P, size_t off) { asm volatile("" : "+s"(off)); return P.ws + off; }
; #define ZERO_ACC(a) _Pragma("unroll") for (int m_ = 0; m_ < 4; ++m_) _Pragma("unroll") for (int n_ = 0; n_ < 4; ++n_) a[m_][n_] = f32x4{0.f, 0.f, 0.f, 0.f}
; template <int BR, int IN, int OUT>
; DEVI void p6_branch(const Params& P, int pm, int pn, float* macc, char* smem, int tid) {
;   asm volatile("" : "+s"(pm), "+s"(pn));
;   const bfu* Z = (const bfu*)wsp(P, O_Z);
;   bfu* M = (bfu*)wsp(P, O_CB);
;   const bfu* A = (const bfu*)wsp(P, BR == 0 ? O_UA : BR == 1 ? O_UB : O_UC) + (long)pm * 128 * 1024;
;   const bfu* B = (const bfu*)wsp(P, BR == 0 ? O_WOA : BR == 1 ? O_WOB : O_WOC) + (long)pn * 128 * 1024;
;   f32x4 acc[4][4]; ZERO_ACC(acc);
;   gemm_core(acc, A, 1024, B, 1024, 1024, smem, tid);
;   epi_stage_f32(acc, smem, tid);
;   const float* T = reinterpret_cast<const float*>(smem);
; #pragma unroll 8
;   for (int q = 0; q < 16; ++q) {
;     const int id = tid + 256 * q, row = id >> 5, c4 = id & 31;
;     const long grow = (long)pm * 128 + row;
;     const int gcol = pn * 128 + c4 * 4;
;     float4 a = *reinterpret_cast<const float4*>(T + row * 128 + c4 * 4);
;     float g[4];
;     load4bf(Z + grow * NCOL + (9 + BR) * 1024 + gcol, g);
;     float v[4] = {sigmoidf_(g[0]) * a.x, sigmoidf_(g[1]) * a.y, sigmoidf_(g[2]) * a.z, sigmoidf_(g[3]) * a.w};
;     if (IN == 1) {
;       float mo[4]; load4bf(M + grow * 1024 + gcol, mo);
;       v[0] += mo[0]; v[1] += mo[1]; v[2] += mo[2]; v[3] += mo[3];
;     }
;     if (IN == 2) {
;       float4 mo = *reinterpret_cast<const float4*>(macc + grow * 1024 + gcol);
;       v[0] += mo.x; v[1] += mo.y; v[2] += mo.z; v[3] += mo.w;
;     }
;     if (OUT == 1) *reinterpret_cast<float4*>(macc + grow * 1024 + gcol) = make_float4(v[0], v[1], v[2], v[3]);
;     else store4bf(M + grow * 1024 + gcol, v);
;   }
	s_nop 0
	v_add_u32_e32 v8, s24, v91
	v_ashrrev_i32_e32 v6, 5, v8
	v_ashrrev_i32_e32 v7, 31, v6
	v_lshl_add_u64 v[10:11], s[46:47], 0, v[6:7]
	v_lshl_or_b32 v9, v6, 9, v152
	v_mov_b64_e32 v[6:7], s[44:45]
	v_mad_u64_u32 v[12:13], s[48:49], v10, s22, v[6:7]
	v_mad_i32_i24 v13, v11, s22, v13
	v_lshl_add_u64 v[12:13], v[12:13], 0, v[4:5]
	v_add_co_u32_e32 v12, vcc, 0x5000, v12
	s_addk_i32 s24, 0x800
	s_nop 0
	v_addc_co_u32_e32 v13, vcc, 0, v13, vcc
	v_mov_b32_e32 v12, v208
	v_mov_b32_e32 v13, v209
	s_cmpk_lg_i32 s24, 0x1000
	v_lshlrev_b32_e32 v14, 16, v12
	v_and_b32_e32 v12, 0xffff0000, v12
	v_lshlrev_b32_e32 v16, 16, v13
	v_mul_f32_e32 v12, 0xbfb8aa3b, v12
	v_and_b32_e32 v13, 0xffff0000, v13
	v_exp_f32_e32 v15, v12
	v_mul_f32_e32 v12, 0xbfb8aa3b, v16
	v_exp_f32_e32 v16, v12
	v_mul_f32_e32 v12, 0xbfb8aa3b, v13
	v_exp_f32_e32 v17, v12
	v_lshlrev_b64 v[12:13], 11, v[10:11]
	v_lshl_add_u64 v[12:13], v[0:1], 0, v[12:13]
	v_mov_b32_e32 v12, v210
	v_mov_b32_e32 v13, v211
	v_mul_f32_e32 v14, 0xbfb8aa3b, v14
	v_exp_f32_e32 v14, v14
	v_lshlrev_b64 v[10:11], 12, v[10:11]
	v_lshl_add_u64 v[22:23], v[2:3], 0, v[10:11]
	v_pk_add_f32 v[14:15], v[14:15], 1.0 op_sel_hi:[1,0]
	v_lshlrev_b32_e32 v18, 16, v12
	v_and_b32_e32 v19, 0xffff0000, v12
	v_lshlrev_b32_e32 v20, 16, v13
	v_and_b32_e32 v21, 0xffff0000, v13
	ds_read_b128 v[10:13], v9
	v_div_scale_f32 v9, s[48:49], v15, v15, 1.0
	v_rcp_f32_e32 v24, v9
	s_nop 0
	v_fma_f32 v25, -v9, v24, 1.0
	v_fmac_f32_e32 v24, v25, v24
	v_div_scale_f32 v25, vcc, 1.0, v15, 1.0
	v_mul_f32_e32 v26, v25, v24
	v_fma_f32 v27, -v9, v26, v25
	v_fmac_f32_e32 v26, v27, v24
	v_fma_f32 v9, -v9, v26, v25
	v_div_fmas_f32 v9, v9, v24, v26
	v_div_fixup_f32 v15, v9, v15, 1.0
	v_div_scale_f32 v9, s[48:49], v14, v14, 1.0
	v_rcp_f32_e32 v24, v9
	s_nop 0
	v_fma_f32 v25, -v9, v24, 1.0
	v_fmac_f32_e32 v24, v25, v24
	v_div_scale_f32 v25, vcc, 1.0, v14, 1.0
	v_mul_f32_e32 v26, v25, v24
	v_fma_f32 v27, -v9, v26, v25
	v_fmac_f32_e32 v26, v27, v24
	v_fma_f32 v9, -v9, v26, v25
	v_div_fmas_f32 v9, v9, v24, v26
	v_div_fixup_f32 v14, v9, v14, 1.0
	s_waitcnt lgkmcnt(0)
	v_pk_fma_f32 v[10:11], v[10:11], v[14:15], v[18:19]
	v_pk_add_f32 v[14:15], v[16:17], 1.0 op_sel_hi:[1,0]
	s_nop 0
	v_div_scale_f32 v9, s[48:49], v15, v15, 1.0
	v_rcp_f32_e32 v16, v9
	s_nop 0
	v_fma_f32 v17, -v9, v16, 1.0
	v_fmac_f32_e32 v16, v17, v16
	v_div_scale_f32 v17, vcc, 1.0, v15, 1.0
	v_mul_f32_e32 v18, v17, v16
	v_fma_f32 v19, -v9, v18, v17
	v_fmac_f32_e32 v18, v19, v16
	v_fma_f32 v9, -v9, v18, v17
	v_div_fmas_f32 v9, v9, v16, v18
	v_div_fixup_f32 v15, v9, v15, 1.0
	v_div_scale_f32 v9, s[48:49], v14, v14, 1.0
	v_rcp_f32_e32 v16, v9
	s_nop 0
	v_fma_f32 v17, -v9, v16, 1.0
	v_fmac_f32_e32 v16, v17, v16
	v_div_scale_f32 v17, vcc, 1.0, v14, 1.0
	v_mul_f32_e32 v18, v17, v16
	v_fma_f32 v19, -v9, v18, v17
	v_fmac_f32_e32 v18, v19, v16
	v_fma_f32 v9, -v9, v18, v17
	v_div_fmas_f32 v9, v9, v16, v18
	v_div_fixup_f32 v14, v9, v14, 1.0
	v_pk_fma_f32 v[12:13], v[12:13], v[14:15], v[20:21]
	v_add_u32_e32 v9, 0x100, v8
	global_store_dwordx4 v[22:23], v[10:13], off
	s_nop 1
	v_ashrrev_i32_e32 v10, 5, v9
	v_ashrrev_i32_e32 v11, 31, v10
	v_lshl_add_u64 v[12:13], s[46:47], 0, v[10:11]
	v_lshl_or_b32 v9, v10, 9, v152
	v_mad_u64_u32 v[10:11], s[48:49], v12, s22, v[6:7]
	v_mad_i32_i24 v11, v13, s22, v11
	v_lshl_add_u64 v[10:11], v[10:11], 0, v[4:5]
	v_add_co_u32_e32 v10, vcc, s21, v10
	s_nop 1
	v_addc_co_u32_e32 v11, vcc, 0, v11, vcc
	v_mov_b32_e32 v10, v212
	v_mov_b32_e32 v11, v213
	v_lshlrev_b32_e32 v14, 16, v10
	v_and_b32_e32 v10, 0xffff0000, v10
	v_lshlrev_b32_e32 v16, 16, v11
	v_mul_f32_e32 v10, 0xbfb8aa3b, v10
	v_and_b32_e32 v11, 0xffff0000, v11
	v_exp_f32_e32 v15, v10
	v_mul_f32_e32 v10, 0xbfb8aa3b, v16
	v_exp_f32_e32 v16, v10
	v_mul_f32_e32 v10, 0xbfb8aa3b, v11
	v_exp_f32_e32 v17, v10
	v_lshlrev_b64 v[10:11], 11, v[12:13]
	v_lshl_add_u64 v[10:11], v[0:1], 0, v[10:11]
	v_mov_b32_e32 v10, v214
	v_mov_b32_e32 v11, v215
	v_mul_f32_e32 v14, 0xbfb8aa3b, v14
	v_exp_f32_e32 v14, v14
	v_lshlrev_b32_e32 v18, 16, v10
	v_and_b32_e32 v19, 0xffff0000, v10
	v_lshlrev_b32_e32 v20, 16, v11
	v_and_b32_e32 v21, 0xffff0000, v11
	v_lshlrev_b64 v[10:11], 12, v[12:13]
	v_pk_add_f32 v[14:15], v[14:15], 1.0 op_sel_hi:[1,0]
	v_lshl_add_u64 v[22:23], v[2:3], 0, v[10:11]
	ds_read_b128 v[10:13], v9
	v_div_scale_f32 v9, s[48:49], v15, v15, 1.0
	v_rcp_f32_e32 v24, v9
	s_nop 0
	v_fma_f32 v25, -v9, v24, 1.0
	v_fmac_f32_e32 v24, v25, v24
	v_div_scale_f32 v25, vcc, 1.0, v15, 1.0
	v_mul_f32_e32 v26, v25, v24
	v_fma_f32 v27, -v9, v26, v25
	v_fmac_f32_e32 v26, v27, v24
	v_fma_f32 v9, -v9, v26, v25
	v_div_fmas_f32 v9, v9, v24, v26
	v_div_fixup_f32 v15, v9, v15, 1.0
	v_div_scale_f32 v9, s[48:49], v14, v14, 1.0
	v_rcp_f32_e32 v24, v9
	s_nop 0
	v_fma_f32 v25, -v9, v24, 1.0
	v_fmac_f32_e32 v24, v25, v24
	v_div_scale_f32 v25, vcc, 1.0, v14, 1.0
	v_mul_f32_e32 v26, v25, v24
	v_fma_f32 v27, -v9, v26, v25
	v_fmac_f32_e32 v26, v27, v24
	v_fma_f32 v9, -v9, v26, v25
	v_div_fmas_f32 v9, v9, v24, v26
	v_div_fixup_f32 v14, v9, v14, 1.0
	s_waitcnt lgkmcnt(0)
; DEVI float sigmoidf_(float x) { return 1.f / (1.f + __expf(-x)); }
; DEVI char* wsp(const Params& P, size_t off) { asm volatile("" : "+s"(off)); return P.ws + off; }
; #define ZERO_ACC(a) _Pragma("unroll") for (int m_ = 0; m_ < 4; ++m_) _Pragma("unroll") for (int n_ = 0; n_ < 4; ++n_) a[m_][n_] = f32x4{0.f, 0.f, 0.f, 0.f}
; template <int BR, int IN, int OUT>
; DEVI void p6_branch(const Params& P, int pm, int pn, float* macc, char* smem, int tid) {
;   asm volatile("" : "+s"(pm), "+s"(pn));
;   const bfu* Z = (const bfu*)wsp(P, O_Z);
;   bfu* M = (bfu*)wsp(P, O_CB);
;   const bfu* A = (const bfu*)wsp(P, BR == 0 ? O_UA : BR == 1 ? O_UB : O_UC) + (long)pm * 128 * 1024;
;   const bfu* B = (const bfu*)wsp(P, BR == 0 ? O_WOA : BR == 1 ? O_WOB : O_WOC) + (long)pn * 128 * 1024;
;   f32x4 acc[4][4]; ZERO_ACC(acc);
;   gemm_core(acc, A, 1024, B, 1024, 1024, smem, tid);
;   epi_stage_f32(acc, smem, tid);
;   const float* T = reinterpret_cast<const float*>(smem);
; #pragma unroll 8
;   for (int q = 0; q < 16; ++q) {
;     const int id = tid + 256 * q, row = id >> 5, c4 = id & 31;
;     const long grow = (long)pm * 128 + row;
;     const int gcol = pn * 128 + c4 * 4;
;     float4 a = *reinterpret_cast<const float4*>(T + row * 128 + c4 * 4);
;     float g[4];
;     load4bf(Z + grow * NCOL + (9 + BR) * 1024 + gcol, g);
;     float v[4] = {sigmoidf_(g[0]) * a.x, sigmoidf_(g[1]) * a.y, sigmoidf_(g[2]) * a.z, sigmoidf_(g[3]) * a.w};
;     if (IN == 1) {
;       float mo[4]; load4bf(M + grow * 1024 + gcol, mo);
;       v[0] += mo[0]; v[1] += mo[1]; v[2] += mo[2]; v[3] += mo[3];
;     }
;     if (IN == 2) {
;       float4 mo = *reinterpret_cast<const float4*>(macc + grow * 1024 + gcol);
;       v[0] += mo.x; v[1] += mo.y; v[2] += mo.z; v[3] += mo.w;
;     }
;     if (OUT == 1) *reinterpret_cast<float4*>(macc + grow * 1024 + gcol) = make_float4(v[0], v[1], v[2], v[3]);
;     else store4bf(M + grow * 1024 + gcol, v);
;   }
	v_pk_fma_f32 v[10:11], v[10:11], v[14:15], v[18:19]
	v_pk_add_f32 v[14:15], v[16:17], 1.0 op_sel_hi:[1,0]
	s_nop 0
	v_div_scale_f32 v9, s[48:49], v15, v15, 1.0
	v_rcp_f32_e32 v16, v9
	s_nop 0
	v_fma_f32 v17, -v9, v16, 1.0
	v_fmac_f32_e32 v16, v17, v16
	v_div_scale_f32 v17, vcc, 1.0, v15, 1.0
	v_mul_f32_e32 v18, v17, v16
	v_fma_f32 v19, -v9, v18, v17
	v_fmac_f32_e32 v18, v19, v16
	v_fma_f32 v9, -v9, v18, v17
	v_div_fmas_f32 v9, v9, v16, v18
	v_div_fixup_f32 v15, v9, v15, 1.0
	v_div_scale_f32 v9, s[48:49], v14, v14, 1.0
	v_rcp_f32_e32 v16, v9
	s_nop 0
	v_fma_f32 v17, -v9, v16, 1.0
	v_fmac_f32_e32 v16, v17, v16
	v_div_scale_f32 v17, vcc, 1.0, v14, 1.0
	v_mul_f32_e32 v18, v17, v16
	v_fma_f32 v19, -v9, v18, v17
	v_fmac_f32_e32 v18, v19, v16
	v_fma_f32 v9, -v9, v18, v17
	v_div_fmas_f32 v9, v9, v16, v18
	v_div_fixup_f32 v14, v9, v14, 1.0
	v_pk_fma_f32 v[12:13], v[12:13], v[14:15], v[20:21]
	v_add_u32_e32 v9, 0x200, v8
	global_store_dwordx4 v[22:23], v[10:13], off
	s_nop 1
	v_ashrrev_i32_e32 v10, 5, v9
	v_ashrrev_i32_e32 v11, 31, v10
	v_lshl_add_u64 v[12:13], s[46:47], 0, v[10:11]
	v_lshl_or_b32 v9, v10, 9, v152
	v_mad_u64_u32 v[10:11], s[48:49], v12, s22, v[6:7]
	v_mad_i32_i24 v11, v13, s22, v11
	v_lshl_add_u64 v[10:11], v[10:11], 0, v[4:5]
	v_add_co_u32_e32 v10, vcc, s21, v10
	s_nop 1
	v_addc_co_u32_e32 v11, vcc, 0, v11, vcc
	v_mov_b32_e32 v10, v216
	v_mov_b32_e32 v11, v217
	v_lshlrev_b32_e32 v14, 16, v10
	v_and_b32_e32 v10, 0xffff0000, v10
	v_lshlrev_b32_e32 v16, 16, v11
	v_mul_f32_e32 v10, 0xbfb8aa3b, v10
	v_and_b32_e32 v11, 0xffff0000, v11
	v_exp_f32_e32 v15, v10
	v_mul_f32_e32 v10, 0xbfb8aa3b, v16
	v_exp_f32_e32 v16, v10
	v_mul_f32_e32 v10, 0xbfb8aa3b, v11
	v_exp_f32_e32 v17, v10
	v_lshlrev_b64 v[10:11], 11, v[12:13]
	v_lshl_add_u64 v[10:11], v[0:1], 0, v[10:11]
	v_mov_b32_e32 v10, v218
	v_mov_b32_e32 v11, v219
	v_mul_f32_e32 v14, 0xbfb8aa3b, v14
	v_exp_f32_e32 v14, v14
	v_lshlrev_b32_e32 v18, 16, v10
	v_and_b32_e32 v19, 0xffff0000, v10
	v_lshlrev_b32_e32 v20, 16, v11
	v_and_b32_e32 v21, 0xffff0000, v11
	v_lshlrev_b64 v[10:11], 12, v[12:13]
	v_pk_add_f32 v[14:15], v[14:15], 1.0 op_sel_hi:[1,0]
	v_lshl_add_u64 v[22:23], v[2:3], 0, v[10:11]
	ds_read_b128 v[10:13], v9
	v_div_scale_f32 v9, s[48:49], v15, v15, 1.0
	v_rcp_f32_e32 v24, v9
	s_nop 0
	v_fma_f32 v25, -v9, v24, 1.0
	v_fmac_f32_e32 v24, v25, v24
	v_div_scale_f32 v25, vcc, 1.0, v15, 1.0
	v_mul_f32_e32 v26, v25, v24
	v_fma_f32 v27, -v9, v26, v25
	v_fmac_f32_e32 v26, v27, v24
	v_fma_f32 v9, -v9, v26, v25
	v_div_fmas_f32 v9, v9, v24, v26
	v_div_fixup_f32 v15, v9, v15, 1.0
	v_div_scale_f32 v9, s[48:49], v14, v14, 1.0
	v_rcp_f32_e32 v24, v9
	s_nop 0
	v_fma_f32 v25, -v9, v24, 1.0
	v_fmac_f32_e32 v24, v25, v24
	v_div_scale_f32 v25, vcc, 1.0, v14, 1.0
	v_mul_f32_e32 v26, v25, v24
	v_fma_f32 v27, -v9, v26, v25
	v_fmac_f32_e32 v26, v27, v24
	v_fma_f32 v9, -v9, v26, v25
	v_div_fmas_f32 v9, v9, v24, v26
	v_div_fixup_f32 v14, v9, v14, 1.0
	s_waitcnt lgkmcnt(0)
	v_pk_fma_f32 v[10:11], v[10:11], v[14:15], v[18:19]
	v_pk_add_f32 v[14:15], v[16:17], 1.0 op_sel_hi:[1,0]
	s_nop 0
	v_div_scale_f32 v9, s[48:49], v15, v15, 1.0
	v_rcp_f32_e32 v16, v9
	s_nop 0
	v_fma_f32 v17, -v9, v16, 1.0
	v_fmac_f32_e32 v16, v17, v16
	v_div_scale_f32 v17, vcc, 1.0, v15, 1.0
	v_mul_f32_e32 v18, v17, v16
	v_fma_f32 v19, -v9, v18, v17
	v_fmac_f32_e32 v18, v19, v16
	v_fma_f32 v9, -v9, v18, v17
	v_div_fmas_f32 v9, v9, v16, v18
	v_div_fixup_f32 v15, v9, v15, 1.0
	v_div_scale_f32 v9, s[48:49], v14, v14, 1.0
	v_rcp_f32_e32 v16, v9
	s_nop 0
	v_fma_f32 v17, -v9, v16, 1.0
	v_fmac_f32_e32 v16, v17, v16
	v_div_scale_f32 v17, vcc, 1.0, v14, 1.0
	v_mul_f32_e32 v18, v17, v16
	v_fma_f32 v19, -v9, v18, v17
	v_fmac_f32_e32 v18, v19, v16
	v_fma_f32 v9, -v9, v18, v17
	v_div_fmas_f32 v9, v9, v16, v18
	v_div_fixup_f32 v14, v9, v14, 1.0
	v_pk_fma_f32 v[12:13], v[12:13], v[14:15], v[20:21]
	v_add_u32_e32 v9, 0x300, v8
	global_store_dwordx4 v[22:23], v[10:13], off
	s_nop 1
	v_ashrrev_i32_e32 v10, 5, v9
	v_ashrrev_i32_e32 v11, 31, v10
	v_lshl_add_u64 v[12:13], s[46:47], 0, v[10:11]
	v_lshl_or_b32 v9, v10, 9, v152
	v_mad_u64_u32 v[10:11], s[48:49], v12, s22, v[6:7]
	v_mad_i32_i24 v11, v13, s22, v11
	v_lshl_add_u64 v[10:11], v[10:11], 0, v[4:5]
	v_add_co_u32_e32 v10, vcc, s21, v10
	s_nop 1
	v_addc_co_u32_e32 v11, vcc, 0, v11, vcc
	v_mov_b32_e32 v10, v220
	v_mov_b32_e32 v11, v221
	v_lshlrev_b32_e32 v14, 16, v10
	v_and_b32_e32 v10, 0xffff0000, v10
	v_lshlrev_b32_e32 v16, 16, v11
	v_mul_f32_e32 v10, 0xbfb8aa3b, v10
	v_and_b32_e32 v11, 0xffff0000, v11
	v_exp_f32_e32 v15, v10
	v_mul_f32_e32 v10, 0xbfb8aa3b, v16
	v_exp_f32_e32 v16, v10
	v_mul_f32_e32 v10, 0xbfb8aa3b, v11
	v_exp_f32_e32 v17, v10
	v_lshlrev_b64 v[10:11], 11, v[12:13]
	v_lshl_add_u64 v[10:11], v[0:1], 0, v[10:11]
	v_mov_b32_e32 v10, v222
	v_mov_b32_e32 v11, v223
	v_mul_f32_e32 v14, 0xbfb8aa3b, v14
	v_exp_f32_e32 v14, v14
	v_lshlrev_b32_e32 v18, 16, v10
	v_and_b32_e32 v19, 0xffff0000, v10
	v_lshlrev_b32_e32 v20, 16, v11
	v_and_b32_e32 v21, 0xffff0000, v11
	v_lshlrev_b64 v[10:11], 12, v[12:13]
	v_pk_add_f32 v[14:15], v[14:15], 1.0 op_sel_hi:[1,0]
	v_lshl_add_u64 v[22:23], v[2:3], 0, v[10:11]
	ds_read_b128 v[10:13], v9
	v_div_scale_f32 v9, s[48:49], v15, v15, 1.0
	v_rcp_f32_e32 v24, v9
	s_nop 0
	v_fma_f32 v25, -v9, v24, 1.0
	v_fmac_f32_e32 v24, v25, v24
	v_div_scale_f32 v25, vcc, 1.0, v15, 1.0
	v_mul_f32_e32 v26, v25, v24
	v_fma_f32 v27, -v9, v26, v25
	v_fmac_f32_e32 v26, v27, v24
	v_fma_f32 v9, -v9, v26, v25
	v_div_fmas_f32 v9, v9, v24, v26
	v_div_fixup_f32 v15, v9, v15, 1.0
	v_div_scale_f32 v9, s[48:49], v14, v14, 1.0
	v_rcp_f32_e32 v24, v9
	s_nop 0
	v_fma_f32 v25, -v9, v24, 1.0
	v_fmac_f32_e32 v24, v25, v24
	v_div_scale_f32 v25, vcc, 1.0, v14, 1.0
	v_mul_f32_e32 v26, v25, v24
	v_fma_f32 v27, -v9, v26, v25
	v_fmac_f32_e32 v26, v27, v24
	v_fma_f32 v9, -v9, v26, v25
	v_div_fmas_f32 v9, v9, v24, v26
	v_div_fixup_f32 v14, v9, v14, 1.0
	s_waitcnt lgkmcnt(0)
; DEVI float sigmoidf_(float x) { return 1.f / (1.f + __expf(-x)); }
; DEVI char* wsp(const Params& P, size_t off) { asm volatile("" : "+s"(off)); return P.ws + off; }
; #define ZERO_ACC(a) _Pragma("unroll") for (int m_ = 0; m_ < 4; ++m_) _Pragma("unroll") for (int n_ = 0; n_ < 4; ++n_) a[m_][n_] = f32x4{0.f, 0.f, 0.f, 0.f}
; template <int BR, int IN, int OUT>
; DEVI void p6_branch(const Params& P, int pm, int pn, float* macc, char* smem, int tid) {
;   asm volatile("" : "+s"(pm), "+s"(pn));
;   const bfu* Z = (const bfu*)wsp(P, O_Z);
;   bfu* M = (bfu*)wsp(P, O_CB);
;   const bfu* A = (const bfu*)wsp(P, BR == 0 ? O_UA : BR == 1 ? O_UB : O_UC) + (long)pm * 128 * 1024;
;   const bfu* B = (const bfu*)wsp(P, BR == 0 ? O_WOA : BR == 1 ? O_WOB : O_WOC) + (long)pn * 128 * 1024;
;   f32x4 acc[4][4]; ZERO_ACC(acc);
;   gemm_core(acc, A, 1024, B, 1024, 1024, smem, tid);
;   epi_stage_f32(acc, smem, tid);
;   const float* T = reinterpret_cast<const float*>(smem);
; #pragma unroll 8
;   for (int q = 0; q < 16; ++q) {
;     const int id = tid + 256 * q, row = id >> 5, c4 = id & 31;
;     const long grow = (long)pm * 128 + row;
;     const int gcol = pn * 128 + c4 * 4;
;     float4 a = *reinterpret_cast<const float4*>(T + row * 128 + c4 * 4);
;     float g[4];
;     load4bf(Z + grow * NCOL + (9 + BR) * 1024 + gcol, g);
;     float v[4] = {sigmoidf_(g[0]) * a.x, sigmoidf_(g[1]) * a.y, sigmoidf_(g[2]) * a.z, sigmoidf_(g[3]) * a.w};
;     if (IN == 1) {
;       float mo[4]; load4bf(M + grow * 1024 + gcol, mo);
;       v[0] += mo[0]; v[1] += mo[1]; v[2] += mo[2]; v[3] += mo[3];
;     }
;     if (IN == 2) {
;       float4 mo = *reinterpret_cast<const float4*>(macc + grow * 1024 + gcol);
;       v[0] += mo.x; v[1] += mo.y; v[2] += mo.z; v[3] += mo.w;
;     }
;     if (OUT == 1) *reinterpret_cast<float4*>(macc + grow * 1024 + gcol) = make_float4(v[0], v[1], v[2], v[3]);
;     else store4bf(M + grow * 1024 + gcol, v);
;   }
	v_pk_fma_f32 v[10:11], v[10:11], v[14:15], v[18:19]
	v_pk_add_f32 v[14:15], v[16:17], 1.0 op_sel_hi:[1,0]
	s_nop 0
	v_div_scale_f32 v9, s[48:49], v15, v15, 1.0
	v_rcp_f32_e32 v16, v9
	s_nop 0
	v_fma_f32 v17, -v9, v16, 1.0
	v_fmac_f32_e32 v16, v17, v16
	v_div_scale_f32 v17, vcc, 1.0, v15, 1.0
	v_mul_f32_e32 v18, v17, v16
	v_fma_f32 v19, -v9, v18, v17
	v_fmac_f32_e32 v18, v19, v16
	v_fma_f32 v9, -v9, v18, v17
	v_div_fmas_f32 v9, v9, v16, v18
	v_div_fixup_f32 v15, v9, v15, 1.0
	v_div_scale_f32 v9, s[48:49], v14, v14, 1.0
	v_rcp_f32_e32 v16, v9
	s_nop 0
	v_fma_f32 v17, -v9, v16, 1.0
	v_fmac_f32_e32 v16, v17, v16
	v_div_scale_f32 v17, vcc, 1.0, v14, 1.0
	v_mul_f32_e32 v18, v17, v16
	v_fma_f32 v19, -v9, v18, v17
	v_fmac_f32_e32 v18, v19, v16
	v_fma_f32 v9, -v9, v18, v17
	v_div_fmas_f32 v9, v9, v16, v18
	v_div_fixup_f32 v14, v9, v14, 1.0
	v_pk_fma_f32 v[12:13], v[12:13], v[14:15], v[20:21]
	v_add_u32_e32 v9, 0x400, v8
	global_store_dwordx4 v[22:23], v[10:13], off
	s_nop 1
	v_ashrrev_i32_e32 v10, 5, v9
	v_ashrrev_i32_e32 v11, 31, v10
	v_lshl_add_u64 v[12:13], s[46:47], 0, v[10:11]
	v_lshl_or_b32 v9, v10, 9, v152
	v_mad_u64_u32 v[10:11], s[48:49], v12, s22, v[6:7]
	v_mad_i32_i24 v11, v13, s22, v11
	v_lshl_add_u64 v[10:11], v[10:11], 0, v[4:5]
	v_add_co_u32_e32 v10, vcc, s21, v10
	s_nop 1
	v_addc_co_u32_e32 v11, vcc, 0, v11, vcc
	v_mov_b32_e32 v10, v224
	v_mov_b32_e32 v11, v225
	v_lshlrev_b32_e32 v14, 16, v10
	v_and_b32_e32 v10, 0xffff0000, v10
	v_lshlrev_b32_e32 v16, 16, v11
	v_mul_f32_e32 v10, 0xbfb8aa3b, v10
	v_and_b32_e32 v11, 0xffff0000, v11
	v_exp_f32_e32 v15, v10
	v_mul_f32_e32 v10, 0xbfb8aa3b, v16
	v_exp_f32_e32 v16, v10
	v_mul_f32_e32 v10, 0xbfb8aa3b, v11
	v_exp_f32_e32 v17, v10
	v_lshlrev_b64 v[10:11], 11, v[12:13]
	v_lshl_add_u64 v[10:11], v[0:1], 0, v[10:11]
	v_mov_b32_e32 v10, v226
	v_mov_b32_e32 v11, v227
	v_mul_f32_e32 v14, 0xbfb8aa3b, v14
	v_exp_f32_e32 v14, v14
	v_lshlrev_b32_e32 v18, 16, v10
	v_and_b32_e32 v19, 0xffff0000, v10
	v_lshlrev_b32_e32 v20, 16, v11
	v_and_b32_e32 v21, 0xffff0000, v11
	v_lshlrev_b64 v[10:11], 12, v[12:13]
	v_pk_add_f32 v[14:15], v[14:15], 1.0 op_sel_hi:[1,0]
	v_lshl_add_u64 v[22:23], v[2:3], 0, v[10:11]
	ds_read_b128 v[10:13], v9
	v_div_scale_f32 v9, s[48:49], v15, v15, 1.0
	v_rcp_f32_e32 v24, v9
	s_nop 0
	v_fma_f32 v25, -v9, v24, 1.0
	v_fmac_f32_e32 v24, v25, v24
	v_div_scale_f32 v25, vcc, 1.0, v15, 1.0
	v_mul_f32_e32 v26, v25, v24
	v_fma_f32 v27, -v9, v26, v25
	v_fmac_f32_e32 v26, v27, v24
	v_fma_f32 v9, -v9, v26, v25
	v_div_fmas_f32 v9, v9, v24, v26
	v_div_fixup_f32 v15, v9, v15, 1.0
	v_div_scale_f32 v9, s[48:49], v14, v14, 1.0
	v_rcp_f32_e32 v24, v9
	s_nop 0
	v_fma_f32 v25, -v9, v24, 1.0
	v_fmac_f32_e32 v24, v25, v24
	v_div_scale_f32 v25, vcc, 1.0, v14, 1.0
	v_mul_f32_e32 v26, v25, v24
	v_fma_f32 v27, -v9, v26, v25
	v_fmac_f32_e32 v26, v27, v24
	v_fma_f32 v9, -v9, v26, v25
	v_div_fmas_f32 v9, v9, v24, v26
	v_div_fixup_f32 v14, v9, v14, 1.0
	s_waitcnt lgkmcnt(0)
	v_pk_fma_f32 v[10:11], v[10:11], v[14:15], v[18:19]
	v_pk_add_f32 v[14:15], v[16:17], 1.0 op_sel_hi:[1,0]
	s_nop 0
	v_div_scale_f32 v9, s[48:49], v15, v15, 1.0
	v_rcp_f32_e32 v16, v9
	s_nop 0
	v_fma_f32 v17, -v9, v16, 1.0
	v_fmac_f32_e32 v16, v17, v16
	v_div_scale_f32 v17, vcc, 1.0, v15, 1.0
	v_mul_f32_e32 v18, v17, v16
	v_fma_f32 v19, -v9, v18, v17
	v_fmac_f32_e32 v18, v19, v16
	v_fma_f32 v9, -v9, v18, v17
	v_div_fmas_f32 v9, v9, v16, v18
	v_div_fixup_f32 v15, v9, v15, 1.0
	v_div_scale_f32 v9, s[48:49], v14, v14, 1.0
	v_rcp_f32_e32 v16, v9
	s_nop 0
	v_fma_f32 v17, -v9, v16, 1.0
	v_fmac_f32_e32 v16, v17, v16
	v_div_scale_f32 v17, vcc, 1.0, v14, 1.0
	v_mul_f32_e32 v18, v17, v16
	v_fma_f32 v19, -v9, v18, v17
	v_fmac_f32_e32 v18, v19, v16
	v_fma_f32 v9, -v9, v18, v17
	v_div_fmas_f32 v9, v9, v16, v18
	v_div_fixup_f32 v14, v9, v14, 1.0
	v_pk_fma_f32 v[12:13], v[12:13], v[14:15], v[20:21]
	v_add_u32_e32 v9, 0x500, v8
	global_store_dwordx4 v[22:23], v[10:13], off
	s_nop 1
	v_ashrrev_i32_e32 v10, 5, v9
	v_ashrrev_i32_e32 v11, 31, v10
	v_lshl_add_u64 v[12:13], s[46:47], 0, v[10:11]
	v_lshl_or_b32 v9, v10, 9, v152
	v_mad_u64_u32 v[10:11], s[48:49], v12, s22, v[6:7]
	v_mad_i32_i24 v11, v13, s22, v11
	v_lshl_add_u64 v[10:11], v[10:11], 0, v[4:5]
	v_add_co_u32_e32 v10, vcc, s21, v10
	s_nop 1
	v_addc_co_u32_e32 v11, vcc, 0, v11, vcc
	v_mov_b32_e32 v10, v228
	v_mov_b32_e32 v11, v229
	v_lshlrev_b32_e32 v14, 16, v10
	v_and_b32_e32 v10, 0xffff0000, v10
	v_lshlrev_b32_e32 v16, 16, v11
	v_mul_f32_e32 v10, 0xbfb8aa3b, v10
	v_and_b32_e32 v11, 0xffff0000, v11
	v_exp_f32_e32 v15, v10
	v_mul_f32_e32 v10, 0xbfb8aa3b, v16
	v_exp_f32_e32 v16, v10
	v_mul_f32_e32 v10, 0xbfb8aa3b, v11
	v_exp_f32_e32 v17, v10
	v_lshlrev_b64 v[10:11], 11, v[12:13]
	v_lshl_add_u64 v[10:11], v[0:1], 0, v[10:11]
	v_mov_b32_e32 v10, v230
	v_mov_b32_e32 v11, v231
	v_mul_f32_e32 v14, 0xbfb8aa3b, v14
	v_exp_f32_e32 v14, v14
	v_lshlrev_b32_e32 v18, 16, v10
	v_and_b32_e32 v19, 0xffff0000, v10
	v_lshlrev_b32_e32 v20, 16, v11
	v_and_b32_e32 v21, 0xffff0000, v11
	v_lshlrev_b64 v[10:11], 12, v[12:13]
	v_pk_add_f32 v[14:15], v[14:15], 1.0 op_sel_hi:[1,0]
	v_lshl_add_u64 v[22:23], v[2:3], 0, v[10:11]
	ds_read_b128 v[10:13], v9
	v_div_scale_f32 v9, s[48:49], v15, v15, 1.0
	v_rcp_f32_e32 v24, v9
	s_nop 0
	v_fma_f32 v25, -v9, v24, 1.0
	v_fmac_f32_e32 v24, v25, v24
	v_div_scale_f32 v25, vcc, 1.0, v15, 1.0
	v_mul_f32_e32 v26, v25, v24
	v_fma_f32 v27, -v9, v26, v25
	v_fmac_f32_e32 v26, v27, v24
	v_fma_f32 v9, -v9, v26, v25
	v_div_fmas_f32 v9, v9, v24, v26
	v_div_fixup_f32 v15, v9, v15, 1.0
	v_div_scale_f32 v9, s[48:49], v14, v14, 1.0
	v_rcp_f32_e32 v24, v9
	s_nop 0
	v_fma_f32 v25, -v9, v24, 1.0
	v_fmac_f32_e32 v24, v25, v24
	v_div_scale_f32 v25, vcc, 1.0, v14, 1.0
	v_mul_f32_e32 v26, v25, v24
	v_fma_f32 v27, -v9, v26, v25
	v_fmac_f32_e32 v26, v27, v24
	v_fma_f32 v9, -v9, v26, v25
	v_div_fmas_f32 v9, v9, v24, v26
	v_div_fixup_f32 v14, v9, v14, 1.0
	s_waitcnt lgkmcnt(0)
; DEVI float sigmoidf_(float x) { return 1.f / (1.f + __expf(-x)); }
; DEVI char* wsp(const Params& P, size_t off) { asm volatile("" : "+s"(off)); return P.ws + off; }
; #define ZERO_ACC(a) _Pragma("unroll") for (int m_ = 0; m_ < 4; ++m_) _Pragma("unroll") for (int n_ = 0; n_ < 4; ++n_) a[m_][n_] = f32x4{0.f, 0.f, 0.f, 0.f}
; template <int BR, int IN, int OUT>
; DEVI void p6_branch(const Params& P, int pm, int pn, float* macc, char* smem, int tid) {
;   asm volatile("" : "+s"(pm), "+s"(pn));
;   const bfu* Z = (const bfu*)wsp(P, O_Z);
;   bfu* M = (bfu*)wsp(P, O_CB);
;   const bfu* A = (const bfu*)wsp(P, BR == 0 ? O_UA : BR == 1 ? O_UB : O_UC) + (long)pm * 128 * 1024;
;   const bfu* B = (const bfu*)wsp(P, BR == 0 ? O_WOA : BR == 1 ? O_WOB : O_WOC) + (long)pn * 128 * 1024;
;   f32x4 acc[4][4]; ZERO_ACC(acc);
;   gemm_core(acc, A, 1024, B, 1024, 1024, smem, tid);
;   epi_stage_f32(acc, smem, tid);
;   const float* T = reinterpret_cast<const float*>(smem);
; #pragma unroll 8
;   for (int q = 0; q < 16; ++q) {
;     const int id = tid + 256 * q, row = id >> 5, c4 = id & 31;
;     const long grow = (long)pm * 128 + row;
;     const int gcol = pn * 128 + c4 * 4;
;     float4 a = *reinterpret_cast<const float4*>(T + row * 128 + c4 * 4);
;     float g[4];
;     load4bf(Z + grow * NCOL + (9 + BR) * 1024 + gcol, g);
;     float v[4] = {sigmoidf_(g[0]) * a.x, sigmoidf_(g[1]) * a.y, sigmoidf_(g[2]) * a.z, sigmoidf_(g[3]) * a.w};
;     if (IN == 1) {
;       float mo[4]; load4bf(M + grow * 1024 + gcol, mo);
;       v[0] += mo[0]; v[1] += mo[1]; v[2] += mo[2]; v[3] += mo[3];
;     }
;     if (IN == 2) {
;       float4 mo = *reinterpret_cast<const float4*>(macc + grow * 1024 + gcol);
;       v[0] += mo.x; v[1] += mo.y; v[2] += mo.z; v[3] += mo.w;
;     }
;     if (OUT == 1) *reinterpret_cast<float4*>(macc + grow * 1024 + gcol) = make_float4(v[0], v[1], v[2], v[3]);
;     else store4bf(M + grow * 1024 + gcol, v);
;   }
	v_pk_fma_f32 v[10:11], v[10:11], v[14:15], v[18:19]
	v_pk_add_f32 v[14:15], v[16:17], 1.0 op_sel_hi:[1,0]
	s_nop 0
	v_div_scale_f32 v9, s[48:49], v15, v15, 1.0
	v_rcp_f32_e32 v16, v9
	s_nop 0
	v_fma_f32 v17, -v9, v16, 1.0
	v_fmac_f32_e32 v16, v17, v16
	v_div_scale_f32 v17, vcc, 1.0, v15, 1.0
	v_mul_f32_e32 v18, v17, v16
	v_fma_f32 v19, -v9, v18, v17
	v_fmac_f32_e32 v18, v19, v16
	v_fma_f32 v9, -v9, v18, v17
	v_div_fmas_f32 v9, v9, v16, v18
	v_div_fixup_f32 v15, v9, v15, 1.0
	v_div_scale_f32 v9, s[48:49], v14, v14, 1.0
	v_rcp_f32_e32 v16, v9
	s_nop 0
	v_fma_f32 v17, -v9, v16, 1.0
	v_fmac_f32_e32 v16, v17, v16
	v_div_scale_f32 v17, vcc, 1.0, v14, 1.0
	v_mul_f32_e32 v18, v17, v16
	v_fma_f32 v19, -v9, v18, v17
	v_fmac_f32_e32 v18, v19, v16
	v_fma_f32 v9, -v9, v18, v17
	v_div_fmas_f32 v9, v9, v16, v18
	v_div_fixup_f32 v14, v9, v14, 1.0
	v_pk_fma_f32 v[12:13], v[12:13], v[14:15], v[20:21]
	v_add_u32_e32 v9, 0x600, v8
	global_store_dwordx4 v[22:23], v[10:13], off
	v_add_u32_e32 v8, 0x700, v8
	v_ashrrev_i32_e32 v8, 5, v8
	v_ashrrev_i32_e32 v10, 5, v9
	v_ashrrev_i32_e32 v11, 31, v10
	v_lshl_add_u64 v[12:13], s[46:47], 0, v[10:11]
	v_lshl_or_b32 v9, v10, 9, v152
	v_mad_u64_u32 v[10:11], s[48:49], v12, s22, v[6:7]
	v_mad_i32_i24 v11, v13, s22, v11
	v_lshl_add_u64 v[10:11], v[10:11], 0, v[4:5]
	v_add_co_u32_e32 v10, vcc, s21, v10
	s_nop 1
	v_addc_co_u32_e32 v11, vcc, 0, v11, vcc
	v_mov_b32_e32 v10, v232
	v_mov_b32_e32 v11, v233
	v_lshlrev_b32_e32 v14, 16, v10
	v_and_b32_e32 v10, 0xffff0000, v10
	v_lshlrev_b32_e32 v16, 16, v11
	v_mul_f32_e32 v10, 0xbfb8aa3b, v10
	v_and_b32_e32 v11, 0xffff0000, v11
	v_exp_f32_e32 v15, v10
	v_mul_f32_e32 v10, 0xbfb8aa3b, v16
	v_exp_f32_e32 v16, v10
	v_mul_f32_e32 v10, 0xbfb8aa3b, v11
	v_exp_f32_e32 v17, v10
	v_lshlrev_b64 v[10:11], 11, v[12:13]
	v_lshl_add_u64 v[10:11], v[0:1], 0, v[10:11]
	v_mov_b32_e32 v10, v234
	v_mov_b32_e32 v11, v235
	v_mul_f32_e32 v14, 0xbfb8aa3b, v14
	v_exp_f32_e32 v14, v14
	v_lshlrev_b32_e32 v18, 16, v10
	v_and_b32_e32 v19, 0xffff0000, v10
	v_lshlrev_b32_e32 v20, 16, v11
	v_and_b32_e32 v21, 0xffff0000, v11
	v_lshlrev_b64 v[10:11], 12, v[12:13]
	v_pk_add_f32 v[14:15], v[14:15], 1.0 op_sel_hi:[1,0]
	v_lshl_add_u64 v[22:23], v[2:3], 0, v[10:11]
	ds_read_b128 v[10:13], v9
	v_div_scale_f32 v9, s[48:49], v15, v15, 1.0
	v_rcp_f32_e32 v24, v9
	s_nop 0
	v_fma_f32 v25, -v9, v24, 1.0
	v_fmac_f32_e32 v24, v25, v24
	v_div_scale_f32 v25, vcc, 1.0, v15, 1.0
	v_mul_f32_e32 v26, v25, v24
	v_fma_f32 v27, -v9, v26, v25
	v_fmac_f32_e32 v26, v27, v24
	v_fma_f32 v9, -v9, v26, v25
	v_div_fmas_f32 v9, v9, v24, v26
	v_div_fixup_f32 v15, v9, v15, 1.0
	v_div_scale_f32 v9, s[48:49], v14, v14, 1.0
	v_rcp_f32_e32 v24, v9
	s_nop 0
	v_fma_f32 v25, -v9, v24, 1.0
	v_fmac_f32_e32 v24, v25, v24
	v_div_scale_f32 v25, vcc, 1.0, v14, 1.0
	v_mul_f32_e32 v26, v25, v24
	v_fma_f32 v27, -v9, v26, v25
	v_fmac_f32_e32 v26, v27, v24
	v_fma_f32 v9, -v9, v26, v25
	v_div_fmas_f32 v9, v9, v24, v26
	v_div_fixup_f32 v14, v9, v14, 1.0
	s_waitcnt lgkmcnt(0)
	v_pk_fma_f32 v[10:11], v[10:11], v[14:15], v[18:19]
	v_pk_add_f32 v[14:15], v[16:17], 1.0 op_sel_hi:[1,0]
	s_nop 0
	v_div_scale_f32 v9, s[48:49], v15, v15, 1.0
	v_rcp_f32_e32 v16, v9
	s_nop 0
	v_fma_f32 v17, -v9, v16, 1.0
	v_fmac_f32_e32 v16, v17, v16
	v_div_scale_f32 v17, vcc, 1.0, v15, 1.0
	v_mul_f32_e32 v18, v17, v16
	v_fma_f32 v19, -v9, v18, v17
	v_fmac_f32_e32 v18, v19, v16
	v_fma_f32 v9, -v9, v18, v17
	v_div_fmas_f32 v9, v9, v16, v18
	v_div_fixup_f32 v15, v9, v15, 1.0
	v_div_scale_f32 v9, s[48:49], v14, v14, 1.0
	v_rcp_f32_e32 v16, v9
	s_nop 0
	v_fma_f32 v17, -v9, v16, 1.0
	v_fmac_f32_e32 v16, v17, v16
	v_div_scale_f32 v17, vcc, 1.0, v14, 1.0
	v_mul_f32_e32 v18, v17, v16
	v_fma_f32 v19, -v9, v18, v17
	v_fmac_f32_e32 v18, v19, v16
	v_fma_f32 v9, -v9, v18, v17
	v_div_fmas_f32 v9, v9, v16, v18
	v_div_fixup_f32 v14, v9, v14, 1.0
	v_pk_fma_f32 v[12:13], v[12:13], v[14:15], v[20:21]
	v_ashrrev_i32_e32 v9, 31, v8
	global_store_dwordx4 v[22:23], v[10:13], off
	s_nop 1
	v_lshl_add_u64 v[10:11], s[46:47], 0, v[8:9]
	v_mad_u64_u32 v[6:7], s[48:49], v10, s22, v[6:7]
	v_mad_i32_i24 v7, v11, s22, v7
	v_lshl_add_u64 v[6:7], v[6:7], 0, v[4:5]
	v_add_co_u32_e32 v6, vcc, s21, v6
	v_lshl_or_b32 v8, v8, 9, v152
	s_nop 0
	v_addc_co_u32_e32 v7, vcc, 0, v7, vcc
	v_mov_b32_e32 v6, v236
	v_mov_b32_e32 v7, v237
	v_lshlrev_b32_e32 v9, 16, v6
	v_and_b32_e32 v6, 0xffff0000, v6
	v_lshlrev_b32_e32 v14, 16, v7
	v_mul_f32_e32 v6, 0xbfb8aa3b, v6
	v_and_b32_e32 v7, 0xffff0000, v7
	v_exp_f32_e32 v13, v6
	v_mul_f32_e32 v6, 0xbfb8aa3b, v14
	v_exp_f32_e32 v14, v6
	v_mul_f32_e32 v6, 0xbfb8aa3b, v7
	v_exp_f32_e32 v15, v6
	v_lshlrev_b64 v[6:7], 11, v[10:11]
	v_lshl_add_u64 v[6:7], v[0:1], 0, v[6:7]
	v_mov_b32_e32 v6, v238
	v_mov_b32_e32 v7, v239
	v_mul_f32_e32 v9, 0xbfb8aa3b, v9
	v_exp_f32_e32 v12, v9
	v_lshlrev_b32_e32 v16, 16, v6
	v_pk_add_f32 v[12:13], v[12:13], 1.0 op_sel_hi:[1,0]
	v_and_b32_e32 v17, 0xffff0000, v6
	v_div_scale_f32 v20, s[48:49], v13, v13, 1.0
	v_rcp_f32_e32 v21, v20
	v_lshlrev_b32_e32 v18, 16, v7
	v_and_b32_e32 v19, 0xffff0000, v7
	v_lshlrev_b64 v[6:7], 12, v[10:11]
	v_fma_f32 v22, -v20, v21, 1.0
	v_fmac_f32_e32 v21, v22, v21
	v_div_scale_f32 v22, vcc, 1.0, v13, 1.0
	v_mul_f32_e32 v23, v22, v21
	v_fma_f32 v24, -v20, v23, v22
	v_fmac_f32_e32 v23, v24, v21
	v_fma_f32 v20, -v20, v23, v22
	v_div_fmas_f32 v20, v20, v21, v23
	v_div_fixup_f32 v13, v20, v13, 1.0
	v_div_scale_f32 v20, s[48:49], v12, v12, 1.0
	v_rcp_f32_e32 v21, v20
	v_lshl_add_u64 v[10:11], v[2:3], 0, v[6:7]
	ds_read_b128 v[6:9], v8
	v_fma_f32 v22, -v20, v21, 1.0
	v_fmac_f32_e32 v21, v22, v21
	v_div_scale_f32 v22, vcc, 1.0, v12, 1.0
	v_mul_f32_e32 v23, v22, v21
	v_fma_f32 v24, -v20, v23, v22
	v_fmac_f32_e32 v23, v24, v21
	v_fma_f32 v20, -v20, v23, v22
	v_div_fmas_f32 v20, v20, v21, v23
	v_div_fixup_f32 v12, v20, v12, 1.0
	s_waitcnt lgkmcnt(0)
	v_pk_fma_f32 v[6:7], v[6:7], v[12:13], v[16:17]
	v_pk_add_f32 v[12:13], v[14:15], 1.0 op_sel_hi:[1,0]
	s_nop 0
	v_div_scale_f32 v14, s[48:49], v13, v13, 1.0
	v_rcp_f32_e32 v15, v14
	s_nop 0
	v_fma_f32 v16, -v14, v15, 1.0
	v_fmac_f32_e32 v15, v16, v15
	v_div_scale_f32 v16, vcc, 1.0, v13, 1.0
	v_mul_f32_e32 v17, v16, v15
	v_fma_f32 v20, -v14, v17, v16
	v_fmac_f32_e32 v17, v20, v15
	v_fma_f32 v14, -v14, v17, v16
	v_div_fmas_f32 v14, v14, v15, v17
	v_div_fixup_f32 v13, v14, v13, 1.0
	v_div_scale_f32 v14, s[48:49], v12, v12, 1.0
	v_rcp_f32_e32 v15, v14
	s_nop 0
	v_fma_f32 v16, -v14, v15, 1.0
	v_fmac_f32_e32 v15, v16, v15
	v_div_scale_f32 v16, vcc, 1.0, v12, 1.0
	v_mul_f32_e32 v17, v16, v15
	v_fma_f32 v20, -v14, v17, v16
	v_fmac_f32_e32 v17, v20, v15
	v_fma_f32 v14, -v14, v17, v16
	v_div_fmas_f32 v14, v14, v15, v17
	v_div_fixup_f32 v12, v14, v12, 1.0
	v_pk_fma_f32 v[8:9], v[8:9], v[12:13], v[18:19]
	global_store_dwordx4 v[10:11], v[6:9], off
	s_cbranch_scc1 .LBB0_737
; DEVI char* wsp(const Params& P, size_t off) { asm volatile("" : "+s"(off)); return P.ws + off; }
; #define ZERO_ACC(a) _Pragma("unroll") for (int m_ = 0; m_ < 4; ++m_) _Pragma("unroll") for (int n_ = 0; n_ < 4; ++n_) a[m_][n_] = f32x4{0.f, 0.f, 0.f, 0.f}
; template <int GATE>
; DEVI void gemm_core_t(f32x4 (&acc)[4][4], const bfu* __restrict__ A, int lda,
;                     const bfu* __restrict__ B, int ldb, int K, char* smem, int tid, const bfu* __restrict__ B2 = nullptr) {
;     ...
;   __syncthreads();
;   stage_tile(A, lda, 0, smem, tid);
;   if (GATE) stage_tile_gate(B, B2, 0, smem + 16384, tid); else stage_tile(B, ldb, 0, smem + 16384, tid);
; template <int BR, int IN, int OUT>
; DEVI void p6_branch(const Params& P, int pm, int pn, float* macc, char* smem, int tid) {
;     ...
;   const bfu* Z = (const bfu*)wsp(P, O_Z);
;   bfu* M = (bfu*)wsp(P, O_CB);
;   const bfu* A = (const bfu*)wsp(P, BR == 0 ? O_UA : BR == 1 ? O_UB : O_UC) + (long)pm * 128 * 1024;
;   const bfu* B = (const bfu*)wsp(P, BR == 0 ? O_WOA : BR == 1 ? O_WOB : O_WOC) + (long)pn * 128 * 1024;
;   f32x4 acc[4][4]; ZERO_ACC(acc);
;   gemm_core(acc, A, 1024, B, 1024, 1024, smem, tid);
	s_ashr_i32 s41, s40, 31
	s_ashr_i32 s27, s26, 31
	s_mov_b64 s[44:45], 0x8582000
	s_mov_b64 s[46:47], 0x17d02000
	s_mov_b64 s[48:49], 0x15c02000
	s_lshl_b64 s[50:51], s[40:41], 18
	s_lshl_b64 s[54:55], s[26:27], 18
	s_add_u32 s24, s30, s48
	s_addc_u32 s27, s31, s49
	s_add_u32 s56, s24, s50
	s_mov_b64 s[52:53], 0x1a00000
	s_addc_u32 s57, s27, s51
	s_add_u32 s24, s30, s52
	s_addc_u32 s27, s31, s53
	s_add_u32 s58, s24, s54
	v_lshl_add_u64 v[0:1], s[56:57], 0, v[116:117]
	v_readfirstlane_b32 s24, v101
	v_lshl_add_u64 v[0:1], v[0:1], 0, v[88:89]
	s_mov_b32 m0, s24
	s_barrier
	global_load_lds_dwordx4 v[0:1], off
	v_lshl_add_u64 v[0:1], s[56:57], 0, v[118:119]
	v_mov_b32_e32 v125, v89
	v_readfirstlane_b32 s24, v103
	v_lshl_add_u64 v[0:1], v[0:1], 0, v[124:125]
	s_mov_b32 m0, s24
	v_mov_b32_e32 v127, v89
	global_load_lds_dwordx4 v[0:1], off
	v_lshl_add_u64 v[0:1], s[56:57], 0, v[120:121]
	v_readfirstlane_b32 s24, v105
	v_lshl_add_u64 v[0:1], v[0:1], 0, v[126:127]
	s_mov_b32 m0, s24
	v_mov_b32_e32 v129, v89
	global_load_lds_dwordx4 v[0:1], off
	v_lshl_add_u64 v[0:1], s[56:57], 0, v[122:123]
	v_readfirstlane_b32 s24, v107
	s_addc_u32 s59, s27, s55
	v_lshl_add_u64 v[0:1], v[0:1], 0, v[128:129]
	s_mov_b32 m0, s24
	v_readfirstlane_b32 s24, v153
	global_load_lds_dwordx4 v[0:1], off
	v_lshl_add_u64 v[0:1], s[58:59], 0, v[116:117]
	v_lshl_add_u64 v[0:1], v[0:1], 0, v[88:89]
	s_mov_b32 m0, s24
	v_readfirstlane_b32 s24, v154
	global_load_lds_dwordx4 v[0:1], off
	v_lshl_add_u64 v[0:1], s[58:59], 0, v[118:119]
	v_lshl_add_u64 v[0:1], v[0:1], 0, v[124:125]
	s_mov_b32 m0, s24
	v_readfirstlane_b32 s24, v155
	global_load_lds_dwordx4 v[0:1], off
	v_lshl_add_u64 v[0:1], s[58:59], 0, v[120:121]
	v_lshl_add_u64 v[0:1], v[0:1], 0, v[126:127]
	s_mov_b32 m0, s24
	v_readfirstlane_b32 s24, v156
	global_load_lds_dwordx4 v[0:1], off
	v_lshl_add_u64 v[0:1], s[58:59], 0, v[122:123]
	v_lshl_add_u64 v[0:1], v[0:1], 0, v[128:129]
	s_mov_b32 m0, s24
	s_add_u32 s48, s48, s50
	global_load_lds_dwordx4 v[0:1], off
	s_addc_u32 s49, s49, s51
	v_lshl_add_u64 v[124:125], v[108:109], 0, s[48:49]
	v_lshl_add_u64 v[126:127], v[110:111], 0, s[48:49]
	v_lshl_add_u64 v[128:129], v[112:113], 0, s[48:49]
	v_lshl_add_u64 v[130:131], v[114:115], 0, s[48:49]
	s_add_u32 s48, s52, s54
	s_addc_u32 s49, s53, s55
	v_mov_b32_e32 v0, 0
	v_lshl_add_u64 v[132:133], v[108:109], 0, s[48:49]
	v_lshl_add_u64 v[134:135], v[110:111], 0, s[48:49]
	v_lshl_add_u64 v[136:137], v[112:113], 0, s[48:49]
	v_lshl_add_u64 v[138:139], v[114:115], 0, s[48:49]
	s_mov_b64 s[48:49], 0
	s_mov_b32 s24, 0x8000
	v_mov_b32_e32 v1, v0
	v_mov_b32_e32 v2, v0
	v_mov_b32_e32 v3, v0
	v_mov_b32_e32 v4, v0
	v_mov_b32_e32 v5, v0
	v_mov_b32_e32 v6, v0
	v_mov_b32_e32 v7, v0
	v_mov_b32_e32 v8, v0
	v_mov_b32_e32 v9, v0
	v_mov_b32_e32 v10, v0
	v_mov_b32_e32 v11, v0
	v_mov_b32_e32 v12, v0
	v_mov_b32_e32 v13, v0
	v_mov_b32_e32 v14, v0
	v_mov_b32_e32 v15, v0
	v_mov_b32_e32 v16, v0
	v_mov_b32_e32 v17, v0
	v_mov_b32_e32 v18, v0
	v_mov_b32_e32 v19, v0
	v_mov_b32_e32 v20, v0
	v_mov_b32_e32 v21, v0
	v_mov_b32_e32 v22, v0
	v_mov_b32_e32 v23, v0
	v_mov_b32_e32 v24, v0
	v_mov_b32_e32 v25, v0
	v_mov_b32_e32 v26, v0
	v_mov_b32_e32 v27, v0
	v_mov_b32_e32 v28, v0
	v_mov_b32_e32 v29, v0
	v_mov_b32_e32 v30, v0
	v_mov_b32_e32 v31, v0
	v_mov_b32_e32 v32, v0
	v_mov_b32_e32 v33, v0
	v_mov_b32_e32 v34, v0
	v_mov_b32_e32 v35, v0
	v_mov_b32_e32 v36, v0
	v_mov_b32_e32 v37, v0
	v_mov_b32_e32 v38, v0
	v_mov_b32_e32 v39, v0
	v_mov_b32_e32 v40, v0
	v_mov_b32_e32 v41, v0
	v_mov_b32_e32 v42, v0
	v_mov_b32_e32 v43, v0
	v_mov_b32_e32 v44, v0
	v_mov_b32_e32 v45, v0
	v_mov_b32_e32 v46, v0
	v_mov_b32_e32 v47, v0
	v_mov_b32_e32 v48, v0
	v_mov_b32_e32 v49, v0
	v_mov_b32_e32 v50, v0
	v_mov_b32_e32 v51, v0
	v_mov_b32_e32 v52, v0
	v_mov_b32_e32 v53, v0
	v_mov_b32_e32 v54, v0
	v_mov_b32_e32 v55, v0
	v_mov_b32_e32 v56, v0
	v_mov_b32_e32 v57, v0
	v_mov_b32_e32 v58, v0
	v_mov_b32_e32 v59, v0
	v_mov_b32_e32 v60, v0
	v_mov_b32_e32 v61, v0
	v_mov_b32_e32 v62, v0
	v_mov_b32_e32 v63, v0

; DEVI float sigmoidf_(float x) { return 1.f / (1.f + __expf(-x)); }
; DEVI char* wsp(const Params& P, size_t off) { asm volatile("" : "+s"(off)); return P.ws + off; }
; #define ZERO_ACC(a) _Pragma("unroll") for (int m_ = 0; m_ < 4; ++m_) _Pragma("unroll") for (int n_ = 0; n_ < 4; ++n_) a[m_][n_] = f32x4{0.f, 0.f, 0.f, 0.f}
; template <int BR, int IN, int OUT>
; DEVI void p6_branch(const Params& P, int pm, int pn, float* macc, char* smem, int tid) {
;   asm volatile("" : "+s"(pm), "+s"(pn));
;   const bfu* Z = (const bfu*)wsp(P, O_Z);
;   bfu* M = (bfu*)wsp(P, O_CB);
;   const bfu* A = (const bfu*)wsp(P, BR == 0 ? O_UA : BR == 1 ? O_UB : O_UC) + (long)pm * 128 * 1024;
;   const bfu* B = (const bfu*)wsp(P, BR == 0 ? O_WOA : BR == 1 ? O_WOB : O_WOC) + (long)pn * 128 * 1024;
;   f32x4 acc[4][4]; ZERO_ACC(acc);
;   gemm_core(acc, A, 1024, B, 1024, 1024, smem, tid);
;   epi_stage_f32(acc, smem, tid);
;   const float* T = reinterpret_cast<const float*>(smem);
; #pragma unroll 8
;   for (int q = 0; q < 16; ++q) {
;     const int id = tid + 256 * q, row = id >> 5, c4 = id & 31;
;     const long grow = (long)pm * 128 + row;
;     const int gcol = pn * 128 + c4 * 4;
;     float4 a = *reinterpret_cast<const float4*>(T + row * 128 + c4 * 4);
;     float g[4];
;     load4bf(Z + grow * NCOL + (9 + BR) * 1024 + gcol, g);
;     float v[4] = {sigmoidf_(g[0]) * a.x, sigmoidf_(g[1]) * a.y, sigmoidf_(g[2]) * a.z, sigmoidf_(g[3]) * a.w};
;     if (IN == 1) {
;       float mo[4]; load4bf(M + grow * 1024 + gcol, mo);
;       v[0] += mo[0]; v[1] += mo[1]; v[2] += mo[2]; v[3] += mo[3];
;     }
;     if (IN == 2) {
;       float4 mo = *reinterpret_cast<const float4*>(macc + grow * 1024 + gcol);
;       v[0] += mo.x; v[1] += mo.y; v[2] += mo.z; v[3] += mo.w;
;     }
;     if (OUT == 1) *reinterpret_cast<float4*>(macc + grow * 1024 + gcol) = make_float4(v[0], v[1], v[2], v[3]);
;     else store4bf(M + grow * 1024 + gcol, v);
;   }
.LBB0_741:
	v_add_u32_e32 v238, s24, v91
	v_ashrrev_i32_e32 v236, 5, v238
	v_ashrrev_i32_e32 v237, 31, v236
	v_lshl_add_u64 v[240:241], s[40:41], 0, v[236:237]
	v_mov_b64_e32 v[236:237], s[44:45]
	v_mad_u64_u32 v[242:243], s[26:27], v240, s22, v[236:237]
	v_mad_i32_i24 v243, v241, s22, v243
	v_lshl_add_u64 v[242:243], v[242:243], 0, v[4:5]
	v_add_co_u32_e32 v242, vcc, 0x5000, v242
	s_nop 1
	v_addc_co_u32_e32 v243, vcc, 0, v243, vcc
	global_load_dwordx2 v[154:155], v[242:243], off
	v_add_u32_e32 v238, s24, v91
	v_ashrrev_i32_e32 v236, 5, v238
	v_ashrrev_i32_e32 v237, 31, v236
	v_lshl_add_u64 v[240:241], s[40:41], 0, v[236:237]
	v_lshlrev_b64 v[242:243], 12, v[240:241]
	v_lshl_add_u64 v[244:245], v[0:1], 0, v[242:243]
	global_load_dwordx4 v[156:159], v[244:245], off
	v_add_u32_e32 v238, s24, v91
	v_mov_b64_e32 v[236:237], s[44:45]
	v_add_u32_e32 v239, 0x100, v238
	v_ashrrev_i32_e32 v240, 5, v239
	v_ashrrev_i32_e32 v241, 31, v240
	v_lshl_add_u64 v[242:243], s[40:41], 0, v[240:241]
	v_mad_u64_u32 v[240:241], s[26:27], v242, s22, v[236:237]
	v_mad_i32_i24 v241, v243, s22, v241
	v_lshl_add_u64 v[240:241], v[240:241], 0, v[4:5]
	v_add_co_u32_e32 v240, vcc, s21, v240
	s_nop 1
	v_addc_co_u32_e32 v241, vcc, 0, v241, vcc
	global_load_dwordx2 v[160:161], v[240:241], off
	v_add_u32_e32 v236, s24, v91
	v_add_u32_e32 v237, 0x100, v236
	v_ashrrev_i32_e32 v238, 5, v237
	v_ashrrev_i32_e32 v239, 31, v238
	v_lshl_add_u64 v[240:241], s[40:41], 0, v[238:239]
	v_lshlrev_b64 v[238:239], 12, v[240:241]
	v_lshl_add_u64 v[242:243], v[0:1], 0, v[238:239]
	global_load_dwordx4 v[164:167], v[242:243], off
	v_add_u32_e32 v238, s24, v91
	v_mov_b64_e32 v[236:237], s[44:45]
	v_add_u32_e32 v239, 0x200, v238
	v_ashrrev_i32_e32 v240, 5, v239
	v_ashrrev_i32_e32 v241, 31, v240
	v_lshl_add_u64 v[242:243], s[40:41], 0, v[240:241]
	v_mad_u64_u32 v[240:241], s[26:27], v242, s22, v[236:237]
	v_mad_i32_i24 v241, v243, s22, v241
	v_lshl_add_u64 v[240:241], v[240:241], 0, v[4:5]
	v_add_co_u32_e32 v240, vcc, s21, v240
	s_nop 1
	v_addc_co_u32_e32 v241, vcc, 0, v241, vcc
	global_load_dwordx2 v[162:163], v[240:241], off
	v_add_u32_e32 v236, s24, v91
	v_add_u32_e32 v237, 0x200, v236
	v_ashrrev_i32_e32 v238, 5, v237
	v_ashrrev_i32_e32 v239, 31, v238
	v_lshl_add_u64 v[240:241], s[40:41], 0, v[238:239]
	v_lshlrev_b64 v[238:239], 12, v[240:241]
	v_lshl_add_u64 v[242:243], v[0:1], 0, v[238:239]
	global_load_dwordx4 v[168:171], v[242:243], off
	v_add_u32_e32 v238, s24, v91
	v_mov_b64_e32 v[236:237], s[44:45]
	v_add_u32_e32 v239, 0x300, v238
	v_ashrrev_i32_e32 v240, 5, v239
	v_ashrrev_i32_e32 v241, 31, v240
	v_lshl_add_u64 v[242:243], s[40:41], 0, v[240:241]
	v_mad_u64_u32 v[240:241], s[26:27], v242, s22, v[236:237]
	v_mad_i32_i24 v241, v243, s22, v241
	v_lshl_add_u64 v[240:241], v[240:241], 0, v[4:5]
	v_add_co_u32_e32 v240, vcc, s21, v240
	s_nop 1
	v_addc_co_u32_e32 v241, vcc, 0, v241, vcc
	global_load_dwordx2 v[172:173], v[240:241], off
	v_add_u32_e32 v236, s24, v91
	v_add_u32_e32 v237, 0x300, v236
	v_ashrrev_i32_e32 v238, 5, v237
	v_ashrrev_i32_e32 v239, 31, v238
	v_lshl_add_u64 v[240:241], s[40:41], 0, v[238:239]
	v_lshlrev_b64 v[238:239], 12, v[240:241]
	v_lshl_add_u64 v[242:243], v[0:1], 0, v[238:239]
	global_load_dwordx4 v[176:179], v[242:243], off
	v_add_u32_e32 v238, s24, v91
	v_mov_b64_e32 v[236:237], s[44:45]
	v_add_u32_e32 v239, 0x400, v238
	v_ashrrev_i32_e32 v240, 5, v239
	v_ashrrev_i32_e32 v241, 31, v240
	v_lshl_add_u64 v[242:243], s[40:41], 0, v[240:241]
	v_mad_u64_u32 v[240:241], s[26:27], v242, s22, v[236:237]
	v_mad_i32_i24 v241, v243, s22, v241
	v_lshl_add_u64 v[240:241], v[240:241], 0, v[4:5]
	v_add_co_u32_e32 v240, vcc, s21, v240
	s_nop 1
	v_addc_co_u32_e32 v241, vcc, 0, v241, vcc
	global_load_dwordx2 v[174:175], v[240:241], off
	v_add_u32_e32 v236, s24, v91
	v_add_u32_e32 v237, 0x400, v236
	v_ashrrev_i32_e32 v238, 5, v237
	v_ashrrev_i32_e32 v239, 31, v238
	v_lshl_add_u64 v[240:241], s[40:41], 0, v[238:239]
	v_lshlrev_b64 v[238:239], 12, v[240:241]
	v_lshl_add_u64 v[242:243], v[0:1], 0, v[238:239]
	global_load_dwordx4 v[180:183], v[242:243], off
	v_add_u32_e32 v238, s24, v91
	v_mov_b64_e32 v[236:237], s[44:45]
	v_add_u32_e32 v239, 0x500, v238
	v_ashrrev_i32_e32 v240, 5, v239
	v_ashrrev_i32_e32 v241, 31, v240
	v_lshl_add_u64 v[242:243], s[40:41], 0, v[240:241]
	v_mad_u64_u32 v[240:241], s[26:27], v242, s22, v[236:237]
	v_mad_i32_i24 v241, v243, s22, v241
	v_lshl_add_u64 v[240:241], v[240:241], 0, v[4:5]
	v_add_co_u32_e32 v240, vcc, s21, v240
	s_nop 1
	v_addc_co_u32_e32 v241, vcc, 0, v241, vcc
	global_load_dwordx2 v[208:209], v[240:241], off
	v_add_u32_e32 v236, s24, v91
	v_add_u32_e32 v237, 0x500, v236
	v_ashrrev_i32_e32 v238, 5, v237
	v_ashrrev_i32_e32 v239, 31, v238
	v_lshl_add_u64 v[240:241], s[40:41], 0, v[238:239]
	v_lshlrev_b64 v[238:239], 12, v[240:241]
	v_lshl_add_u64 v[242:243], v[0:1], 0, v[238:239]
	global_load_dwordx4 v[212:215], v[242:243], off
	v_add_u32_e32 v238, s24, v91
	v_mov_b64_e32 v[236:237], s[44:45]
	v_add_u32_e32 v239, 0x600, v238
	v_ashrrev_i32_e32 v240, 5, v239
	v_ashrrev_i32_e32 v241, 31, v240
	v_lshl_add_u64 v[242:243], s[40:41], 0, v[240:241]
	v_mad_u64_u32 v[240:241], s[26:27], v242, s22, v[236:237]
	v_mad_i32_i24 v241, v243, s22, v241
	v_lshl_add_u64 v[240:241], v[240:241], 0, v[4:5]
	v_add_co_u32_e32 v240, vcc, s21, v240
	s_nop 1
	v_addc_co_u32_e32 v241, vcc, 0, v241, vcc
	global_load_dwordx2 v[210:211], v[240:241], off
	v_add_u32_e32 v236, s24, v91
	v_add_u32_e32 v237, 0x600, v236
	v_ashrrev_i32_e32 v238, 5, v237
	v_ashrrev_i32_e32 v239, 31, v238
	v_lshl_add_u64 v[240:241], s[40:41], 0, v[238:239]
	v_lshlrev_b64 v[238:239], 12, v[240:241]
	v_lshl_add_u64 v[242:243], v[0:1], 0, v[238:239]
	global_load_dwordx4 v[216:219], v[242:243], off
	v_add_u32_e32 v238, s24, v91
	v_mov_b64_e32 v[236:237], s[44:45]
	v_add_u32_e32 v238, 0x700, v238
	v_ashrrev_i32_e32 v238, 5, v238
	v_ashrrev_i32_e32 v239, 31, v238
	v_lshl_add_u64 v[240:241], s[40:41], 0, v[238:239]
	v_mad_u64_u32 v[236:237], s[26:27], v240, s22, v[236:237]
	v_mad_i32_i24 v237, v241, s22, v237
	v_lshl_add_u64 v[236:237], v[236:237], 0, v[4:5]
	v_add_co_u32_e32 v236, vcc, s21, v236
	s_nop 1
	v_addc_co_u32_e32 v237, vcc, 0, v237, vcc
	global_load_dwordx2 v[220:221], v[236:237], off
	v_add_u32_e32 v238, s24, v91
	v_add_u32_e32 v238, 0x700, v238
	v_ashrrev_i32_e32 v238, 5, v238
	v_ashrrev_i32_e32 v239, 31, v238
	v_lshl_add_u64 v[240:241], s[40:41], 0, v[238:239]
	v_lshlrev_b64 v[236:237], 12, v[240:241]
	v_lshl_add_u64 v[242:243], v[0:1], 0, v[236:237]
	global_load_dwordx4 v[224:227], v[242:243], off
	s_waitcnt vmcnt(0)
; DEVI float sigmoidf_(float x) { return 1.f / (1.f + __expf(-x)); }
; DEVI char* wsp(const Params& P, size_t off) { asm volatile("" : "+s"(off)); return P.ws + off; }
; #define ZERO_ACC(a) _Pragma("unroll") for (int m_ = 0; m_ < 4; ++m_) _Pragma("unroll") for (int n_ = 0; n_ < 4; ++n_) a[m_][n_] = f32x4{0.f, 0.f, 0.f, 0.f}
; template <int BR, int IN, int OUT>
; DEVI void p6_branch(const Params& P, int pm, int pn, float* macc, char* smem, int tid) {
;   asm volatile("" : "+s"(pm), "+s"(pn));
;   const bfu* Z = (const bfu*)wsp(P, O_Z);
;   bfu* M = (bfu*)wsp(P, O_CB);
;   const bfu* A = (const bfu*)wsp(P, BR == 0 ? O_UA : BR == 1 ? O_UB : O_UC) + (long)pm * 128 * 1024;
;   const bfu* B = (const bfu*)wsp(P, BR == 0 ? O_WOA : BR == 1 ? O_WOB : O_WOC) + (long)pn * 128 * 1024;
;   f32x4 acc[4][4]; ZERO_ACC(acc);
;   gemm_core(acc, A, 1024, B, 1024, 1024, smem, tid);
;   epi_stage_f32(acc, smem, tid);
;   const float* T = reinterpret_cast<const float*>(smem);
; #pragma unroll 8
;   for (int q = 0; q < 16; ++q) {
;     const int id = tid + 256 * q, row = id >> 5, c4 = id & 31;
;     const long grow = (long)pm * 128 + row;
;     const int gcol = pn * 128 + c4 * 4;
;     float4 a = *reinterpret_cast<const float4*>(T + row * 128 + c4 * 4);
;     float g[4];
;     load4bf(Z + grow * NCOL + (9 + BR) * 1024 + gcol, g);
;     float v[4] = {sigmoidf_(g[0]) * a.x, sigmoidf_(g[1]) * a.y, sigmoidf_(g[2]) * a.z, sigmoidf_(g[3]) * a.w};
;     if (IN == 1) {
;       float mo[4]; load4bf(M + grow * 1024 + gcol, mo);
;       v[0] += mo[0]; v[1] += mo[1]; v[2] += mo[2]; v[3] += mo[3];
;     }
;     if (IN == 2) {
;       float4 mo = *reinterpret_cast<const float4*>(macc + grow * 1024 + gcol);
;       v[0] += mo.x; v[1] += mo.y; v[2] += mo.z; v[3] += mo.w;
;     }
;     if (OUT == 1) *reinterpret_cast<float4*>(macc + grow * 1024 + gcol) = make_float4(v[0], v[1], v[2], v[3]);
;     else store4bf(M + grow * 1024 + gcol, v);
;   }
	v_add_u32_e32 v8, s24, v91
	v_ashrrev_i32_e32 v6, 5, v8
	v_ashrrev_i32_e32 v7, 31, v6
	v_lshl_add_u64 v[10:11], s[40:41], 0, v[6:7]
	v_lshl_or_b32 v9, v6, 9, v152
	v_mov_b64_e32 v[6:7], s[44:45]
	v_mad_u64_u32 v[12:13], s[26:27], v10, s22, v[6:7]
	v_mad_i32_i24 v13, v11, s22, v13
	v_lshl_add_u64 v[12:13], v[12:13], 0, v[4:5]
	v_add_co_u32_e32 v12, vcc, 0x5000, v12
	s_addk_i32 s24, 0x800
	s_nop 0
	v_addc_co_u32_e32 v13, vcc, 0, v13, vcc
	v_mov_b32_e32 v12, v154
	v_mov_b32_e32 v13, v155
	s_cmpk_lg_i32 s24, 0x1000
	v_lshlrev_b32_e32 v14, 16, v12
	v_and_b32_e32 v12, 0xffff0000, v12
	v_lshlrev_b32_e32 v15, 16, v13
	v_mul_f32_e32 v12, 0xbfb8aa3b, v12
	v_mul_f32_e32 v14, 0xbfb8aa3b, v14
	v_exp_f32_e32 v16, v12
	v_mul_f32_e32 v12, 0xbfb8aa3b, v15
	v_exp_f32_e32 v14, v14
	v_exp_f32_e32 v15, v12
	v_and_b32_e32 v13, 0xffff0000, v13
	v_mul_f32_e32 v12, 0xbfb8aa3b, v13
	v_exp_f32_e32 v17, v12
	v_lshlrev_b64 v[12:13], 12, v[10:11]
	v_lshlrev_b64 v[10:11], 11, v[10:11]
	v_pk_add_f32 v[14:15], v[14:15], 1.0 op_sel_hi:[1,0]
	v_lshl_add_u64 v[18:19], v[0:1], 0, v[12:13]
	v_lshl_add_u64 v[20:21], v[2:3], 0, v[10:11]
	ds_read_b128 v[10:13], v9
	v_div_scale_f32 v9, s[26:27], v15, v15, 1.0
	v_rcp_f32_e32 v22, v9
	s_nop 0
	v_fma_f32 v23, -v9, v22, 1.0
	v_fmac_f32_e32 v22, v23, v22
	v_div_scale_f32 v23, vcc, 1.0, v15, 1.0
	v_mul_f32_e32 v24, v23, v22
	v_fma_f32 v25, -v9, v24, v23
	v_fmac_f32_e32 v24, v25, v22
	v_fma_f32 v9, -v9, v24, v23
	v_div_fmas_f32 v9, v9, v22, v24
	v_div_fixup_f32 v23, v9, v15, 1.0
	v_div_scale_f32 v9, s[26:27], v14, v14, 1.0
	v_rcp_f32_e32 v15, v9
	s_nop 0
	v_fma_f32 v22, -v9, v15, 1.0
	v_fmac_f32_e32 v15, v22, v15
	v_div_scale_f32 v22, vcc, 1.0, v14, 1.0
	v_mul_f32_e32 v24, v22, v15
	v_fma_f32 v25, -v9, v24, v22
	v_fmac_f32_e32 v24, v25, v15
	v_fma_f32 v9, -v9, v24, v22
	v_div_fmas_f32 v9, v9, v15, v24
	v_div_fixup_f32 v22, v9, v14, 1.0
	v_pk_add_f32 v[14:15], v[16:17], 1.0 op_sel_hi:[1,0]
	s_waitcnt lgkmcnt(0)
	v_mov_b32_e32 v24, v10
	v_div_scale_f32 v9, s[26:27], v15, v15, 1.0
	v_rcp_f32_e32 v10, v9
	v_mov_b32_e32 v25, v12
	v_fma_f32 v12, -v9, v10, 1.0
	v_fmac_f32_e32 v10, v12, v10
	v_div_scale_f32 v12, vcc, 1.0, v15, 1.0
	v_mul_f32_e32 v16, v12, v10
	v_fma_f32 v17, -v9, v16, v12
	v_fmac_f32_e32 v16, v17, v10
	v_fma_f32 v9, -v9, v16, v12
	v_div_fmas_f32 v9, v9, v10, v16
	v_div_fixup_f32 v27, v9, v15, 1.0
	v_div_scale_f32 v9, s[26:27], v14, v14, 1.0
	v_rcp_f32_e32 v10, v9
	s_nop 0
	v_fma_f32 v12, -v9, v10, 1.0
	v_fmac_f32_e32 v10, v12, v10
	v_div_scale_f32 v12, vcc, 1.0, v14, 1.0
	v_mul_f32_e32 v15, v12, v10
	v_fma_f32 v16, -v9, v15, v12
	v_fmac_f32_e32 v15, v16, v10
	v_fma_f32 v9, -v9, v15, v12
	v_div_fmas_f32 v9, v9, v10, v15
	v_div_fixup_f32 v26, v9, v14, 1.0
	v_mov_b32_e32 v14, v156
	v_mov_b32_e32 v15, v157
	v_mov_b32_e32 v16, v158
	v_mov_b32_e32 v17, v159
	v_mov_b32_e32 v12, v11
	v_mov_b32_e32 v10, v14
	v_mov_b32_e32 v11, v16
	v_pk_fma_f32 v[10:11], v[24:25], v[22:23], v[10:11]
	v_mov_b32_e32 v16, v15
	v_pk_fma_f32 v[12:13], v[12:13], v[26:27], v[16:17]
	v_and_b32_sdwa v9, v11, v95 dst_sel:DWORD dst_unused:UNUSED_PAD src0_sel:WORD_1 src1_sel:DWORD
	v_and_b32_sdwa v14, v10, v95 dst_sel:DWORD dst_unused:UNUSED_PAD src0_sel:WORD_1 src1_sel:DWORD
	v_add3_u32 v10, v10, v14, s39
	v_add3_u32 v9, v11, v9, s39
	v_and_b32_sdwa v11, v13, v95 dst_sel:DWORD dst_unused:UNUSED_PAD src0_sel:WORD_1 src1_sel:DWORD
	v_and_b32_sdwa v14, v12, v95 dst_sel:DWORD dst_unused:UNUSED_PAD src0_sel:WORD_1 src1_sel:DWORD
	v_add3_u32 v11, v13, v11, s39
	v_add3_u32 v12, v12, v14, s39
	v_and_b32_e32 v11, 0xffff0000, v11
	v_and_b32_e32 v12, 0xffff0000, v12
	v_or_b32_sdwa v11, v11, v9 dst_sel:DWORD dst_unused:UNUSED_PAD src0_sel:DWORD src1_sel:WORD_1
	v_or_b32_sdwa v10, v12, v10 dst_sel:DWORD dst_unused:UNUSED_PAD src0_sel:DWORD src1_sel:WORD_1
	v_add_u32_e32 v9, 0x100, v8
	global_store_dwordx2 v[20:21], v[10:11], off
	v_ashrrev_i32_e32 v10, 5, v9
	v_ashrrev_i32_e32 v11, 31, v10
	v_lshl_add_u64 v[12:13], s[40:41], 0, v[10:11]
	v_lshl_or_b32 v9, v10, 9, v152
	v_mad_u64_u32 v[10:11], s[26:27], v12, s22, v[6:7]
	v_mad_i32_i24 v11, v13, s22, v11
	v_lshl_add_u64 v[10:11], v[10:11], 0, v[4:5]
	v_add_co_u32_e32 v10, vcc, s21, v10
	s_nop 1
	v_addc_co_u32_e32 v11, vcc, 0, v11, vcc
	v_mov_b32_e32 v10, v160
	v_mov_b32_e32 v11, v161
	v_lshlrev_b32_e32 v14, 16, v10
	v_and_b32_e32 v10, 0xffff0000, v10
	v_lshlrev_b32_e32 v15, 16, v11
	v_mul_f32_e32 v10, 0xbfb8aa3b, v10
	v_mul_f32_e32 v14, 0xbfb8aa3b, v14
	v_exp_f32_e32 v16, v10
	v_mul_f32_e32 v10, 0xbfb8aa3b, v15
	v_exp_f32_e32 v14, v14
	v_exp_f32_e32 v15, v10
	v_and_b32_e32 v11, 0xffff0000, v11
	v_mul_f32_e32 v10, 0xbfb8aa3b, v11
	v_exp_f32_e32 v17, v10
	v_lshlrev_b64 v[10:11], 12, v[12:13]
	v_lshl_add_u64 v[18:19], v[0:1], 0, v[10:11]
	v_lshlrev_b64 v[10:11], 11, v[12:13]
	v_pk_add_f32 v[14:15], v[14:15], 1.0 op_sel_hi:[1,0]
	v_lshl_add_u64 v[20:21], v[2:3], 0, v[10:11]
	ds_read_b128 v[10:13], v9
	v_div_scale_f32 v9, s[26:27], v15, v15, 1.0
	v_rcp_f32_e32 v22, v9
	s_nop 0
	v_fma_f32 v23, -v9, v22, 1.0
	v_fmac_f32_e32 v22, v23, v22
	v_div_scale_f32 v23, vcc, 1.0, v15, 1.0
	v_mul_f32_e32 v24, v23, v22
	v_fma_f32 v25, -v9, v24, v23
	v_fmac_f32_e32 v24, v25, v22
	v_fma_f32 v9, -v9, v24, v23
	v_div_fmas_f32 v9, v9, v22, v24
	v_div_fixup_f32 v23, v9, v15, 1.0
	v_div_scale_f32 v9, s[26:27], v14, v14, 1.0
	v_rcp_f32_e32 v15, v9
	s_nop 0
	v_fma_f32 v22, -v9, v15, 1.0
	v_fmac_f32_e32 v15, v22, v15
	v_div_scale_f32 v22, vcc, 1.0, v14, 1.0
	v_mul_f32_e32 v24, v22, v15
	v_fma_f32 v25, -v9, v24, v22
	v_fmac_f32_e32 v24, v25, v15
	v_fma_f32 v9, -v9, v24, v22
	v_div_fmas_f32 v9, v9, v15, v24
	v_div_fixup_f32 v22, v9, v14, 1.0
	v_pk_add_f32 v[14:15], v[16:17], 1.0 op_sel_hi:[1,0]
	s_waitcnt lgkmcnt(0)
; DEVI float sigmoidf_(float x) { return 1.f / (1.f + __expf(-x)); }
; template <int BR, int IN, int OUT>
; DEVI void p6_branch(const Params& P, int pm, int pn, float* macc, char* smem, int tid) {
;     ...
;   for (int q = 0; q < 16; ++q) {
;     const int id = tid + 256 * q, row = id >> 5, c4 = id & 31;
;     const long grow = (long)pm * 128 + row;
;     const int gcol = pn * 128 + c4 * 4;
;     float4 a = *reinterpret_cast<const float4*>(T + row * 128 + c4 * 4);
;     float g[4];
;     load4bf(Z + grow * NCOL + (9 + BR) * 1024 + gcol, g);
;     float v[4] = {sigmoidf_(g[0]) * a.x, sigmoidf_(g[1]) * a.y, sigmoidf_(g[2]) * a.z, sigmoidf_(g[3]) * a.w};
;     if (IN == 1) {
;       float mo[4]; load4bf(M + grow * 1024 + gcol, mo);
;       v[0] += mo[0]; v[1] += mo[1]; v[2] += mo[2]; v[3] += mo[3];
;     }
;     if (IN == 2) {
;       float4 mo = *reinterpret_cast<const float4*>(macc + grow * 1024 + gcol);
;       v[0] += mo.x; v[1] += mo.y; v[2] += mo.z; v[3] += mo.w;
;     }
;     if (OUT == 1) *reinterpret_cast<float4*>(macc + grow * 1024 + gcol) = make_float4(v[0], v[1], v[2], v[3]);
;     else store4bf(M + grow * 1024 + gcol, v);
	v_mov_b32_e32 v24, v10
	v_div_scale_f32 v9, s[26:27], v15, v15, 1.0
	v_rcp_f32_e32 v10, v9
	v_mov_b32_e32 v25, v12
	v_fma_f32 v12, -v9, v10, 1.0
	v_fmac_f32_e32 v10, v12, v10
	v_div_scale_f32 v12, vcc, 1.0, v15, 1.0
	v_mul_f32_e32 v16, v12, v10
	v_fma_f32 v17, -v9, v16, v12
	v_fmac_f32_e32 v16, v17, v10
	v_fma_f32 v9, -v9, v16, v12
	v_div_fmas_f32 v9, v9, v10, v16
	v_div_fixup_f32 v27, v9, v15, 1.0
	v_div_scale_f32 v9, s[26:27], v14, v14, 1.0
	v_rcp_f32_e32 v10, v9
	s_nop 0
	v_fma_f32 v12, -v9, v10, 1.0
	v_fmac_f32_e32 v10, v12, v10
	v_div_scale_f32 v12, vcc, 1.0, v14, 1.0
	v_mul_f32_e32 v15, v12, v10
	v_fma_f32 v16, -v9, v15, v12
	v_fmac_f32_e32 v15, v16, v10
	v_fma_f32 v9, -v9, v15, v12
	v_div_fmas_f32 v9, v9, v10, v15
	v_div_fixup_f32 v26, v9, v14, 1.0
	v_mov_b32_e32 v14, v164
	v_mov_b32_e32 v15, v165
	v_mov_b32_e32 v16, v166
	v_mov_b32_e32 v17, v167
	v_mov_b32_e32 v12, v11
	v_mov_b32_e32 v10, v14
	v_mov_b32_e32 v11, v16
	v_pk_fma_f32 v[10:11], v[24:25], v[22:23], v[10:11]
	v_mov_b32_e32 v16, v15
	v_pk_fma_f32 v[12:13], v[12:13], v[26:27], v[16:17]
	v_and_b32_sdwa v9, v11, v95 dst_sel:DWORD dst_unused:UNUSED_PAD src0_sel:WORD_1 src1_sel:DWORD
	v_and_b32_sdwa v14, v10, v95 dst_sel:DWORD dst_unused:UNUSED_PAD src0_sel:WORD_1 src1_sel:DWORD
	v_add3_u32 v10, v10, v14, s39
	v_add3_u32 v9, v11, v9, s39
	v_and_b32_sdwa v11, v13, v95 dst_sel:DWORD dst_unused:UNUSED_PAD src0_sel:WORD_1 src1_sel:DWORD
	v_and_b32_sdwa v14, v12, v95 dst_sel:DWORD dst_unused:UNUSED_PAD src0_sel:WORD_1 src1_sel:DWORD
	v_add3_u32 v11, v13, v11, s39
	v_add3_u32 v12, v12, v14, s39
	v_and_b32_e32 v11, 0xffff0000, v11
	v_and_b32_e32 v12, 0xffff0000, v12
	v_or_b32_sdwa v11, v11, v9 dst_sel:DWORD dst_unused:UNUSED_PAD src0_sel:DWORD src1_sel:WORD_1
	v_or_b32_sdwa v10, v12, v10 dst_sel:DWORD dst_unused:UNUSED_PAD src0_sel:DWORD src1_sel:WORD_1
	v_add_u32_e32 v9, 0x200, v8
	global_store_dwordx2 v[20:21], v[10:11], off
	v_ashrrev_i32_e32 v10, 5, v9
	v_ashrrev_i32_e32 v11, 31, v10
	v_lshl_add_u64 v[12:13], s[40:41], 0, v[10:11]
	v_lshl_or_b32 v9, v10, 9, v152
	v_mad_u64_u32 v[10:11], s[26:27], v12, s22, v[6:7]
	v_mad_i32_i24 v11, v13, s22, v11
	v_lshl_add_u64 v[10:11], v[10:11], 0, v[4:5]
	v_add_co_u32_e32 v10, vcc, s21, v10
	s_nop 1
	v_addc_co_u32_e32 v11, vcc, 0, v11, vcc
	v_mov_b32_e32 v10, v162
	v_mov_b32_e32 v11, v163
	v_lshlrev_b32_e32 v14, 16, v10
	v_and_b32_e32 v10, 0xffff0000, v10
	v_lshlrev_b32_e32 v15, 16, v11
	v_mul_f32_e32 v10, 0xbfb8aa3b, v10
	v_mul_f32_e32 v14, 0xbfb8aa3b, v14
	v_exp_f32_e32 v16, v10
	v_mul_f32_e32 v10, 0xbfb8aa3b, v15
	v_exp_f32_e32 v14, v14
	v_exp_f32_e32 v15, v10
	v_and_b32_e32 v11, 0xffff0000, v11
	v_mul_f32_e32 v10, 0xbfb8aa3b, v11
	v_exp_f32_e32 v17, v10
	v_lshlrev_b64 v[10:11], 12, v[12:13]
	v_lshl_add_u64 v[18:19], v[0:1], 0, v[10:11]
	v_lshlrev_b64 v[10:11], 11, v[12:13]
	v_pk_add_f32 v[14:15], v[14:15], 1.0 op_sel_hi:[1,0]
	v_lshl_add_u64 v[20:21], v[2:3], 0, v[10:11]
	ds_read_b128 v[10:13], v9
	v_div_scale_f32 v9, s[26:27], v15, v15, 1.0
	v_rcp_f32_e32 v22, v9
	s_nop 0
	v_fma_f32 v23, -v9, v22, 1.0
	v_fmac_f32_e32 v22, v23, v22
	v_div_scale_f32 v23, vcc, 1.0, v15, 1.0
	v_mul_f32_e32 v24, v23, v22
	v_fma_f32 v25, -v9, v24, v23
	v_fmac_f32_e32 v24, v25, v22
	v_fma_f32 v9, -v9, v24, v23
	v_div_fmas_f32 v9, v9, v22, v24
	v_div_fixup_f32 v23, v9, v15, 1.0
	v_div_scale_f32 v9, s[26:27], v14, v14, 1.0
	v_rcp_f32_e32 v15, v9
	s_nop 0
	v_fma_f32 v22, -v9, v15, 1.0
	v_fmac_f32_e32 v15, v22, v15
	v_div_scale_f32 v22, vcc, 1.0, v14, 1.0
	v_mul_f32_e32 v24, v22, v15
	v_fma_f32 v25, -v9, v24, v22
	v_fmac_f32_e32 v24, v25, v15
	v_fma_f32 v9, -v9, v24, v22
	v_div_fmas_f32 v9, v9, v15, v24
	v_div_fixup_f32 v22, v9, v14, 1.0
	v_pk_add_f32 v[14:15], v[16:17], 1.0 op_sel_hi:[1,0]
	s_waitcnt lgkmcnt(0)
	v_mov_b32_e32 v24, v10
	v_div_scale_f32 v9, s[26:27], v15, v15, 1.0
	v_rcp_f32_e32 v10, v9
	v_mov_b32_e32 v25, v12
	v_fma_f32 v12, -v9, v10, 1.0
	v_fmac_f32_e32 v10, v12, v10
	v_div_scale_f32 v12, vcc, 1.0, v15, 1.0
	v_mul_f32_e32 v16, v12, v10
	v_fma_f32 v17, -v9, v16, v12
	v_fmac_f32_e32 v16, v17, v10
	v_fma_f32 v9, -v9, v16, v12
	v_div_fmas_f32 v9, v9, v10, v16
	v_div_fixup_f32 v27, v9, v15, 1.0
	v_div_scale_f32 v9, s[26:27], v14, v14, 1.0
	v_rcp_f32_e32 v10, v9
	s_nop 0
	v_fma_f32 v12, -v9, v10, 1.0
	v_fmac_f32_e32 v10, v12, v10
	v_div_scale_f32 v12, vcc, 1.0, v14, 1.0
	v_mul_f32_e32 v15, v12, v10
	v_fma_f32 v16, -v9, v15, v12
	v_fmac_f32_e32 v15, v16, v10
	v_fma_f32 v9, -v9, v15, v12
	v_div_fmas_f32 v9, v9, v10, v15
	v_div_fixup_f32 v26, v9, v14, 1.0
	v_mov_b32_e32 v14, v168
	v_mov_b32_e32 v15, v169
	v_mov_b32_e32 v16, v170
	v_mov_b32_e32 v17, v171
	v_mov_b32_e32 v12, v11
	v_mov_b32_e32 v10, v14
	v_mov_b32_e32 v11, v16
	v_pk_fma_f32 v[10:11], v[24:25], v[22:23], v[10:11]
	v_mov_b32_e32 v16, v15
	v_pk_fma_f32 v[12:13], v[12:13], v[26:27], v[16:17]
	v_and_b32_sdwa v9, v11, v95 dst_sel:DWORD dst_unused:UNUSED_PAD src0_sel:WORD_1 src1_sel:DWORD
	v_and_b32_sdwa v14, v10, v95 dst_sel:DWORD dst_unused:UNUSED_PAD src0_sel:WORD_1 src1_sel:DWORD
	v_add3_u32 v10, v10, v14, s39
	v_add3_u32 v9, v11, v9, s39
	v_and_b32_sdwa v11, v13, v95 dst_sel:DWORD dst_unused:UNUSED_PAD src0_sel:WORD_1 src1_sel:DWORD
	v_and_b32_sdwa v14, v12, v95 dst_sel:DWORD dst_unused:UNUSED_PAD src0_sel:WORD_1 src1_sel:DWORD
	v_add3_u32 v11, v13, v11, s39
	v_add3_u32 v12, v12, v14, s39
	v_and_b32_e32 v11, 0xffff0000, v11
	v_and_b32_e32 v12, 0xffff0000, v12
	v_or_b32_sdwa v11, v11, v9 dst_sel:DWORD dst_unused:UNUSED_PAD src0_sel:DWORD src1_sel:WORD_1
	v_or_b32_sdwa v10, v12, v10 dst_sel:DWORD dst_unused:UNUSED_PAD src0_sel:DWORD src1_sel:WORD_1
	v_add_u32_e32 v9, 0x300, v8
; DEVI float sigmoidf_(float x) { return 1.f / (1.f + __expf(-x)); }
; template <int BR, int IN, int OUT>
; DEVI void p6_branch(const Params& P, int pm, int pn, float* macc, char* smem, int tid) {
;     ...
;   for (int q = 0; q < 16; ++q) {
;     const int id = tid + 256 * q, row = id >> 5, c4 = id & 31;
;     const long grow = (long)pm * 128 + row;
;     const int gcol = pn * 128 + c4 * 4;
;     float4 a = *reinterpret_cast<const float4*>(T + row * 128 + c4 * 4);
;     float g[4];
;     load4bf(Z + grow * NCOL + (9 + BR) * 1024 + gcol, g);
;     float v[4] = {sigmoidf_(g[0]) * a.x, sigmoidf_(g[1]) * a.y, sigmoidf_(g[2]) * a.z, sigmoidf_(g[3]) * a.w};
;     if (IN == 1) {
;       float mo[4]; load4bf(M + grow * 1024 + gcol, mo);
;       v[0] += mo[0]; v[1] += mo[1]; v[2] += mo[2]; v[3] += mo[3];
;     }
;     if (IN == 2) {
;       float4 mo = *reinterpret_cast<const float4*>(macc + grow * 1024 + gcol);
;       v[0] += mo.x; v[1] += mo.y; v[2] += mo.z; v[3] += mo.w;
;     }
;     if (OUT == 1) *reinterpret_cast<float4*>(macc + grow * 1024 + gcol) = make_float4(v[0], v[1], v[2], v[3]);
;     else store4bf(M + grow * 1024 + gcol, v);
	global_store_dwordx2 v[20:21], v[10:11], off
	v_ashrrev_i32_e32 v10, 5, v9
	v_ashrrev_i32_e32 v11, 31, v10
	v_lshl_add_u64 v[12:13], s[40:41], 0, v[10:11]
	v_lshl_or_b32 v9, v10, 9, v152
	v_mad_u64_u32 v[10:11], s[26:27], v12, s22, v[6:7]
	v_mad_i32_i24 v11, v13, s22, v11
	v_lshl_add_u64 v[10:11], v[10:11], 0, v[4:5]
	v_add_co_u32_e32 v10, vcc, s21, v10
	s_nop 1
	v_addc_co_u32_e32 v11, vcc, 0, v11, vcc
	v_mov_b32_e32 v10, v172
	v_mov_b32_e32 v11, v173
	v_lshlrev_b32_e32 v14, 16, v10
	v_and_b32_e32 v10, 0xffff0000, v10
	v_lshlrev_b32_e32 v15, 16, v11
	v_mul_f32_e32 v10, 0xbfb8aa3b, v10
	v_mul_f32_e32 v14, 0xbfb8aa3b, v14
	v_exp_f32_e32 v16, v10
	v_mul_f32_e32 v10, 0xbfb8aa3b, v15
	v_exp_f32_e32 v14, v14
	v_exp_f32_e32 v15, v10
	v_and_b32_e32 v11, 0xffff0000, v11
	v_mul_f32_e32 v10, 0xbfb8aa3b, v11
	v_exp_f32_e32 v17, v10
	v_lshlrev_b64 v[10:11], 12, v[12:13]
	v_lshl_add_u64 v[18:19], v[0:1], 0, v[10:11]
	v_lshlrev_b64 v[10:11], 11, v[12:13]
	v_pk_add_f32 v[14:15], v[14:15], 1.0 op_sel_hi:[1,0]
	v_lshl_add_u64 v[20:21], v[2:3], 0, v[10:11]
	ds_read_b128 v[10:13], v9
	v_div_scale_f32 v9, s[26:27], v15, v15, 1.0
	v_rcp_f32_e32 v22, v9
	s_nop 0
	v_fma_f32 v23, -v9, v22, 1.0
	v_fmac_f32_e32 v22, v23, v22
	v_div_scale_f32 v23, vcc, 1.0, v15, 1.0
	v_mul_f32_e32 v24, v23, v22
	v_fma_f32 v25, -v9, v24, v23
	v_fmac_f32_e32 v24, v25, v22
	v_fma_f32 v9, -v9, v24, v23
	v_div_fmas_f32 v9, v9, v22, v24
	v_div_fixup_f32 v23, v9, v15, 1.0
	v_div_scale_f32 v9, s[26:27], v14, v14, 1.0
	v_rcp_f32_e32 v15, v9
	s_nop 0
	v_fma_f32 v22, -v9, v15, 1.0
	v_fmac_f32_e32 v15, v22, v15
	v_div_scale_f32 v22, vcc, 1.0, v14, 1.0
	v_mul_f32_e32 v24, v22, v15
	v_fma_f32 v25, -v9, v24, v22
	v_fmac_f32_e32 v24, v25, v15
	v_fma_f32 v9, -v9, v24, v22
	v_div_fmas_f32 v9, v9, v15, v24
	v_div_fixup_f32 v22, v9, v14, 1.0
	v_pk_add_f32 v[14:15], v[16:17], 1.0 op_sel_hi:[1,0]
	s_waitcnt lgkmcnt(0)
	v_mov_b32_e32 v24, v10
	v_div_scale_f32 v9, s[26:27], v15, v15, 1.0
	v_rcp_f32_e32 v10, v9
	v_mov_b32_e32 v25, v12
	v_fma_f32 v12, -v9, v10, 1.0
	v_fmac_f32_e32 v10, v12, v10
	v_div_scale_f32 v12, vcc, 1.0, v15, 1.0
	v_mul_f32_e32 v16, v12, v10
	v_fma_f32 v17, -v9, v16, v12
	v_fmac_f32_e32 v16, v17, v10
	v_fma_f32 v9, -v9, v16, v12
	v_div_fmas_f32 v9, v9, v10, v16
	v_div_fixup_f32 v27, v9, v15, 1.0
	v_div_scale_f32 v9, s[26:27], v14, v14, 1.0
	v_rcp_f32_e32 v10, v9
	s_nop 0
	v_fma_f32 v12, -v9, v10, 1.0
	v_fmac_f32_e32 v10, v12, v10
	v_div_scale_f32 v12, vcc, 1.0, v14, 1.0
	v_mul_f32_e32 v15, v12, v10
	v_fma_f32 v16, -v9, v15, v12
	v_fmac_f32_e32 v15, v16, v10
	v_fma_f32 v9, -v9, v15, v12
	v_div_fmas_f32 v9, v9, v10, v15
	v_div_fixup_f32 v26, v9, v14, 1.0
	v_mov_b32_e32 v14, v176
	v_mov_b32_e32 v15, v177
	v_mov_b32_e32 v16, v178
	v_mov_b32_e32 v17, v179
	v_mov_b32_e32 v12, v11
	v_mov_b32_e32 v10, v14
	v_mov_b32_e32 v11, v16
	v_pk_fma_f32 v[10:11], v[24:25], v[22:23], v[10:11]
	v_mov_b32_e32 v16, v15
	v_pk_fma_f32 v[12:13], v[12:13], v[26:27], v[16:17]
	v_and_b32_sdwa v9, v11, v95 dst_sel:DWORD dst_unused:UNUSED_PAD src0_sel:WORD_1 src1_sel:DWORD
	v_and_b32_sdwa v14, v10, v95 dst_sel:DWORD dst_unused:UNUSED_PAD src0_sel:WORD_1 src1_sel:DWORD
	v_add3_u32 v10, v10, v14, s39
	v_add3_u32 v9, v11, v9, s39
	v_and_b32_sdwa v11, v13, v95 dst_sel:DWORD dst_unused:UNUSED_PAD src0_sel:WORD_1 src1_sel:DWORD
	v_and_b32_sdwa v14, v12, v95 dst_sel:DWORD dst_unused:UNUSED_PAD src0_sel:WORD_1 src1_sel:DWORD
	v_add3_u32 v11, v13, v11, s39
	v_add3_u32 v12, v12, v14, s39
	v_and_b32_e32 v11, 0xffff0000, v11
	v_and_b32_e32 v12, 0xffff0000, v12
	v_or_b32_sdwa v11, v11, v9 dst_sel:DWORD dst_unused:UNUSED_PAD src0_sel:DWORD src1_sel:WORD_1
	v_or_b32_sdwa v10, v12, v10 dst_sel:DWORD dst_unused:UNUSED_PAD src0_sel:DWORD src1_sel:WORD_1
	v_add_u32_e32 v9, 0x400, v8
	global_store_dwordx2 v[20:21], v[10:11], off
	v_ashrrev_i32_e32 v10, 5, v9
	v_ashrrev_i32_e32 v11, 31, v10
	v_lshl_add_u64 v[12:13], s[40:41], 0, v[10:11]
	v_lshl_or_b32 v9, v10, 9, v152
	v_mad_u64_u32 v[10:11], s[26:27], v12, s22, v[6:7]
	v_mad_i32_i24 v11, v13, s22, v11
	v_lshl_add_u64 v[10:11], v[10:11], 0, v[4:5]
	v_add_co_u32_e32 v10, vcc, s21, v10
	s_nop 1
	v_addc_co_u32_e32 v11, vcc, 0, v11, vcc
	v_mov_b32_e32 v10, v174
	v_mov_b32_e32 v11, v175
	v_lshlrev_b32_e32 v14, 16, v10
	v_and_b32_e32 v10, 0xffff0000, v10
	v_lshlrev_b32_e32 v15, 16, v11
	v_mul_f32_e32 v10, 0xbfb8aa3b, v10
	v_mul_f32_e32 v14, 0xbfb8aa3b, v14
	v_exp_f32_e32 v16, v10
	v_mul_f32_e32 v10, 0xbfb8aa3b, v15
	v_exp_f32_e32 v14, v14
	v_exp_f32_e32 v15, v10
	v_and_b32_e32 v11, 0xffff0000, v11
	v_mul_f32_e32 v10, 0xbfb8aa3b, v11
	v_exp_f32_e32 v17, v10
	v_lshlrev_b64 v[10:11], 12, v[12:13]
	v_lshl_add_u64 v[18:19], v[0:1], 0, v[10:11]
	v_lshlrev_b64 v[10:11], 11, v[12:13]
	v_pk_add_f32 v[14:15], v[14:15], 1.0 op_sel_hi:[1,0]
	v_lshl_add_u64 v[20:21], v[2:3], 0, v[10:11]
	ds_read_b128 v[10:13], v9
	v_div_scale_f32 v9, s[26:27], v15, v15, 1.0
	v_rcp_f32_e32 v22, v9
	s_nop 0
	v_fma_f32 v23, -v9, v22, 1.0
	v_fmac_f32_e32 v22, v23, v22
	v_div_scale_f32 v23, vcc, 1.0, v15, 1.0
	v_mul_f32_e32 v24, v23, v22
	v_fma_f32 v25, -v9, v24, v23
	v_fmac_f32_e32 v24, v25, v22
	v_fma_f32 v9, -v9, v24, v23
	v_div_fmas_f32 v9, v9, v22, v24
	v_div_fixup_f32 v23, v9, v15, 1.0
	v_div_scale_f32 v9, s[26:27], v14, v14, 1.0
	v_rcp_f32_e32 v15, v9
	s_nop 0
	v_fma_f32 v22, -v9, v15, 1.0
	v_fmac_f32_e32 v15, v22, v15
	v_div_scale_f32 v22, vcc, 1.0, v14, 1.0
	v_mul_f32_e32 v24, v22, v15
	v_fma_f32 v25, -v9, v24, v22
	v_fmac_f32_e32 v24, v25, v15
	v_fma_f32 v9, -v9, v24, v22
	v_div_fmas_f32 v9, v9, v15, v24
	v_div_fixup_f32 v22, v9, v14, 1.0
	v_pk_add_f32 v[14:15], v[16:17], 1.0 op_sel_hi:[1,0]
	s_waitcnt lgkmcnt(0)
; DEVI float sigmoidf_(float x) { return 1.f / (1.f + __expf(-x)); }
; template <int BR, int IN, int OUT>
; DEVI void p6_branch(const Params& P, int pm, int pn, float* macc, char* smem, int tid) {
;     ...
;   for (int q = 0; q < 16; ++q) {
;     const int id = tid + 256 * q, row = id >> 5, c4 = id & 31;
;     const long grow = (long)pm * 128 + row;
;     const int gcol = pn * 128 + c4 * 4;
;     float4 a = *reinterpret_cast<const float4*>(T + row * 128 + c4 * 4);
;     float g[4];
;     load4bf(Z + grow * NCOL + (9 + BR) * 1024 + gcol, g);
;     float v[4] = {sigmoidf_(g[0]) * a.x, sigmoidf_(g[1]) * a.y, sigmoidf_(g[2]) * a.z, sigmoidf_(g[3]) * a.w};
;     if (IN == 1) {
;       float mo[4]; load4bf(M + grow * 1024 + gcol, mo);
;       v[0] += mo[0]; v[1] += mo[1]; v[2] += mo[2]; v[3] += mo[3];
;     }
;     if (IN == 2) {
;       float4 mo = *reinterpret_cast<const float4*>(macc + grow * 1024 + gcol);
;       v[0] += mo.x; v[1] += mo.y; v[2] += mo.z; v[3] += mo.w;
;     }
;     if (OUT == 1) *reinterpret_cast<float4*>(macc + grow * 1024 + gcol) = make_float4(v[0], v[1], v[2], v[3]);
;     else store4bf(M + grow * 1024 + gcol, v);
	v_mov_b32_e32 v24, v10
	v_div_scale_f32 v9, s[26:27], v15, v15, 1.0
	v_rcp_f32_e32 v10, v9
	v_mov_b32_e32 v25, v12
	v_fma_f32 v12, -v9, v10, 1.0
	v_fmac_f32_e32 v10, v12, v10
	v_div_scale_f32 v12, vcc, 1.0, v15, 1.0
	v_mul_f32_e32 v16, v12, v10
	v_fma_f32 v17, -v9, v16, v12
	v_fmac_f32_e32 v16, v17, v10
	v_fma_f32 v9, -v9, v16, v12
	v_div_fmas_f32 v9, v9, v10, v16
	v_div_fixup_f32 v27, v9, v15, 1.0
	v_div_scale_f32 v9, s[26:27], v14, v14, 1.0
	v_rcp_f32_e32 v10, v9
	s_nop 0
	v_fma_f32 v12, -v9, v10, 1.0
	v_fmac_f32_e32 v10, v12, v10
	v_div_scale_f32 v12, vcc, 1.0, v14, 1.0
	v_mul_f32_e32 v15, v12, v10
	v_fma_f32 v16, -v9, v15, v12
	v_fmac_f32_e32 v15, v16, v10
	v_fma_f32 v9, -v9, v15, v12
	v_div_fmas_f32 v9, v9, v10, v15
	v_div_fixup_f32 v26, v9, v14, 1.0
	v_mov_b32_e32 v14, v180
	v_mov_b32_e32 v15, v181
	v_mov_b32_e32 v16, v182
	v_mov_b32_e32 v17, v183
	v_mov_b32_e32 v12, v11
	v_mov_b32_e32 v10, v14
	v_mov_b32_e32 v11, v16
	v_pk_fma_f32 v[10:11], v[24:25], v[22:23], v[10:11]
	v_mov_b32_e32 v16, v15
	v_pk_fma_f32 v[12:13], v[12:13], v[26:27], v[16:17]
	v_and_b32_sdwa v9, v11, v95 dst_sel:DWORD dst_unused:UNUSED_PAD src0_sel:WORD_1 src1_sel:DWORD
	v_and_b32_sdwa v14, v10, v95 dst_sel:DWORD dst_unused:UNUSED_PAD src0_sel:WORD_1 src1_sel:DWORD
	v_add3_u32 v10, v10, v14, s39
	v_add3_u32 v9, v11, v9, s39
	v_and_b32_sdwa v11, v13, v95 dst_sel:DWORD dst_unused:UNUSED_PAD src0_sel:WORD_1 src1_sel:DWORD
	v_and_b32_sdwa v14, v12, v95 dst_sel:DWORD dst_unused:UNUSED_PAD src0_sel:WORD_1 src1_sel:DWORD
	v_add3_u32 v11, v13, v11, s39
	v_add3_u32 v12, v12, v14, s39
	v_and_b32_e32 v11, 0xffff0000, v11
	v_and_b32_e32 v12, 0xffff0000, v12
	v_or_b32_sdwa v11, v11, v9 dst_sel:DWORD dst_unused:UNUSED_PAD src0_sel:DWORD src1_sel:WORD_1
	v_or_b32_sdwa v10, v12, v10 dst_sel:DWORD dst_unused:UNUSED_PAD src0_sel:DWORD src1_sel:WORD_1
	v_add_u32_e32 v9, 0x500, v8
	global_store_dwordx2 v[20:21], v[10:11], off
	v_ashrrev_i32_e32 v10, 5, v9
	v_ashrrev_i32_e32 v11, 31, v10
	v_lshl_add_u64 v[12:13], s[40:41], 0, v[10:11]
	v_lshl_or_b32 v9, v10, 9, v152
	v_mad_u64_u32 v[10:11], s[26:27], v12, s22, v[6:7]
	v_mad_i32_i24 v11, v13, s22, v11
	v_lshl_add_u64 v[10:11], v[10:11], 0, v[4:5]
	v_add_co_u32_e32 v10, vcc, s21, v10
	s_nop 1
	v_addc_co_u32_e32 v11, vcc, 0, v11, vcc
	v_mov_b32_e32 v10, v208
	v_mov_b32_e32 v11, v209
	v_lshlrev_b32_e32 v14, 16, v10
	v_and_b32_e32 v10, 0xffff0000, v10
	v_lshlrev_b32_e32 v15, 16, v11
	v_mul_f32_e32 v10, 0xbfb8aa3b, v10
	v_mul_f32_e32 v14, 0xbfb8aa3b, v14
	v_exp_f32_e32 v16, v10
	v_mul_f32_e32 v10, 0xbfb8aa3b, v15
	v_exp_f32_e32 v14, v14
	v_exp_f32_e32 v15, v10
	v_and_b32_e32 v11, 0xffff0000, v11
	v_mul_f32_e32 v10, 0xbfb8aa3b, v11
	v_exp_f32_e32 v17, v10
	v_lshlrev_b64 v[10:11], 12, v[12:13]
	v_lshl_add_u64 v[18:19], v[0:1], 0, v[10:11]
	v_lshlrev_b64 v[10:11], 11, v[12:13]
	v_pk_add_f32 v[14:15], v[14:15], 1.0 op_sel_hi:[1,0]
	v_lshl_add_u64 v[20:21], v[2:3], 0, v[10:11]
	ds_read_b128 v[10:13], v9
	v_div_scale_f32 v9, s[26:27], v15, v15, 1.0
	v_rcp_f32_e32 v22, v9
	s_nop 0
	v_fma_f32 v23, -v9, v22, 1.0
	v_fmac_f32_e32 v22, v23, v22
	v_div_scale_f32 v23, vcc, 1.0, v15, 1.0
	v_mul_f32_e32 v24, v23, v22
	v_fma_f32 v25, -v9, v24, v23
	v_fmac_f32_e32 v24, v25, v22
	v_fma_f32 v9, -v9, v24, v23
	v_div_fmas_f32 v9, v9, v22, v24
	v_div_fixup_f32 v23, v9, v15, 1.0
	v_div_scale_f32 v9, s[26:27], v14, v14, 1.0
	v_rcp_f32_e32 v15, v9
	s_nop 0
	v_fma_f32 v22, -v9, v15, 1.0
	v_fmac_f32_e32 v15, v22, v15
	v_div_scale_f32 v22, vcc, 1.0, v14, 1.0
	v_mul_f32_e32 v24, v22, v15
	v_fma_f32 v25, -v9, v24, v22
	v_fmac_f32_e32 v24, v25, v15
	v_fma_f32 v9, -v9, v24, v22
	v_div_fmas_f32 v9, v9, v15, v24
	v_div_fixup_f32 v22, v9, v14, 1.0
	v_pk_add_f32 v[14:15], v[16:17], 1.0 op_sel_hi:[1,0]
	s_waitcnt lgkmcnt(0)
	v_mov_b32_e32 v24, v10
	v_div_scale_f32 v9, s[26:27], v15, v15, 1.0
	v_rcp_f32_e32 v10, v9
	v_mov_b32_e32 v25, v12
	v_fma_f32 v12, -v9, v10, 1.0
	v_fmac_f32_e32 v10, v12, v10
	v_div_scale_f32 v12, vcc, 1.0, v15, 1.0
	v_mul_f32_e32 v16, v12, v10
	v_fma_f32 v17, -v9, v16, v12
	v_fmac_f32_e32 v16, v17, v10
	v_fma_f32 v9, -v9, v16, v12
	v_div_fmas_f32 v9, v9, v10, v16
	v_div_fixup_f32 v27, v9, v15, 1.0
	v_div_scale_f32 v9, s[26:27], v14, v14, 1.0
	v_rcp_f32_e32 v10, v9
	s_nop 0
	v_fma_f32 v12, -v9, v10, 1.0
	v_fmac_f32_e32 v10, v12, v10
	v_div_scale_f32 v12, vcc, 1.0, v14, 1.0
	v_mul_f32_e32 v15, v12, v10
	v_fma_f32 v16, -v9, v15, v12
	v_fmac_f32_e32 v15, v16, v10
	v_fma_f32 v9, -v9, v15, v12
	v_div_fmas_f32 v9, v9, v10, v15
	v_div_fixup_f32 v26, v9, v14, 1.0
	v_mov_b32_e32 v14, v212
	v_mov_b32_e32 v15, v213
	v_mov_b32_e32 v16, v214
	v_mov_b32_e32 v17, v215
	v_mov_b32_e32 v12, v11
	v_mov_b32_e32 v10, v14
	v_mov_b32_e32 v11, v16
	v_pk_fma_f32 v[10:11], v[24:25], v[22:23], v[10:11]
	v_mov_b32_e32 v16, v15
	v_pk_fma_f32 v[12:13], v[12:13], v[26:27], v[16:17]
	v_and_b32_sdwa v9, v11, v95 dst_sel:DWORD dst_unused:UNUSED_PAD src0_sel:WORD_1 src1_sel:DWORD
	v_and_b32_sdwa v14, v10, v95 dst_sel:DWORD dst_unused:UNUSED_PAD src0_sel:WORD_1 src1_sel:DWORD
	v_add3_u32 v10, v10, v14, s39
	v_add3_u32 v9, v11, v9, s39
	v_and_b32_sdwa v11, v13, v95 dst_sel:DWORD dst_unused:UNUSED_PAD src0_sel:WORD_1 src1_sel:DWORD
	v_and_b32_sdwa v14, v12, v95 dst_sel:DWORD dst_unused:UNUSED_PAD src0_sel:WORD_1 src1_sel:DWORD
	v_add3_u32 v11, v13, v11, s39
	v_add3_u32 v12, v12, v14, s39
	v_and_b32_e32 v11, 0xffff0000, v11
	v_and_b32_e32 v12, 0xffff0000, v12
	v_or_b32_sdwa v11, v11, v9 dst_sel:DWORD dst_unused:UNUSED_PAD src0_sel:DWORD src1_sel:WORD_1
	v_or_b32_sdwa v10, v12, v10 dst_sel:DWORD dst_unused:UNUSED_PAD src0_sel:DWORD src1_sel:WORD_1
	v_add_u32_e32 v9, 0x600, v8
; DEVI float sigmoidf_(float x) { return 1.f / (1.f + __expf(-x)); }
; template <int BR, int IN, int OUT>
; DEVI void p6_branch(const Params& P, int pm, int pn, float* macc, char* smem, int tid) {
;     ...
;   for (int q = 0; q < 16; ++q) {
;     const int id = tid + 256 * q, row = id >> 5, c4 = id & 31;
;     const long grow = (long)pm * 128 + row;
;     const int gcol = pn * 128 + c4 * 4;
;     float4 a = *reinterpret_cast<const float4*>(T + row * 128 + c4 * 4);
;     float g[4];
;     load4bf(Z + grow * NCOL + (9 + BR) * 1024 + gcol, g);
;     float v[4] = {sigmoidf_(g[0]) * a.x, sigmoidf_(g[1]) * a.y, sigmoidf_(g[2]) * a.z, sigmoidf_(g[3]) * a.w};
;     if (IN == 1) {
;       float mo[4]; load4bf(M + grow * 1024 + gcol, mo);
;       v[0] += mo[0]; v[1] += mo[1]; v[2] += mo[2]; v[3] += mo[3];
;     }
;     if (IN == 2) {
;       float4 mo = *reinterpret_cast<const float4*>(macc + grow * 1024 + gcol);
;       v[0] += mo.x; v[1] += mo.y; v[2] += mo.z; v[3] += mo.w;
;     }
;     if (OUT == 1) *reinterpret_cast<float4*>(macc + grow * 1024 + gcol) = make_float4(v[0], v[1], v[2], v[3]);
;     else store4bf(M + grow * 1024 + gcol, v);
	global_store_dwordx2 v[20:21], v[10:11], off
	v_ashrrev_i32_e32 v10, 5, v9
	v_ashrrev_i32_e32 v11, 31, v10
	v_lshl_add_u64 v[12:13], s[40:41], 0, v[10:11]
	v_lshl_or_b32 v9, v10, 9, v152
	v_mad_u64_u32 v[10:11], s[26:27], v12, s22, v[6:7]
	v_mad_i32_i24 v11, v13, s22, v11
	v_lshl_add_u64 v[10:11], v[10:11], 0, v[4:5]
	v_add_co_u32_e32 v10, vcc, s21, v10
	v_add_u32_e32 v8, 0x700, v8
	s_nop 0
	v_addc_co_u32_e32 v11, vcc, 0, v11, vcc
	v_mov_b32_e32 v10, v210
	v_mov_b32_e32 v11, v211
	v_ashrrev_i32_e32 v8, 5, v8
	v_lshlrev_b32_e32 v14, 16, v10
	v_and_b32_e32 v10, 0xffff0000, v10
	v_lshlrev_b32_e32 v15, 16, v11
	v_mul_f32_e32 v10, 0xbfb8aa3b, v10
	v_mul_f32_e32 v14, 0xbfb8aa3b, v14
	v_exp_f32_e32 v16, v10
	v_mul_f32_e32 v10, 0xbfb8aa3b, v15
	v_exp_f32_e32 v14, v14
	v_exp_f32_e32 v15, v10
	v_and_b32_e32 v11, 0xffff0000, v11
	v_mul_f32_e32 v10, 0xbfb8aa3b, v11
	v_exp_f32_e32 v17, v10
	v_lshlrev_b64 v[10:11], 12, v[12:13]
	v_lshl_add_u64 v[18:19], v[0:1], 0, v[10:11]
	v_lshlrev_b64 v[10:11], 11, v[12:13]
	v_pk_add_f32 v[14:15], v[14:15], 1.0 op_sel_hi:[1,0]
	v_lshl_add_u64 v[20:21], v[2:3], 0, v[10:11]
	ds_read_b128 v[10:13], v9
	v_div_scale_f32 v9, s[26:27], v15, v15, 1.0
	v_rcp_f32_e32 v22, v9
	s_nop 0
	v_fma_f32 v23, -v9, v22, 1.0
	v_fmac_f32_e32 v22, v23, v22
	v_div_scale_f32 v23, vcc, 1.0, v15, 1.0
	v_mul_f32_e32 v24, v23, v22
	v_fma_f32 v25, -v9, v24, v23
	v_fmac_f32_e32 v24, v25, v22
	v_fma_f32 v9, -v9, v24, v23
	v_div_fmas_f32 v9, v9, v22, v24
	v_div_fixup_f32 v23, v9, v15, 1.0
	v_div_scale_f32 v9, s[26:27], v14, v14, 1.0
	v_rcp_f32_e32 v15, v9
	s_nop 0
	v_fma_f32 v22, -v9, v15, 1.0
	v_fmac_f32_e32 v15, v22, v15
	v_div_scale_f32 v22, vcc, 1.0, v14, 1.0
	v_mul_f32_e32 v24, v22, v15
	v_fma_f32 v25, -v9, v24, v22
	v_fmac_f32_e32 v24, v25, v15
	v_fma_f32 v9, -v9, v24, v22
	v_div_fmas_f32 v9, v9, v15, v24
	v_div_fixup_f32 v22, v9, v14, 1.0
	v_pk_add_f32 v[14:15], v[16:17], 1.0 op_sel_hi:[1,0]
	s_waitcnt lgkmcnt(0)
	v_mov_b32_e32 v24, v10
	v_div_scale_f32 v9, s[26:27], v15, v15, 1.0
	v_rcp_f32_e32 v10, v9
	v_mov_b32_e32 v25, v12
	v_fma_f32 v12, -v9, v10, 1.0
	v_fmac_f32_e32 v10, v12, v10
	v_div_scale_f32 v12, vcc, 1.0, v15, 1.0
	v_mul_f32_e32 v16, v12, v10
	v_fma_f32 v17, -v9, v16, v12
	v_fmac_f32_e32 v16, v17, v10
	v_fma_f32 v9, -v9, v16, v12
	v_div_fmas_f32 v9, v9, v10, v16
	v_div_fixup_f32 v27, v9, v15, 1.0
	v_div_scale_f32 v9, s[26:27], v14, v14, 1.0
	v_rcp_f32_e32 v10, v9
	s_nop 0
	v_fma_f32 v12, -v9, v10, 1.0
	v_fmac_f32_e32 v10, v12, v10
	v_div_scale_f32 v12, vcc, 1.0, v14, 1.0
	v_mul_f32_e32 v15, v12, v10
	v_fma_f32 v16, -v9, v15, v12
	v_fmac_f32_e32 v15, v16, v10
	v_fma_f32 v9, -v9, v15, v12
	v_div_fmas_f32 v9, v9, v10, v15
	v_div_fixup_f32 v26, v9, v14, 1.0
	v_mov_b32_e32 v14, v216
	v_mov_b32_e32 v15, v217
	v_mov_b32_e32 v16, v218
	v_mov_b32_e32 v17, v219
	v_mov_b32_e32 v12, v11
	v_mov_b32_e32 v10, v14
	v_mov_b32_e32 v11, v16
	v_pk_fma_f32 v[10:11], v[24:25], v[22:23], v[10:11]
	v_mov_b32_e32 v16, v15
	v_pk_fma_f32 v[12:13], v[12:13], v[26:27], v[16:17]
	v_and_b32_sdwa v9, v11, v95 dst_sel:DWORD dst_unused:UNUSED_PAD src0_sel:WORD_1 src1_sel:DWORD
	v_and_b32_sdwa v14, v10, v95 dst_sel:DWORD dst_unused:UNUSED_PAD src0_sel:WORD_1 src1_sel:DWORD
	v_add3_u32 v10, v10, v14, s39
	v_add3_u32 v9, v11, v9, s39
	v_and_b32_sdwa v11, v13, v95 dst_sel:DWORD dst_unused:UNUSED_PAD src0_sel:WORD_1 src1_sel:DWORD
	v_and_b32_sdwa v14, v12, v95 dst_sel:DWORD dst_unused:UNUSED_PAD src0_sel:WORD_1 src1_sel:DWORD
	v_add3_u32 v11, v13, v11, s39
	v_add3_u32 v12, v12, v14, s39
	v_and_b32_e32 v11, 0xffff0000, v11
	v_and_b32_e32 v12, 0xffff0000, v12
	v_or_b32_sdwa v11, v11, v9 dst_sel:DWORD dst_unused:UNUSED_PAD src0_sel:DWORD src1_sel:WORD_1
	v_or_b32_sdwa v10, v12, v10 dst_sel:DWORD dst_unused:UNUSED_PAD src0_sel:DWORD src1_sel:WORD_1
	v_ashrrev_i32_e32 v9, 31, v8
	global_store_dwordx2 v[20:21], v[10:11], off
	v_lshl_add_u64 v[10:11], s[40:41], 0, v[8:9]
	v_mad_u64_u32 v[6:7], s[26:27], v10, s22, v[6:7]
	v_mad_i32_i24 v7, v11, s22, v7
	v_lshl_add_u64 v[6:7], v[6:7], 0, v[4:5]
	v_add_co_u32_e32 v6, vcc, s21, v6
	v_lshl_or_b32 v8, v8, 9, v152
	s_nop 0
	v_addc_co_u32_e32 v7, vcc, 0, v7, vcc
	v_mov_b32_e32 v6, v220
	v_mov_b32_e32 v7, v221
	v_lshlrev_b32_e32 v9, 16, v6
	v_and_b32_e32 v6, 0xffff0000, v6
	v_lshlrev_b32_e32 v13, 16, v7
	v_mul_f32_e32 v6, 0xbfb8aa3b, v6
	v_mul_f32_e32 v9, 0xbfb8aa3b, v9
	v_exp_f32_e32 v14, v6
	v_mul_f32_e32 v6, 0xbfb8aa3b, v13
	v_exp_f32_e32 v12, v9
	v_exp_f32_e32 v13, v6
	v_and_b32_e32 v7, 0xffff0000, v7
	v_mul_f32_e32 v6, 0xbfb8aa3b, v7
	v_exp_f32_e32 v15, v6
	v_lshlrev_b64 v[6:7], 12, v[10:11]
	v_lshl_add_u64 v[16:17], v[0:1], 0, v[6:7]
	v_lshlrev_b64 v[6:7], 11, v[10:11]
	v_pk_add_f32 v[10:11], v[12:13], 1.0 op_sel_hi:[1,0]
	v_lshl_add_u64 v[18:19], v[2:3], 0, v[6:7]
	v_div_scale_f32 v12, s[26:27], v11, v11, 1.0
	v_rcp_f32_e32 v13, v12
	ds_read_b128 v[6:9], v8
	v_fma_f32 v20, -v12, v13, 1.0
	v_fmac_f32_e32 v13, v20, v13
	v_div_scale_f32 v20, vcc, 1.0, v11, 1.0
	v_mul_f32_e32 v21, v20, v13
	v_fma_f32 v22, -v12, v21, v20
	v_fmac_f32_e32 v21, v22, v13
	v_fma_f32 v12, -v12, v21, v20
	v_div_fmas_f32 v12, v12, v13, v21
	v_div_fixup_f32 v21, v12, v11, 1.0
	v_div_scale_f32 v11, s[26:27], v10, v10, 1.0
	v_rcp_f32_e32 v12, v11
	s_waitcnt lgkmcnt(0)
; DEVI float sigmoidf_(float x) { return 1.f / (1.f + __expf(-x)); }
; template <int BR, int IN, int OUT>
; DEVI void p6_branch(const Params& P, int pm, int pn, float* macc, char* smem, int tid) {
;     ...
;   for (int q = 0; q < 16; ++q) {
;     const int id = tid + 256 * q, row = id >> 5, c4 = id & 31;
;     const long grow = (long)pm * 128 + row;
;     const int gcol = pn * 128 + c4 * 4;
;     float4 a = *reinterpret_cast<const float4*>(T + row * 128 + c4 * 4);
;     float g[4];
;     load4bf(Z + grow * NCOL + (9 + BR) * 1024 + gcol, g);
;     float v[4] = {sigmoidf_(g[0]) * a.x, sigmoidf_(g[1]) * a.y, sigmoidf_(g[2]) * a.z, sigmoidf_(g[3]) * a.w};
;     if (IN == 1) {
;       float mo[4]; load4bf(M + grow * 1024 + gcol, mo);
;       v[0] += mo[0]; v[1] += mo[1]; v[2] += mo[2]; v[3] += mo[3];
;     }
;     if (IN == 2) {
;       float4 mo = *reinterpret_cast<const float4*>(macc + grow * 1024 + gcol);
;       v[0] += mo.x; v[1] += mo.y; v[2] += mo.z; v[3] += mo.w;
;     }
;     if (OUT == 1) *reinterpret_cast<float4*>(macc + grow * 1024 + gcol) = make_float4(v[0], v[1], v[2], v[3]);
;     else store4bf(M + grow * 1024 + gcol, v);
;   }
	v_mov_b32_e32 v23, v8
	v_fma_f32 v13, -v11, v12, 1.0
	v_fmac_f32_e32 v12, v13, v12
	v_div_scale_f32 v13, vcc, 1.0, v10, 1.0
	v_mul_f32_e32 v20, v13, v12
	v_fma_f32 v22, -v11, v20, v13
	v_fmac_f32_e32 v20, v22, v12
	v_fma_f32 v11, -v11, v20, v13
	v_div_fmas_f32 v11, v11, v12, v20
	v_div_fixup_f32 v20, v11, v10, 1.0
	v_pk_add_f32 v[10:11], v[14:15], 1.0 op_sel_hi:[1,0]
	v_mov_b32_e32 v22, v6
	v_div_scale_f32 v6, s[26:27], v11, v11, 1.0
	v_rcp_f32_e32 v8, v6
	s_nop 0
	v_fma_f32 v12, -v6, v8, 1.0
	v_fmac_f32_e32 v8, v12, v8
	v_div_scale_f32 v12, vcc, 1.0, v11, 1.0
	v_mul_f32_e32 v13, v12, v8
	v_fma_f32 v14, -v6, v13, v12
	v_fmac_f32_e32 v13, v14, v8
	v_fma_f32 v6, -v6, v13, v12
	v_div_fmas_f32 v6, v6, v8, v13
	v_div_fixup_f32 v15, v6, v11, 1.0
	v_div_scale_f32 v6, s[26:27], v10, v10, 1.0
	v_rcp_f32_e32 v8, v6
	s_nop 0
	v_fma_f32 v11, -v6, v8, 1.0
	v_fmac_f32_e32 v8, v11, v8
	v_div_scale_f32 v11, vcc, 1.0, v10, 1.0
	v_mul_f32_e32 v12, v11, v8
	v_fma_f32 v13, -v6, v12, v11
	v_fmac_f32_e32 v12, v13, v8
	v_fma_f32 v6, -v6, v12, v11
	v_div_fmas_f32 v6, v6, v8, v12
	v_div_fixup_f32 v14, v6, v10, 1.0
	v_mov_b32_e32 v10, v224
	v_mov_b32_e32 v11, v225
	v_mov_b32_e32 v12, v226
	v_mov_b32_e32 v13, v227
	v_mov_b32_e32 v8, v7
	v_mov_b32_e32 v6, v10
	v_mov_b32_e32 v7, v12
	v_pk_fma_f32 v[6:7], v[22:23], v[20:21], v[6:7]
	v_mov_b32_e32 v12, v11
	v_pk_fma_f32 v[8:9], v[8:9], v[14:15], v[12:13]
	v_and_b32_sdwa v10, v7, v95 dst_sel:DWORD dst_unused:UNUSED_PAD src0_sel:WORD_1 src1_sel:DWORD
	v_and_b32_sdwa v11, v6, v95 dst_sel:DWORD dst_unused:UNUSED_PAD src0_sel:WORD_1 src1_sel:DWORD
	v_add3_u32 v6, v6, v11, s39
	v_add3_u32 v7, v7, v10, s39
	v_and_b32_sdwa v10, v9, v95 dst_sel:DWORD dst_unused:UNUSED_PAD src0_sel:WORD_1 src1_sel:DWORD
	v_and_b32_sdwa v11, v8, v95 dst_sel:DWORD dst_unused:UNUSED_PAD src0_sel:WORD_1 src1_sel:DWORD
	v_add3_u32 v9, v9, v10, s39
	v_add3_u32 v8, v8, v11, s39
	v_and_b32_e32 v9, 0xffff0000, v9
	v_and_b32_e32 v8, 0xffff0000, v8
	v_or_b32_sdwa v7, v9, v7 dst_sel:DWORD dst_unused:UNUSED_PAD src0_sel:DWORD src1_sel:WORD_1
	v_or_b32_sdwa v6, v8, v6 dst_sel:DWORD dst_unused:UNUSED_PAD src0_sel:DWORD src1_sel:WORD_1
	global_store_dwordx2 v[18:19], v[6:7], off
	s_cbranch_scc1 .LBB0_741
	s_add_i32 s2, s2, s23
	s_cmp_lt_i32 s2, s1
	s_cbranch_scc1 .LBB0_730
